# GEMM K-loops: remaining k+1 tile loads also in saddr form (base+kstep kept in a spare SGPR pair); no 64-bit VALU address math left in the loop
# baseline (speedup 1.0000x reference)
; #define PG8_STAGE(bufoff, gbase, voff) do { _Pragma("unroll") for (int _i = 0; _i < 2; ++_i) \
;         __builtin_amdgcn_global_load_lds((const unsigned*)((const char*)(gbase) + (voff)[_i]), (LAS unsigned*)(lds + (bufoff) + ldsw + _i * 8192), 16, 0, 0); } while (0)
; #define PG8_LDA(dst, b, h) do { _Pragma("unroll") for (int m = 0; m < 4; ++m) _Pragma("unroll") for (int k = 0; k < 2; ++k) dst[m][k] = *(const LAS bf16x8*)(lds + PG8_SA(b, h) + aoff + m * 2048 + k * 1024); } while (0)
; #define PG8_LDB(dst, b, h) do { _Pragma("unroll") for (int n = 0; n < 2; ++n) _Pragma("unroll") for (int k = 0; k < 2; ++k) dst[n][k] = *(const LAS bf16x8*)(lds + PG8_SB(b, h) + boff + n * 2048 + k * 1024); } while (0)
; #define PG8_MMA(ai, bj, At, Bt) do { __builtin_amdgcn_s_setprio(1); _Pragma("unroll") for (int m = 0; m < 4; ++m) _Pragma("unroll") for (int n = 0; n < 2; ++n) _Pragma("unroll") for (int k = 0; k < 2; ++k) \
;         acc[ai][bj][m][n] = __builtin_amdgcn_mfma_f32_16x16x32_bf16(Bt[n][k], At[m][k], acc[ai][bj][m][n], 0, 0, 0); __builtin_amdgcn_s_setprio(0); } while (0)
; #define PG8_WAIT_V(n) asm volatile("s_waitcnt vmcnt(" #n ")" ::: "memory")
; #define PG8_WAIT_L(n) asm volatile("s_waitcnt lgkmcnt(" #n ")" ::: "memory")
; #define PG8_BAR __builtin_amdgcn_s_barrier()
; #define PG8_SCHED __builtin_amdgcn_sched_barrier(0)
; template <class Epi>
; __device__ __forceinline__ void gemm_phase(LAS unsigned char* lds, const Gemm g, const StaticOrder& S, const Epi& E) {
;     ...
;             PG8_LDB(B0, 0, 0); PG8_SCHED; PG8_LDA(At, 0, 0); PG8_STAGE(PG8_SA(1, 1), a1 + hstep, voffA);
;             PG8_WAIT_L(8); PG8_BAR; PG8_WAIT_L(0); PG8_MMA(0, 0, At, B0); PG8_BAR; PG8_SCHED;
;             PG8_LDB(B1, 0, 1); PG8_STAGE(PG8_SB(0, 0), b2, voffB);
;             PG8_BAR; PG8_WAIT_L(0); PG8_MMA(0, 1, At, B1); PG8_BAR;
;             PG8_LDA(At, 0, 1); PG8_STAGE(PG8_SA(0, 0), a2, voffA);
;             PG8_BAR; PG8_WAIT_L(0); PG8_MMA(1, 0, At, B0); PG8_BAR; PG8_SCHED;
;             PG8_STAGE(PG8_SB(0, 1), b2 + hstep, voffB);
;             PG8_WAIT_V(6); PG8_BAR; PG8_MMA(1, 1, At, B1); PG8_BAR;
.LBB0_203:
	ds_read_b128 v[144:147], v153
	ds_read_b128 v[160:163], v153 offset:1024
	ds_read_b128 v[164:167], v153 offset:2048
	ds_read_b128 v[168:171], v153 offset:3072
	s_add_u32 s44, s42, 0xfff80080
	s_addc_u32 s45, s43, -1
	s_cmp_eq_u32 s54, 28
	s_cselect_b32 s47, s25, s45
	s_cselect_b32 s46, s50, s44
	s_cselect_b32 s45, s23, s53
	s_cselect_b32 s44, s51, s52
	s_add_i32 m0, s11, 0xc000
	ds_read_b128 v[172:175], v154
	ds_read_b128 v[176:179], v154 offset:1024
	ds_read_b128 v[180:183], v154 offset:2048
	ds_read_b128 v[184:187], v154 offset:3072
	ds_read_b128 v[188:191], v154 offset:4096
	ds_read_b128 v[192:195], v154 offset:5120
	ds_read_b128 v[196:199], v154 offset:6144
	ds_read_b128 v[200:203], v154 offset:7168
	global_load_lds_dwordx4 v136, s[42:43]
	s_add_i32 m0, s11, 0xe000
	s_nop 0
	global_load_lds_dwordx4 v138, s[42:43]
	s_waitcnt lgkmcnt(8)
	s_barrier
	s_waitcnt lgkmcnt(0)
	s_setprio 1
	s_waitcnt lgkmcnt(0)
	v_mfma_f32_16x16x32_bf16 v[124:127], v[144:147], v[172:175], v[124:127]
	v_mfma_f32_16x16x32_bf16 v[120:123], v[164:167], v[172:175], v[120:123]
	v_mfma_f32_16x16x32_bf16 v[108:111], v[144:147], v[180:183], v[108:111]
	v_mfma_f32_16x16x32_bf16 v[104:107], v[164:167], v[180:183], v[104:107]
	v_mfma_f32_16x16x32_bf16 v[92:95], v[144:147], v[188:191], v[92:95]
	v_mfma_f32_16x16x32_bf16 v[88:91], v[164:167], v[188:191], v[88:91]
	v_mfma_f32_16x16x32_bf16 v[76:79], v[144:147], v[196:199], v[76:79]
	v_mfma_f32_16x16x32_bf16 v[72:75], v[164:167], v[196:199], v[72:75]
	v_mfma_f32_16x16x32_bf16 v[124:127], v[160:163], v[176:179], v[124:127]
	v_mfma_f32_16x16x32_bf16 v[120:123], v[168:171], v[176:179], v[120:123]
	v_mfma_f32_16x16x32_bf16 v[108:111], v[160:163], v[184:187], v[108:111]
	v_mfma_f32_16x16x32_bf16 v[104:107], v[168:171], v[184:187], v[104:107]
	v_mfma_f32_16x16x32_bf16 v[92:95], v[160:163], v[192:195], v[92:95]
	v_mfma_f32_16x16x32_bf16 v[88:91], v[168:171], v[192:195], v[88:91]
	v_mfma_f32_16x16x32_bf16 v[76:79], v[160:163], v[200:203], v[76:79]
	v_mfma_f32_16x16x32_bf16 v[72:75], v[168:171], v[200:203], v[72:75]
	s_setprio 0
	s_barrier
	s_add_i32 s55, s41, s10
	s_add_u32 s98, s44, s8
	s_addc_u32 s99, s45, s9
	s_mov_b32 m0, s55
	ds_read_b128 v[204:207], v155
	ds_read_b128 v[208:211], v155 offset:1024
	ds_read_b128 v[212:215], v155 offset:2048
	ds_read_b128 v[216:219], v155 offset:3072
	global_load_lds_dwordx4 v132, s[44:45]
	s_add_i32 m0, s55, 0x2000
	s_nop 0
	global_load_lds_dwordx4 v128, s[44:45]
	s_barrier
	s_waitcnt lgkmcnt(0)
	s_setprio 1
	s_waitcnt lgkmcnt(0)
	v_mfma_f32_16x16x32_bf16 v[116:119], v[204:207], v[172:175], v[116:119]
	v_mfma_f32_16x16x32_bf16 v[112:115], v[212:215], v[172:175], v[112:115]
	v_mfma_f32_16x16x32_bf16 v[100:103], v[204:207], v[180:183], v[100:103]
	v_mfma_f32_16x16x32_bf16 v[96:99], v[212:215], v[180:183], v[96:99]
	v_mfma_f32_16x16x32_bf16 v[84:87], v[204:207], v[188:191], v[84:87]
	v_mfma_f32_16x16x32_bf16 v[80:83], v[212:215], v[188:191], v[80:83]
	v_mfma_f32_16x16x32_bf16 v[68:71], v[204:207], v[196:199], v[68:71]
	v_mfma_f32_16x16x32_bf16 v[64:67], v[212:215], v[196:199], v[64:67]
	v_mfma_f32_16x16x32_bf16 v[116:119], v[208:211], v[176:179], v[116:119]
	v_mfma_f32_16x16x32_bf16 v[112:115], v[216:219], v[176:179], v[112:115]
	v_mfma_f32_16x16x32_bf16 v[100:103], v[208:211], v[184:187], v[100:103]
	v_mfma_f32_16x16x32_bf16 v[96:99], v[216:219], v[184:187], v[96:99]
	v_mfma_f32_16x16x32_bf16 v[84:87], v[208:211], v[192:195], v[84:87]
	v_mfma_f32_16x16x32_bf16 v[80:83], v[216:219], v[192:195], v[80:83]
	v_mfma_f32_16x16x32_bf16 v[68:71], v[208:211], v[200:203], v[68:71]
	v_mfma_f32_16x16x32_bf16 v[64:67], v[216:219], v[200:203], v[64:67]
	s_setprio 0
	s_mov_b32 m0, s11
	s_add_u32 s100, s46, s8
	s_addc_u32 s101, s47, s9
	s_barrier
	ds_read_b128 v[172:175], v154 offset:16384
	ds_read_b128 v[176:179], v154 offset:17408
	ds_read_b128 v[180:183], v154 offset:18432
	ds_read_b128 v[184:187], v154 offset:19456
	ds_read_b128 v[188:191], v154 offset:20480
	ds_read_b128 v[192:195], v154 offset:21504
	ds_read_b128 v[196:199], v154 offset:22528
	ds_read_b128 v[200:203], v154 offset:23552
	global_load_lds_dwordx4 v134, s[46:47]
	s_mov_b32 m0, s13
	s_nop 0
	global_load_lds_dwordx4 v130, s[46:47]
	s_barrier
	s_waitcnt lgkmcnt(0)
	s_setprio 1
	s_waitcnt lgkmcnt(0)
	v_mfma_f32_16x16x32_bf16 v[60:63], v[144:147], v[172:175], v[60:63]
	v_mfma_f32_16x16x32_bf16 v[56:59], v[164:167], v[172:175], v[56:59]
	v_mfma_f32_16x16x32_bf16 v[44:47], v[144:147], v[180:183], v[44:47]
	v_mfma_f32_16x16x32_bf16 v[40:43], v[164:167], v[180:183], v[40:43]
	v_mfma_f32_16x16x32_bf16 v[28:31], v[144:147], v[188:191], v[28:31]
	v_mfma_f32_16x16x32_bf16 v[24:27], v[164:167], v[188:191], v[24:27]
	v_mfma_f32_16x16x32_bf16 v[12:15], v[144:147], v[196:199], v[12:15]
	v_mfma_f32_16x16x32_bf16 v[8:11], v[164:167], v[196:199], v[8:11]
	v_mfma_f32_16x16x32_bf16 v[60:63], v[160:163], v[176:179], v[60:63]
	v_mfma_f32_16x16x32_bf16 v[56:59], v[168:171], v[176:179], v[56:59]
	v_mfma_f32_16x16x32_bf16 v[44:47], v[160:163], v[184:187], v[44:47]
	v_mfma_f32_16x16x32_bf16 v[40:43], v[168:171], v[184:187], v[40:43]
	v_mfma_f32_16x16x32_bf16 v[28:31], v[160:163], v[192:195], v[28:31]
	v_mfma_f32_16x16x32_bf16 v[24:27], v[168:171], v[192:195], v[24:27]
	v_mfma_f32_16x16x32_bf16 v[12:15], v[160:163], v[200:203], v[12:15]
	v_mfma_f32_16x16x32_bf16 v[8:11], v[168:171], v[200:203], v[8:11]
	s_setprio 0
	s_barrier
	s_add_u32 s56, s44, 0x80000
	s_addc_u32 s57, s45, 0
	s_add_i32 s55, s48, s10
	s_mov_b32 m0, s55
	s_nop 0
	global_load_lds_dwordx4 v132, s[56:57]
	s_add_i32 m0, s55, 0x2000
	s_nop 0
	global_load_lds_dwordx4 v128, s[56:57]
	s_waitcnt vmcnt(6)
	s_barrier
; #define PG8_STAGE(bufoff, gbase, voff) do { _Pragma("unroll") for (int _i = 0; _i < 2; ++_i) \
;         __builtin_amdgcn_global_load_lds((const unsigned*)((const char*)(gbase) + (voff)[_i]), (LAS unsigned*)(lds + (bufoff) + ldsw + _i * 8192), 16, 0, 0); } while (0)
; #define PG8_LDA(dst, b, h) do { _Pragma("unroll") for (int m = 0; m < 4; ++m) _Pragma("unroll") for (int k = 0; k < 2; ++k) dst[m][k] = *(const LAS bf16x8*)(lds + PG8_SA(b, h) + aoff + m * 2048 + k * 1024); } while (0)
; #define PG8_LDB(dst, b, h) do { _Pragma("unroll") for (int n = 0; n < 2; ++n) _Pragma("unroll") for (int k = 0; k < 2; ++k) dst[n][k] = *(const LAS bf16x8*)(lds + PG8_SB(b, h) + boff + n * 2048 + k * 1024); } while (0)
; #define PG8_MMA(ai, bj, At, Bt) do { __builtin_amdgcn_s_setprio(1); _Pragma("unroll") for (int m = 0; m < 4; ++m) _Pragma("unroll") for (int n = 0; n < 2; ++n) _Pragma("unroll") for (int k = 0; k < 2; ++k) \
;         acc[ai][bj][m][n] = __builtin_amdgcn_mfma_f32_16x16x32_bf16(Bt[n][k], At[m][k], acc[ai][bj][m][n], 0, 0, 0); __builtin_amdgcn_s_setprio(0); } while (0)
; #define PG8_WAIT_V(n) asm volatile("s_waitcnt vmcnt(" #n ")" ::: "memory")
; #define PG8_WAIT_L(n) asm volatile("s_waitcnt lgkmcnt(" #n ")" ::: "memory")
; #define PG8_BAR __builtin_amdgcn_s_barrier()
; #define PG8_SCHED __builtin_amdgcn_sched_barrier(0)
; template <class Epi>
; __device__ __forceinline__ void gemm_phase(LAS unsigned char* lds, const Gemm g, const StaticOrder& S, const Epi& E) {
;     ...
;             PG8_WAIT_V(6); PG8_BAR; PG8_MMA(1, 1, At, B1); PG8_BAR;
;             PG8_LDB(B0, 1, 0); PG8_SCHED; PG8_LDA(At, 1, 0); PG8_STAGE(PG8_SA(0, 1), a2 + hstep, voffA);
;             PG8_WAIT_L(8); PG8_BAR; PG8_WAIT_L(0); PG8_MMA(0, 0, At, B0); PG8_BAR; PG8_SCHED;
;             PG8_LDB(B1, 1, 1); PG8_STAGE(PG8_SB(1, 0), b3, voffB);
;             PG8_BAR; PG8_WAIT_L(0); PG8_MMA(0, 1, At, B1); PG8_BAR;
;             PG8_LDA(At, 1, 1); PG8_STAGE(PG8_SA(1, 0), a3, voffA);
	s_setprio 1
	v_mfma_f32_16x16x32_bf16 v[52:55], v[204:207], v[172:175], v[52:55]
	v_mfma_f32_16x16x32_bf16 v[48:51], v[212:215], v[172:175], v[48:51]
	v_mfma_f32_16x16x32_bf16 v[36:39], v[204:207], v[180:183], v[36:39]
	v_mfma_f32_16x16x32_bf16 v[32:35], v[212:215], v[180:183], v[32:35]
	v_mfma_f32_16x16x32_bf16 v[20:23], v[204:207], v[188:191], v[20:23]
	v_mfma_f32_16x16x32_bf16 v[16:19], v[212:215], v[188:191], v[16:19]
	v_mfma_f32_16x16x32_bf16 v[4:7], v[204:207], v[196:199], v[4:7]
	v_mfma_f32_16x16x32_bf16 v[0:3], v[212:215], v[196:199], v[0:3]
	v_mfma_f32_16x16x32_bf16 v[52:55], v[208:211], v[176:179], v[52:55]
	v_mfma_f32_16x16x32_bf16 v[48:51], v[216:219], v[176:179], v[48:51]
	v_mfma_f32_16x16x32_bf16 v[36:39], v[208:211], v[184:187], v[36:39]
	v_mfma_f32_16x16x32_bf16 v[32:35], v[216:219], v[184:187], v[32:35]
	v_mfma_f32_16x16x32_bf16 v[20:23], v[208:211], v[192:195], v[20:23]
	v_mfma_f32_16x16x32_bf16 v[16:19], v[216:219], v[192:195], v[16:19]
	v_mfma_f32_16x16x32_bf16 v[4:7], v[208:211], v[200:203], v[4:7]
	v_mfma_f32_16x16x32_bf16 v[0:3], v[216:219], v[200:203], v[0:3]
	s_setprio 0
	s_add_i32 s55, 0, 0x18000
	v_add_u32_e32 v168, s55, v151
	s_barrier
	ds_read_b128 v[144:147], v168
	ds_read_b128 v[160:163], v168 offset:1024
	ds_read_b128 v[164:167], v168 offset:2048
	ds_read_b128 v[168:171], v168 offset:3072
	s_add_u32 s46, s46, 0x80000
	s_addc_u32 s47, s47, 0
	s_mov_b32 m0, s30
	ds_read_b128 v[172:175], v154 offset:32768
	ds_read_b128 v[176:179], v154 offset:33792
	ds_read_b128 v[180:183], v154 offset:34816
	ds_read_b128 v[184:187], v154 offset:35840
	ds_read_b128 v[188:191], v154 offset:36864
	ds_read_b128 v[192:195], v154 offset:37888
	ds_read_b128 v[196:199], v154 offset:38912
	ds_read_b128 v[200:203], v154 offset:39936
	global_load_lds_dwordx4 v134, s[46:47]
	s_mov_b32 m0, s31
	s_nop 0
	global_load_lds_dwordx4 v130, s[46:47]
	s_waitcnt lgkmcnt(8)
	s_barrier
	s_waitcnt lgkmcnt(0)
	s_setprio 1
	s_waitcnt lgkmcnt(0)
	v_mfma_f32_16x16x32_bf16 v[124:127], v[144:147], v[172:175], v[124:127]
	v_mfma_f32_16x16x32_bf16 v[120:123], v[164:167], v[172:175], v[120:123]
	v_mfma_f32_16x16x32_bf16 v[108:111], v[144:147], v[180:183], v[108:111]
	v_mfma_f32_16x16x32_bf16 v[104:107], v[164:167], v[180:183], v[104:107]
	v_mfma_f32_16x16x32_bf16 v[92:95], v[144:147], v[188:191], v[92:95]
	v_mfma_f32_16x16x32_bf16 v[88:91], v[164:167], v[188:191], v[88:91]
	v_mfma_f32_16x16x32_bf16 v[76:79], v[144:147], v[196:199], v[76:79]
	v_mfma_f32_16x16x32_bf16 v[72:75], v[164:167], v[196:199], v[72:75]
	v_mfma_f32_16x16x32_bf16 v[124:127], v[160:163], v[176:179], v[124:127]
	v_mfma_f32_16x16x32_bf16 v[120:123], v[168:171], v[176:179], v[120:123]
	v_mfma_f32_16x16x32_bf16 v[108:111], v[160:163], v[184:187], v[108:111]
	v_mfma_f32_16x16x32_bf16 v[104:107], v[168:171], v[184:187], v[104:107]
	v_mfma_f32_16x16x32_bf16 v[92:95], v[160:163], v[192:195], v[92:95]
	v_mfma_f32_16x16x32_bf16 v[88:91], v[168:171], v[192:195], v[88:91]
	v_mfma_f32_16x16x32_bf16 v[76:79], v[160:163], v[200:203], v[76:79]
	v_mfma_f32_16x16x32_bf16 v[72:75], v[168:171], v[200:203], v[72:75]
	s_setprio 0
	s_barrier
	s_add_i32 s46, 0, 0x1c000
	s_add_i32 s47, s55, s10
	v_add_u32_e32 v216, s46, v151
	s_mov_b32 m0, s47
	ds_read_b128 v[204:207], v216
	ds_read_b128 v[208:211], v216 offset:1024
	ds_read_b128 v[212:215], v216 offset:2048
	ds_read_b128 v[216:219], v216 offset:3072
	global_load_lds_dwordx4 v132, s[98:99]
	s_add_i32 m0, s47, 0x2000
	s_nop 0
	global_load_lds_dwordx4 v128, s[98:99]
	s_barrier
	s_waitcnt lgkmcnt(0)
	s_setprio 1
	s_waitcnt lgkmcnt(0)
	v_mfma_f32_16x16x32_bf16 v[116:119], v[204:207], v[172:175], v[116:119]
	v_mfma_f32_16x16x32_bf16 v[112:115], v[212:215], v[172:175], v[112:115]
	v_mfma_f32_16x16x32_bf16 v[100:103], v[204:207], v[180:183], v[100:103]
	v_mfma_f32_16x16x32_bf16 v[96:99], v[212:215], v[180:183], v[96:99]
	v_mfma_f32_16x16x32_bf16 v[84:87], v[204:207], v[188:191], v[84:87]
	v_mfma_f32_16x16x32_bf16 v[80:83], v[212:215], v[188:191], v[80:83]
	v_mfma_f32_16x16x32_bf16 v[68:71], v[204:207], v[196:199], v[68:71]
	v_mfma_f32_16x16x32_bf16 v[64:67], v[212:215], v[196:199], v[64:67]
	v_mfma_f32_16x16x32_bf16 v[116:119], v[208:211], v[176:179], v[116:119]
	v_mfma_f32_16x16x32_bf16 v[112:115], v[216:219], v[176:179], v[112:115]
	v_mfma_f32_16x16x32_bf16 v[100:103], v[208:211], v[184:187], v[100:103]
	v_mfma_f32_16x16x32_bf16 v[96:99], v[216:219], v[184:187], v[96:99]
	v_mfma_f32_16x16x32_bf16 v[84:87], v[208:211], v[192:195], v[84:87]
	v_mfma_f32_16x16x32_bf16 v[80:83], v[216:219], v[192:195], v[80:83]
	v_mfma_f32_16x16x32_bf16 v[68:71], v[208:211], v[200:203], v[68:71]
	v_mfma_f32_16x16x32_bf16 v[64:67], v[216:219], v[200:203], v[64:67]
	s_setprio 0
	s_mov_b32 m0, s36
	s_barrier
	ds_read_b128 v[172:175], v154 offset:49152
	ds_read_b128 v[176:179], v154 offset:50176
	ds_read_b128 v[180:183], v154 offset:51200
	ds_read_b128 v[184:187], v154 offset:52224
	ds_read_b128 v[188:191], v154 offset:53248
	ds_read_b128 v[192:195], v154 offset:54272
	ds_read_b128 v[196:199], v154 offset:55296
	ds_read_b128 v[200:203], v154 offset:56320
	global_load_lds_dwordx4 v134, s[100:101]
	s_mov_b32 m0, s37
	s_nop 0
	global_load_lds_dwordx4 v130, s[100:101]
	s_barrier
; __device__ __forceinline__ float fast_rcp(float x) { return __builtin_amdgcn_rcpf(x); }
; __device__ __forceinline__ float fast_exp2(float x) { return __builtin_amdgcn_exp2f(x); }
; #define PG8_STAGE(bufoff, gbase, voff) do { _Pragma("unroll") for (int _i = 0; _i < 2; ++_i) \
;         __builtin_amdgcn_global_load_lds((const unsigned*)((const char*)(gbase) + (voff)[_i]), (LAS unsigned*)(lds + (bufoff) + ldsw + _i * 8192), 16, 0, 0); } while (0)
; #define PG8_MMA(ai, bj, At, Bt) do { __builtin_amdgcn_s_setprio(1); _Pragma("unroll") for (int m = 0; m < 4; ++m) _Pragma("unroll") for (int n = 0; n < 2; ++n) _Pragma("unroll") for (int k = 0; k < 2; ++k) \
;         acc[ai][bj][m][n] = __builtin_amdgcn_mfma_f32_16x16x32_bf16(Bt[n][k], At[m][k], acc[ai][bj][m][n], 0, 0, 0); __builtin_amdgcn_s_setprio(0); } while (0)
; #define PG8_WAIT_V(n) asm volatile("s_waitcnt vmcnt(" #n ")" ::: "memory")
; #define PG8_WAIT_L(n) asm volatile("s_waitcnt lgkmcnt(" #n ")" ::: "memory")
; #define PG8_BAR __builtin_amdgcn_s_barrier()
; #define PG8_SCHED __builtin_amdgcn_sched_barrier(0)
; template <class Epi>
; __device__ __forceinline__ void gemm_phase(LAS unsigned char* lds, const Gemm g, const StaticOrder& S, const Epi& E) {
;     ...
;             PG8_BAR; PG8_WAIT_L(0); PG8_MMA(1, 0, At, B0); PG8_BAR; PG8_SCHED;
;             PG8_STAGE(PG8_SB(1, 1), b3 + hstep, voffB);
;             PG8_WAIT_V(6); PG8_BAR; PG8_MMA(1, 1, At, B1); PG8_BAR;
;     __device__ __forceinline__ void operator()(const f32x4 (&acc)[2][2][4][2], const Unit& u, int wr, int wc, int fr, int fq) const {
;         const int row0 = u.pm * BM + wr * 64 + fr, col0 = u.pn * HALF + wc * 32 + 8 * fq;
; #pragma unroll
;         for (int ai = 0; ai < 2; ++ai)
; #pragma unroll
;             for (int m = 0; m < 4; ++m) { bf16_t* rowp = O + (size_t)(row0 + ai * HALF + m * 16) * DFF + col0;
;                 const float r = rs[row0 + ai * HALF + m * 16], r2 = r * r;
;                 f32x4 h0, h1;
; #pragma unroll
;                 for (int j = 0; j < 4; ++j) {
;                     const float g0 = acc[ai][0][m][0][j], g1 = acc[ai][0][m][1][j];
;                     h0[j] = g0 * r2 * fast_rcp(1.0f + fast_exp2(g0 * (-LOG2E * r))) * acc[ai][1][m][0][j];
;                     h1[j] = g1 * r2 * fast_rcp(1.0f + fast_exp2(g1 * (-LOG2E * r))) * acc[ai][1][m][1][j]; }
;                 *(u32x4*)rowp = pack8(h0, h1); }
	s_waitcnt lgkmcnt(0)
	s_setprio 1
	s_waitcnt lgkmcnt(0)
	v_mfma_f32_16x16x32_bf16 v[60:63], v[144:147], v[172:175], v[60:63]
	v_mfma_f32_16x16x32_bf16 v[56:59], v[164:167], v[172:175], v[56:59]
	v_mfma_f32_16x16x32_bf16 v[44:47], v[144:147], v[180:183], v[44:47]
	v_mfma_f32_16x16x32_bf16 v[40:43], v[164:167], v[180:183], v[40:43]
	v_mfma_f32_16x16x32_bf16 v[28:31], v[144:147], v[188:191], v[28:31]
	v_mfma_f32_16x16x32_bf16 v[24:27], v[164:167], v[188:191], v[24:27]
	v_mfma_f32_16x16x32_bf16 v[12:15], v[144:147], v[196:199], v[12:15]
	v_mfma_f32_16x16x32_bf16 v[8:11], v[164:167], v[196:199], v[8:11]
	v_mfma_f32_16x16x32_bf16 v[60:63], v[160:163], v[176:179], v[60:63]
	v_mfma_f32_16x16x32_bf16 v[56:59], v[168:171], v[176:179], v[56:59]
	v_mfma_f32_16x16x32_bf16 v[44:47], v[160:163], v[184:187], v[44:47]
	v_mfma_f32_16x16x32_bf16 v[40:43], v[168:171], v[184:187], v[40:43]
	v_mfma_f32_16x16x32_bf16 v[28:31], v[160:163], v[192:195], v[28:31]
	v_mfma_f32_16x16x32_bf16 v[24:27], v[168:171], v[192:195], v[24:27]
	v_mfma_f32_16x16x32_bf16 v[12:15], v[160:163], v[200:203], v[12:15]
	v_mfma_f32_16x16x32_bf16 v[8:11], v[168:171], v[200:203], v[8:11]
	s_setprio 0
	s_barrier
	s_add_u32 s44, s44, 0x80080
	s_addc_u32 s45, s45, 0
	s_add_i32 s46, s46, s10
	s_mov_b32 m0, s46
	s_nop 0
	global_load_lds_dwordx4 v132, s[44:45]
	s_add_i32 m0, s46, 0x2000
	s_nop 0
	global_load_lds_dwordx4 v128, s[44:45]
	s_waitcnt vmcnt(6)
	s_barrier
	s_setprio 1
	v_mfma_f32_16x16x32_bf16 v[52:55], v[204:207], v[172:175], v[52:55]
	v_mfma_f32_16x16x32_bf16 v[48:51], v[212:215], v[172:175], v[48:51]
	v_mfma_f32_16x16x32_bf16 v[36:39], v[204:207], v[180:183], v[36:39]
	v_mfma_f32_16x16x32_bf16 v[32:35], v[212:215], v[180:183], v[32:35]
	v_mfma_f32_16x16x32_bf16 v[20:23], v[204:207], v[188:191], v[20:23]
	v_mfma_f32_16x16x32_bf16 v[16:19], v[212:215], v[188:191], v[16:19]
	v_mfma_f32_16x16x32_bf16 v[4:7], v[204:207], v[196:199], v[4:7]
	v_mfma_f32_16x16x32_bf16 v[0:3], v[212:215], v[196:199], v[0:3]
	v_mfma_f32_16x16x32_bf16 v[52:55], v[208:211], v[176:179], v[52:55]
	v_mfma_f32_16x16x32_bf16 v[48:51], v[216:219], v[176:179], v[48:51]
	v_mfma_f32_16x16x32_bf16 v[36:39], v[208:211], v[184:187], v[36:39]
	v_mfma_f32_16x16x32_bf16 v[32:35], v[216:219], v[184:187], v[32:35]
	v_mfma_f32_16x16x32_bf16 v[20:23], v[208:211], v[192:195], v[20:23]
	v_mfma_f32_16x16x32_bf16 v[16:19], v[216:219], v[192:195], v[16:19]
	v_mfma_f32_16x16x32_bf16 v[4:7], v[208:211], v[200:203], v[4:7]
	v_mfma_f32_16x16x32_bf16 v[0:3], v[216:219], v[200:203], v[0:3]
	s_setprio 0
	s_add_i32 s54, s54, 2
	s_add_u32 s42, s42, 0x100
	s_addc_u32 s43, s43, 0
	s_add_u32 s52, s52, 0x100
	s_addc_u32 s53, s53, 0
	s_cmp_gt_u32 s54, 29
	s_barrier
	s_cbranch_scc0 .LBB0_203
	v_lshl_add_u32 v144, s40, 8, v150
	v_ashrrev_i32_e32 v145, 31, v144
	v_lshl_add_u64 v[148:149], v[144:145], 2, s[14:15]
	v_mov_b32_e32 v145, v224
	v_mov_b32_e32 v204, v225
	v_mov_b32_e32 v205, v226
	v_mov_b32_e32 v206, v227
	v_mov_b32_e32 v207, v228
	v_mov_b32_e32 v208, v229
	v_mov_b32_e32 v209, v230
	v_mov_b32_e32 v210, v231
	v_lshl_or_b32 v156, s34, 7, v152
	v_ashrrev_i32_e32 v157, 31, v156
	v_mov_b64_e32 v[146:147], s[20:21]
	v_mad_i64_i32 v[160:161], s[42:43], v144, s49, v[146:147]
	s_and_b64 vcc, exec, s[4:5]
	s_mov_b32 s34, s22
	s_mov_b32 s40, s24
	s_mov_b64 s[44:45], s[28:29]
	v_mul_f32_e32 v162, v145, v145
	v_mul_f32_e32 v145, 0xbfb8aa3b, v145
	v_mul_f32_e32 v163, v124, v162
	v_mul_f32_e32 v124, v124, v145
	v_exp_f32_e32 v124, v124
	s_nop 0
	v_add_f32_e32 v124, 1.0, v124
	v_rcp_f32_e32 v124, v124
	s_nop 0
	v_mul_f32_e32 v124, v163, v124
	v_mul_f32_e32 v116, v116, v124
	v_mul_f32_e32 v124, v120, v162
	v_mul_f32_e32 v120, v120, v145
	v_exp_f32_e32 v120, v120
	s_nop 0
	v_add_f32_e32 v120, 1.0, v120
	v_rcp_f32_e32 v120, v120
	s_nop 0
	v_mul_f32_e32 v120, v124, v120
	v_mul_f32_e32 v124, v125, v145
	v_exp_f32_e32 v124, v124
	v_mul_f32_e32 v120, v112, v120
	v_mul_f32_e32 v112, v125, v162
	v_add_f32_e32 v124, 1.0, v124
	v_rcp_f32_e32 v124, v124
	s_nop 0
	v_mul_f32_e32 v112, v112, v124
	v_mul_f32_e32 v117, v117, v112
	v_mul_f32_e32 v112, v121, v162
	v_mul_f32_e32 v121, v121, v145
	v_exp_f32_e32 v121, v121
	s_nop 0
	v_add_f32_e32 v121, 1.0, v121
	v_rcp_f32_e32 v121, v121
	s_nop 0
	v_mul_f32_e32 v112, v112, v121
	v_mul_f32_e32 v121, v113, v112
	v_mul_f32_e32 v113, v126, v145
	v_exp_f32_e32 v113, v113
	v_mul_f32_e32 v112, v126, v162
	v_add_f32_e32 v113, 1.0, v113
	v_rcp_f32_e32 v113, v113
	s_nop 0
	v_mul_f32_e32 v112, v112, v113
	v_mul_f32_e32 v113, v122, v145
	v_exp_f32_e32 v113, v113
	v_mul_f32_e32 v124, v118, v112
	v_mul_f32_e32 v112, v122, v162
	v_add_f32_e32 v113, 1.0, v113
	v_rcp_f32_e32 v113, v113
	s_nop 0
	v_mul_f32_e32 v112, v112, v113
	v_mul_f32_e32 v113, v127, v145
	v_exp_f32_e32 v113, v113
	v_mul_f32_e32 v122, v114, v112
	v_mul_f32_e32 v112, v127, v162
	v_cvt_pk_bf16_f32 v114, v116, v117
	v_add_f32_e32 v113, 1.0, v113
	v_rcp_f32_e32 v113, v113
	s_nop 0
	v_mul_f32_e32 v112, v112, v113
	v_mul_f32_e32 v113, v123, v145
	v_exp_f32_e32 v113, v113
	v_mul_f32_e32 v125, v119, v112
	v_mul_f32_e32 v112, v123, v162
	v_add_f32_e32 v113, 1.0, v113
	v_rcp_f32_e32 v113, v113
	s_nop 0
	v_mul_f32_e32 v112, v112, v113
	v_mul_f32_e32 v123, v115, v112
	v_lshlrev_b64 v[112:113], 1, v[156:157]
	v_lshl_add_u64 v[118:119], v[160:161], 0, v[112:113]
	v_cvt_pk_bf16_f32 v115, v124, v125
	v_cvt_pk_bf16_f32 v116, v120, v121
	v_cvt_pk_bf16_f32 v117, v122, v123
	global_store_dwordx4 v[118:119], v[114:117], off
	s_nop 1
	v_mov_b32_e32 v116, v204
	s_nop 0
	v_or_b32_e32 v114, 16, v144
	v_mad_i64_i32 v[114:115], s[42:43], v114, s49, v[146:147]
	v_mul_f32_e32 v117, v116, v116
; __device__ __forceinline__ float fast_rcp(float x) { return __builtin_amdgcn_rcpf(x); }
; __device__ __forceinline__ float fast_exp2(float x) { return __builtin_amdgcn_exp2f(x); }
; __device__ __forceinline__ u32x4 pack8(f32x4 v0, f32x4 v1) { u32x4 w; w.x = cvt_pk_bf16(v0[0], v0[1]); w.y = cvt_pk_bf16(v0[2], v0[3]); w.z = cvt_pk_bf16(v1[0], v1[1]); w.w = cvt_pk_bf16(v1[2], v1[3]); return w; }
;     __device__ __forceinline__ void operator()(const f32x4 (&acc)[2][2][4][2], const Unit& u, int wr, int wc, int fr, int fq) const {
;     ...
;             for (int m = 0; m < 4; ++m) { bf16_t* rowp = O + (size_t)(row0 + ai * HALF + m * 16) * DFF + col0;
;                 const float r = rs[row0 + ai * HALF + m * 16], r2 = r * r;
;                 f32x4 h0, h1;
; #pragma unroll
;                 for (int j = 0; j < 4; ++j) {
;                     const float g0 = acc[ai][0][m][0][j], g1 = acc[ai][0][m][1][j];
;                     h0[j] = g0 * r2 * fast_rcp(1.0f + fast_exp2(g0 * (-LOG2E * r))) * acc[ai][1][m][0][j];
;                     h1[j] = g1 * r2 * fast_rcp(1.0f + fast_exp2(g1 * (-LOG2E * r))) * acc[ai][1][m][1][j]; }
;                 *(u32x4*)rowp = pack8(h0, h1); }
	v_mul_f32_e32 v116, 0xbfb8aa3b, v116
	v_mul_f32_e32 v118, v108, v117
	v_mul_f32_e32 v108, v108, v116
	v_exp_f32_e32 v108, v108
	s_nop 0
	v_add_f32_e32 v108, 1.0, v108
	v_rcp_f32_e32 v108, v108
	s_nop 0
	v_mul_f32_e32 v108, v118, v108
	v_mul_f32_e32 v108, v100, v108
	v_mul_f32_e32 v100, v104, v117
	v_mul_f32_e32 v104, v104, v116
	v_exp_f32_e32 v104, v104
	s_nop 0
	v_add_f32_e32 v104, 1.0, v104
	v_rcp_f32_e32 v104, v104
	s_nop 0
	v_mul_f32_e32 v100, v100, v104
	v_mul_f32_e32 v104, v96, v100
	v_mul_f32_e32 v100, v109, v116
	v_exp_f32_e32 v100, v100
	v_mul_f32_e32 v96, v109, v117
	v_add_f32_e32 v100, 1.0, v100
	v_rcp_f32_e32 v100, v100
	s_nop 0
	v_mul_f32_e32 v96, v96, v100
	v_mul_f32_e32 v96, v101, v96
	v_mul_f32_e32 v101, v105, v116
	v_exp_f32_e32 v101, v101
	v_mul_f32_e32 v100, v105, v117
	v_cvt_pk_bf16_f32 v96, v108, v96
	v_add_f32_e32 v101, 1.0, v101
	v_rcp_f32_e32 v101, v101
	s_nop 0
	v_mul_f32_e32 v100, v100, v101
	v_mul_f32_e32 v105, v97, v100
	v_mul_f32_e32 v100, v110, v116
	v_exp_f32_e32 v100, v100
	v_mul_f32_e32 v101, v106, v116
	v_exp_f32_e32 v101, v101
	v_mul_f32_e32 v97, v110, v117
	v_add_f32_e32 v100, 1.0, v100
	v_rcp_f32_e32 v100, v100
	v_add_f32_e32 v101, 1.0, v101
	v_rcp_f32_e32 v101, v101
	v_mul_f32_e32 v97, v97, v100
	v_mul_f32_e32 v100, v106, v117
	v_mul_f32_e32 v100, v100, v101
	v_mul_f32_e32 v97, v102, v97
	v_mul_f32_e32 v102, v98, v100
	v_mul_f32_e32 v100, v111, v116
	v_exp_f32_e32 v100, v100
	v_mul_f32_e32 v101, v107, v116
	v_exp_f32_e32 v101, v101
	v_mul_f32_e32 v98, v111, v117
	v_add_f32_e32 v100, 1.0, v100
	v_rcp_f32_e32 v100, v100
	v_add_f32_e32 v101, 1.0, v101
	v_rcp_f32_e32 v101, v101
	v_mul_f32_e32 v98, v98, v100
	v_mul_f32_e32 v100, v107, v117
	v_mul_f32_e32 v100, v100, v101
	v_mul_f32_e32 v98, v103, v98
	v_mul_f32_e32 v99, v99, v100
	v_lshl_add_u64 v[100:101], v[114:115], 0, v[112:113]
	v_cvt_pk_bf16_f32 v97, v97, v98
	v_cvt_pk_bf16_f32 v98, v104, v105
	v_cvt_pk_bf16_f32 v99, v102, v99
	global_store_dwordx4 v[100:101], v[96:99], off
	s_nop 1
	v_mov_b32_e32 v98, v205
	s_nop 0
	v_or_b32_e32 v96, 32, v144
	v_mad_i64_i32 v[96:97], s[42:43], v96, s49, v[146:147]
	v_mul_f32_e32 v99, v98, v98
	v_mul_f32_e32 v98, 0xbfb8aa3b, v98
	v_mul_f32_e32 v100, v92, v99
	v_mul_f32_e32 v92, v92, v98
	v_exp_f32_e32 v92, v92
	s_nop 0
	v_add_f32_e32 v92, 1.0, v92
	v_rcp_f32_e32 v92, v92
	s_nop 0
	v_mul_f32_e32 v92, v100, v92
	v_mul_f32_e32 v92, v84, v92
	v_mul_f32_e32 v84, v88, v99
	v_mul_f32_e32 v88, v88, v98
	v_exp_f32_e32 v88, v88
	s_nop 0
	v_add_f32_e32 v88, 1.0, v88
	v_rcp_f32_e32 v88, v88
	s_nop 0
	v_mul_f32_e32 v84, v84, v88
	v_mul_f32_e32 v88, v80, v84
	v_mul_f32_e32 v84, v93, v98
	v_exp_f32_e32 v84, v84
	v_mul_f32_e32 v80, v93, v99
	v_add_f32_e32 v84, 1.0, v84
	v_rcp_f32_e32 v84, v84
	s_nop 0
	v_mul_f32_e32 v80, v80, v84
	v_mul_f32_e32 v80, v85, v80
	v_mul_f32_e32 v85, v89, v98
	v_exp_f32_e32 v85, v85
	v_mul_f32_e32 v84, v89, v99
	v_cvt_pk_bf16_f32 v80, v92, v80
	v_add_f32_e32 v85, 1.0, v85
	v_rcp_f32_e32 v85, v85
	s_nop 0
	v_mul_f32_e32 v84, v84, v85
	v_mul_f32_e32 v89, v81, v84
	v_mul_f32_e32 v84, v94, v98
	v_exp_f32_e32 v84, v84
	v_mul_f32_e32 v85, v90, v98
	v_exp_f32_e32 v85, v85
	v_mul_f32_e32 v81, v94, v99
	v_add_f32_e32 v84, 1.0, v84
	v_rcp_f32_e32 v84, v84
	v_add_f32_e32 v85, 1.0, v85
	v_rcp_f32_e32 v85, v85
	v_mul_f32_e32 v81, v81, v84
	v_mul_f32_e32 v84, v90, v99
	v_mul_f32_e32 v84, v84, v85
	v_mul_f32_e32 v81, v86, v81
	v_mul_f32_e32 v86, v82, v84
	v_mul_f32_e32 v84, v95, v98
	v_exp_f32_e32 v84, v84
	v_mul_f32_e32 v85, v91, v98
	v_exp_f32_e32 v85, v85
	v_mul_f32_e32 v82, v95, v99
	v_add_f32_e32 v84, 1.0, v84
	v_rcp_f32_e32 v84, v84
	v_add_f32_e32 v85, 1.0, v85
	v_rcp_f32_e32 v85, v85
	v_mul_f32_e32 v82, v82, v84
	v_mul_f32_e32 v84, v91, v99
	v_mul_f32_e32 v84, v84, v85
	v_mul_f32_e32 v82, v87, v82
	v_mul_f32_e32 v83, v83, v84
	v_lshl_add_u64 v[84:85], v[96:97], 0, v[112:113]
	v_cvt_pk_bf16_f32 v81, v81, v82
	v_cvt_pk_bf16_f32 v82, v88, v89
	v_cvt_pk_bf16_f32 v83, v86, v83
	global_store_dwordx4 v[84:85], v[80:83], off
	s_nop 1
	v_mov_b32_e32 v82, v206
	s_nop 0
	v_or_b32_e32 v80, 48, v144
	v_mad_i64_i32 v[80:81], s[42:43], v80, s49, v[146:147]
	v_mul_f32_e32 v83, v82, v82
	v_mul_f32_e32 v82, 0xbfb8aa3b, v82
	v_mul_f32_e32 v84, v76, v83
	v_mul_f32_e32 v76, v76, v82
	v_exp_f32_e32 v76, v76
	s_nop 0
	v_add_f32_e32 v76, 1.0, v76
	v_rcp_f32_e32 v76, v76
	s_nop 0
	v_mul_f32_e32 v76, v84, v76
	v_mul_f32_e32 v76, v68, v76
	v_mul_f32_e32 v68, v72, v83
	v_mul_f32_e32 v72, v72, v82
	v_exp_f32_e32 v72, v72
	s_nop 0
	v_add_f32_e32 v72, 1.0, v72
	v_rcp_f32_e32 v72, v72
	s_nop 0
	v_mul_f32_e32 v68, v68, v72
	v_mul_f32_e32 v72, v64, v68
	v_mul_f32_e32 v68, v77, v82
	v_exp_f32_e32 v68, v68
	v_mul_f32_e32 v64, v77, v83
	v_add_f32_e32 v68, 1.0, v68
	v_rcp_f32_e32 v68, v68
	s_nop 0
	v_mul_f32_e32 v64, v64, v68
	v_mul_f32_e32 v64, v69, v64
	v_mul_f32_e32 v69, v73, v82
	v_exp_f32_e32 v69, v69
	v_mul_f32_e32 v68, v73, v83
	v_cvt_pk_bf16_f32 v64, v76, v64
	v_add_f32_e32 v69, 1.0, v69
	v_rcp_f32_e32 v69, v69
	s_nop 0
	v_mul_f32_e32 v68, v68, v69
	v_mul_f32_e32 v73, v65, v68
	v_mul_f32_e32 v68, v78, v82
	v_exp_f32_e32 v68, v68
	v_mul_f32_e32 v69, v74, v82
	v_exp_f32_e32 v69, v69
	v_mul_f32_e32 v65, v78, v83
	v_add_f32_e32 v68, 1.0, v68
	v_rcp_f32_e32 v68, v68
	v_add_f32_e32 v69, 1.0, v69
	v_rcp_f32_e32 v69, v69
	v_mul_f32_e32 v65, v65, v68
	v_mul_f32_e32 v68, v74, v83
	v_mul_f32_e32 v68, v68, v69
	v_mul_f32_e32 v65, v70, v65
	v_mul_f32_e32 v70, v66, v68
	v_mul_f32_e32 v68, v79, v82
	v_exp_f32_e32 v68, v68
	v_mul_f32_e32 v69, v75, v82
	v_exp_f32_e32 v69, v69
	v_mul_f32_e32 v66, v79, v83
	v_add_f32_e32 v68, 1.0, v68
	v_rcp_f32_e32 v68, v68
; __device__ __forceinline__ float fast_rcp(float x) { return __builtin_amdgcn_rcpf(x); }
; __device__ __forceinline__ float fast_exp2(float x) { return __builtin_amdgcn_exp2f(x); }
; __device__ __forceinline__ u32x4 pack8(f32x4 v0, f32x4 v1) { u32x4 w; w.x = cvt_pk_bf16(v0[0], v0[1]); w.y = cvt_pk_bf16(v0[2], v0[3]); w.z = cvt_pk_bf16(v1[0], v1[1]); w.w = cvt_pk_bf16(v1[2], v1[3]); return w; }
;     __device__ __forceinline__ void operator()(const f32x4 (&acc)[2][2][4][2], const Unit& u, int wr, int wc, int fr, int fq) const {
;     ...
;             for (int m = 0; m < 4; ++m) { bf16_t* rowp = O + (size_t)(row0 + ai * HALF + m * 16) * DFF + col0;
;                 const float r = rs[row0 + ai * HALF + m * 16], r2 = r * r;
;                 f32x4 h0, h1;
; #pragma unroll
;                 for (int j = 0; j < 4; ++j) {
;                     const float g0 = acc[ai][0][m][0][j], g1 = acc[ai][0][m][1][j];
;                     h0[j] = g0 * r2 * fast_rcp(1.0f + fast_exp2(g0 * (-LOG2E * r))) * acc[ai][1][m][0][j];
;                     h1[j] = g1 * r2 * fast_rcp(1.0f + fast_exp2(g1 * (-LOG2E * r))) * acc[ai][1][m][1][j]; }
;                 *(u32x4*)rowp = pack8(h0, h1); }
	v_add_f32_e32 v69, 1.0, v69
	v_rcp_f32_e32 v69, v69
	v_mul_f32_e32 v66, v66, v68
	v_mul_f32_e32 v68, v75, v83
	v_mul_f32_e32 v68, v68, v69
	v_mul_f32_e32 v66, v71, v66
	v_mul_f32_e32 v67, v67, v68
	v_lshl_add_u64 v[68:69], v[80:81], 0, v[112:113]
	v_cvt_pk_bf16_f32 v65, v65, v66
	v_cvt_pk_bf16_f32 v66, v72, v73
	v_cvt_pk_bf16_f32 v67, v70, v67
	global_store_dwordx4 v[68:69], v[64:67], off
	s_nop 1
	v_mov_b32_e32 v66, v207
	s_nop 0
	v_add_u32_e32 v64, 0x80, v144
	v_mad_i64_i32 v[64:65], s[42:43], v64, s49, v[146:147]
	v_mul_f32_e32 v67, v66, v66
	v_mul_f32_e32 v66, 0xbfb8aa3b, v66
	v_mul_f32_e32 v68, v60, v67
	v_mul_f32_e32 v60, v60, v66
	v_exp_f32_e32 v60, v60
	s_nop 0
	v_add_f32_e32 v60, 1.0, v60
	v_rcp_f32_e32 v60, v60
	s_nop 0
	v_mul_f32_e32 v60, v68, v60
	v_mul_f32_e32 v60, v52, v60
	v_mul_f32_e32 v52, v56, v67
	v_mul_f32_e32 v56, v56, v66
	v_exp_f32_e32 v56, v56
	s_nop 0
	v_add_f32_e32 v56, 1.0, v56
	v_rcp_f32_e32 v56, v56
	s_nop 0
	v_mul_f32_e32 v52, v52, v56
	v_mul_f32_e32 v56, v48, v52
	v_mul_f32_e32 v52, v61, v66
	v_exp_f32_e32 v52, v52
	v_mul_f32_e32 v48, v61, v67
	v_add_f32_e32 v52, 1.0, v52
	v_rcp_f32_e32 v52, v52
	s_nop 0
	v_mul_f32_e32 v48, v48, v52
	v_mul_f32_e32 v48, v53, v48
	v_mul_f32_e32 v53, v57, v66
	v_exp_f32_e32 v53, v53
	v_mul_f32_e32 v52, v57, v67
	v_cvt_pk_bf16_f32 v48, v60, v48
	v_add_f32_e32 v53, 1.0, v53
	v_rcp_f32_e32 v53, v53
	s_nop 0
	v_mul_f32_e32 v52, v52, v53
	v_mul_f32_e32 v57, v49, v52
	v_mul_f32_e32 v52, v62, v66
	v_exp_f32_e32 v52, v52
	v_mul_f32_e32 v53, v58, v66
	v_exp_f32_e32 v53, v53
	v_mul_f32_e32 v49, v62, v67
	v_add_f32_e32 v52, 1.0, v52
	v_rcp_f32_e32 v52, v52
	v_add_f32_e32 v53, 1.0, v53
	v_rcp_f32_e32 v53, v53
	v_mul_f32_e32 v49, v49, v52
	v_mul_f32_e32 v52, v58, v67
	v_mul_f32_e32 v52, v52, v53
	v_mul_f32_e32 v49, v54, v49
	v_mul_f32_e32 v54, v50, v52
	v_mul_f32_e32 v52, v63, v66
	v_exp_f32_e32 v52, v52
	v_mul_f32_e32 v53, v59, v66
	v_exp_f32_e32 v53, v53
	v_mul_f32_e32 v50, v63, v67
	v_add_f32_e32 v52, 1.0, v52
	v_rcp_f32_e32 v52, v52
	v_add_f32_e32 v53, 1.0, v53
	v_rcp_f32_e32 v53, v53
	v_mul_f32_e32 v50, v50, v52
	v_mul_f32_e32 v52, v59, v67
	v_mul_f32_e32 v52, v52, v53
	v_mul_f32_e32 v50, v55, v50
	v_mul_f32_e32 v51, v51, v52
	v_lshl_add_u64 v[52:53], v[64:65], 0, v[112:113]
	v_cvt_pk_bf16_f32 v49, v49, v50
	v_cvt_pk_bf16_f32 v50, v56, v57
	v_cvt_pk_bf16_f32 v51, v54, v51
	global_store_dwordx4 v[52:53], v[48:51], off
	s_nop 1
	v_mov_b32_e32 v50, v208
	s_nop 0
	v_add_u32_e32 v48, 0x90, v144
	v_mad_i64_i32 v[48:49], s[42:43], v48, s49, v[146:147]
	v_mul_f32_e32 v51, v50, v50
	v_mul_f32_e32 v50, 0xbfb8aa3b, v50
	v_mul_f32_e32 v52, v44, v51
	v_mul_f32_e32 v44, v44, v50
	v_exp_f32_e32 v44, v44
	s_nop 0
	v_add_f32_e32 v44, 1.0, v44
	v_rcp_f32_e32 v44, v44
	s_nop 0
	v_mul_f32_e32 v44, v52, v44
	v_mul_f32_e32 v44, v36, v44
	v_mul_f32_e32 v36, v40, v51
	v_mul_f32_e32 v40, v40, v50
	v_exp_f32_e32 v40, v40
	s_nop 0
	v_add_f32_e32 v40, 1.0, v40
	v_rcp_f32_e32 v40, v40
	s_nop 0
	v_mul_f32_e32 v36, v36, v40
	v_mul_f32_e32 v40, v32, v36
	v_mul_f32_e32 v36, v45, v50
	v_exp_f32_e32 v36, v36
	v_mul_f32_e32 v32, v45, v51
	v_add_f32_e32 v36, 1.0, v36
	v_rcp_f32_e32 v36, v36
	s_nop 0
	v_mul_f32_e32 v32, v32, v36
	v_mul_f32_e32 v32, v37, v32
	v_mul_f32_e32 v37, v41, v50
	v_exp_f32_e32 v37, v37
	v_mul_f32_e32 v36, v41, v51
	v_cvt_pk_bf16_f32 v32, v44, v32
	v_add_f32_e32 v37, 1.0, v37
	v_rcp_f32_e32 v37, v37
	s_nop 0
	v_mul_f32_e32 v36, v36, v37
	v_mul_f32_e32 v41, v33, v36
	v_mul_f32_e32 v36, v46, v50
	v_exp_f32_e32 v36, v36
	v_mul_f32_e32 v37, v42, v50
	v_exp_f32_e32 v37, v37
	v_mul_f32_e32 v33, v46, v51
	v_add_f32_e32 v36, 1.0, v36
	v_rcp_f32_e32 v36, v36
	v_add_f32_e32 v37, 1.0, v37
	v_rcp_f32_e32 v37, v37
	v_mul_f32_e32 v33, v33, v36
	v_mul_f32_e32 v36, v42, v51
	v_mul_f32_e32 v36, v36, v37
	v_mul_f32_e32 v33, v38, v33
	v_mul_f32_e32 v38, v34, v36
	v_mul_f32_e32 v36, v47, v50
	v_exp_f32_e32 v36, v36
	v_mul_f32_e32 v37, v43, v50
	v_exp_f32_e32 v37, v37
	v_mul_f32_e32 v34, v47, v51
	v_add_f32_e32 v36, 1.0, v36
	v_rcp_f32_e32 v36, v36
	v_add_f32_e32 v37, 1.0, v37
	v_rcp_f32_e32 v37, v37
	v_mul_f32_e32 v34, v34, v36
	v_mul_f32_e32 v36, v43, v51
	v_mul_f32_e32 v36, v36, v37
	v_mul_f32_e32 v34, v39, v34
	v_mul_f32_e32 v35, v35, v36
; __device__ __forceinline__ float fast_rcp(float x) { return __builtin_amdgcn_rcpf(x); }
; __device__ __forceinline__ float fast_exp2(float x) { return __builtin_amdgcn_exp2f(x); }
; #define PG8_WAIT_V(n) asm volatile("s_waitcnt vmcnt(" #n ")" ::: "memory")
; #define PG8_BAR __builtin_amdgcn_s_barrier()
; __device__ __forceinline__ u32x4 pack8(f32x4 v0, f32x4 v1) { u32x4 w; w.x = cvt_pk_bf16(v0[0], v0[1]); w.y = cvt_pk_bf16(v0[2], v0[3]); w.z = cvt_pk_bf16(v1[0], v1[1]); w.w = cvt_pk_bf16(v1[2], v1[3]); return w; }
; template <class Epi>
; __device__ __forceinline__ void gemm_phase(LAS unsigned char* lds, const Gemm g, const StaticOrder& S, const Epi& E) {
;     ...
;     PG8_WAIT_V(0);
;     if (wr == 0) PG8_BAR;
;     PG8_BAR;
;     __device__ __forceinline__ void operator()(const f32x4 (&acc)[2][2][4][2], const Unit& u, int wr, int wc, int fr, int fq) const {
;     ...
;             for (int m = 0; m < 4; ++m) { bf16_t* rowp = O + (size_t)(row0 + ai * HALF + m * 16) * DFF + col0;
;                 const float r = rs[row0 + ai * HALF + m * 16], r2 = r * r;
;                 f32x4 h0, h1;
; #pragma unroll
;                 for (int j = 0; j < 4; ++j) {
;                     const float g0 = acc[ai][0][m][0][j], g1 = acc[ai][0][m][1][j];
;                     h0[j] = g0 * r2 * fast_rcp(1.0f + fast_exp2(g0 * (-LOG2E * r))) * acc[ai][1][m][0][j];
;                     h1[j] = g1 * r2 * fast_rcp(1.0f + fast_exp2(g1 * (-LOG2E * r))) * acc[ai][1][m][1][j]; }
;                 *(u32x4*)rowp = pack8(h0, h1); }
	v_lshl_add_u64 v[36:37], v[48:49], 0, v[112:113]
	v_cvt_pk_bf16_f32 v33, v33, v34
	v_cvt_pk_bf16_f32 v34, v40, v41
	v_cvt_pk_bf16_f32 v35, v38, v35
	global_store_dwordx4 v[36:37], v[32:35], off
	s_nop 1
	v_mov_b32_e32 v34, v209
	s_nop 0
	v_add_u32_e32 v32, 0xa0, v144
	v_mad_i64_i32 v[32:33], s[42:43], v32, s49, v[146:147]
	v_mul_f32_e32 v35, v34, v34
	v_mul_f32_e32 v34, 0xbfb8aa3b, v34
	v_mul_f32_e32 v36, v28, v35
	v_mul_f32_e32 v28, v28, v34
	v_exp_f32_e32 v28, v28
	s_nop 0
	v_add_f32_e32 v28, 1.0, v28
	v_rcp_f32_e32 v28, v28
	s_nop 0
	v_mul_f32_e32 v28, v36, v28
	v_mul_f32_e32 v28, v20, v28
	v_mul_f32_e32 v20, v24, v35
	v_mul_f32_e32 v24, v24, v34
	v_exp_f32_e32 v24, v24
	s_nop 0
	v_add_f32_e32 v24, 1.0, v24
	v_rcp_f32_e32 v24, v24
	s_nop 0
	v_mul_f32_e32 v20, v20, v24
	v_mul_f32_e32 v24, v16, v20
	v_mul_f32_e32 v20, v29, v34
	v_exp_f32_e32 v20, v20
	v_mul_f32_e32 v16, v29, v35
	v_add_f32_e32 v20, 1.0, v20
	v_rcp_f32_e32 v20, v20
	s_nop 0
	v_mul_f32_e32 v16, v16, v20
	v_mul_f32_e32 v16, v21, v16
	v_mul_f32_e32 v21, v25, v34
	v_exp_f32_e32 v21, v21
	v_mul_f32_e32 v20, v25, v35
	v_cvt_pk_bf16_f32 v16, v28, v16
	v_add_f32_e32 v21, 1.0, v21
	v_rcp_f32_e32 v21, v21
	s_nop 0
	v_mul_f32_e32 v20, v20, v21
	v_mul_f32_e32 v25, v17, v20
	v_mul_f32_e32 v20, v30, v34
	v_exp_f32_e32 v20, v20
	v_mul_f32_e32 v21, v26, v34
	v_exp_f32_e32 v21, v21
	v_mul_f32_e32 v17, v30, v35
	v_add_f32_e32 v20, 1.0, v20
	v_rcp_f32_e32 v20, v20
	v_add_f32_e32 v21, 1.0, v21
	v_rcp_f32_e32 v21, v21
	v_mul_f32_e32 v17, v17, v20
	v_mul_f32_e32 v20, v26, v35
	v_mul_f32_e32 v20, v20, v21
	v_mul_f32_e32 v17, v22, v17
	v_mul_f32_e32 v22, v18, v20
	v_mul_f32_e32 v20, v31, v34
	v_exp_f32_e32 v20, v20
	v_mul_f32_e32 v21, v27, v34
	v_exp_f32_e32 v21, v21
	v_mul_f32_e32 v18, v31, v35
	v_add_f32_e32 v20, 1.0, v20
	v_rcp_f32_e32 v20, v20
	v_add_f32_e32 v21, 1.0, v21
	v_rcp_f32_e32 v21, v21
	v_mul_f32_e32 v18, v18, v20
	v_mul_f32_e32 v20, v27, v35
	v_mul_f32_e32 v20, v20, v21
	v_mul_f32_e32 v18, v23, v18
	v_mul_f32_e32 v19, v19, v20
	v_lshl_add_u64 v[20:21], v[32:33], 0, v[112:113]
	v_cvt_pk_bf16_f32 v17, v17, v18
	v_cvt_pk_bf16_f32 v18, v24, v25
	v_cvt_pk_bf16_f32 v19, v22, v19
	global_store_dwordx4 v[20:21], v[16:19], off
	s_nop 1
	v_mov_b32_e32 v18, v210
	s_nop 0
	v_add_u32_e32 v16, 0xb0, v144
	v_mad_i64_i32 v[16:17], s[42:43], v16, s49, v[146:147]
	s_mov_b64 s[42:43], s[26:27]
	v_mul_f32_e32 v19, v18, v18
	v_mul_f32_e32 v18, 0xbfb8aa3b, v18
	v_mul_f32_e32 v20, v12, v19
	v_mul_f32_e32 v12, v12, v18
	v_exp_f32_e32 v12, v12
	s_nop 0
	v_add_f32_e32 v12, 1.0, v12
	v_rcp_f32_e32 v12, v12
	s_nop 0
	v_mul_f32_e32 v12, v20, v12
	v_mul_f32_e32 v12, v4, v12
	v_mul_f32_e32 v4, v8, v19
	v_mul_f32_e32 v8, v8, v18
	v_exp_f32_e32 v8, v8
	s_nop 0
	v_add_f32_e32 v8, 1.0, v8
	v_rcp_f32_e32 v8, v8
	s_nop 0
	v_mul_f32_e32 v4, v4, v8
	v_mul_f32_e32 v8, v0, v4
	v_mul_f32_e32 v4, v13, v18
	v_exp_f32_e32 v4, v4
	v_mul_f32_e32 v0, v13, v19
	v_add_f32_e32 v4, 1.0, v4
	v_rcp_f32_e32 v4, v4
	s_nop 0
	v_mul_f32_e32 v0, v0, v4
	v_mul_f32_e32 v0, v5, v0
	v_mul_f32_e32 v5, v9, v18
	v_exp_f32_e32 v5, v5
	v_mul_f32_e32 v4, v9, v19
	v_cvt_pk_bf16_f32 v0, v12, v0
	v_add_f32_e32 v5, 1.0, v5
	v_rcp_f32_e32 v5, v5
	s_nop 0
	v_mul_f32_e32 v4, v4, v5
	v_mul_f32_e32 v9, v1, v4
	v_mul_f32_e32 v4, v14, v18
	v_exp_f32_e32 v4, v4
	v_mul_f32_e32 v5, v10, v18
	v_exp_f32_e32 v5, v5
	v_mul_f32_e32 v1, v14, v19
	v_add_f32_e32 v4, 1.0, v4
	v_rcp_f32_e32 v4, v4
	v_add_f32_e32 v5, 1.0, v5
	v_rcp_f32_e32 v5, v5
	v_mul_f32_e32 v1, v1, v4
	v_mul_f32_e32 v4, v10, v19
	v_mul_f32_e32 v4, v4, v5
	v_mul_f32_e32 v1, v6, v1
	v_mul_f32_e32 v6, v2, v4
	v_mul_f32_e32 v4, v15, v18
	v_exp_f32_e32 v4, v4
	v_mul_f32_e32 v5, v11, v18
	v_exp_f32_e32 v5, v5
	v_mul_f32_e32 v2, v15, v19
	v_add_f32_e32 v4, 1.0, v4
	v_rcp_f32_e32 v4, v4
	v_add_f32_e32 v5, 1.0, v5
	v_rcp_f32_e32 v5, v5
	v_mul_f32_e32 v2, v2, v4
	v_mul_f32_e32 v4, v11, v19
	v_mul_f32_e32 v4, v4, v5
	v_mul_f32_e32 v2, v7, v2
	v_mul_f32_e32 v3, v3, v4
	v_lshl_add_u64 v[4:5], v[16:17], 0, v[112:113]
	v_cvt_pk_bf16_f32 v1, v1, v2
	v_cvt_pk_bf16_f32 v2, v8, v9
	v_cvt_pk_bf16_f32 v3, v6, v3
	global_store_dwordx4 v[4:5], v[0:3], off
	s_cbranch_vccz .LBB0_200
	s_waitcnt vmcnt(0)
	s_cmpk_gt_u32 s3, 0xff
	s_cbranch_scc1 .LBB0_207
	s_barrier

; #define PG8_STAGE(bufoff, gbase, voff) do { _Pragma("unroll") for (int _i = 0; _i < 2; ++_i) \
;         __builtin_amdgcn_global_load_lds((const unsigned*)((const char*)(gbase) + (voff)[_i]), (LAS unsigned*)(lds + (bufoff) + ldsw + _i * 8192), 16, 0, 0); } while (0)
; #define PG8_LDA(dst, b, h) do { _Pragma("unroll") for (int m = 0; m < 4; ++m) _Pragma("unroll") for (int k = 0; k < 2; ++k) dst[m][k] = *(const LAS bf16x8*)(lds + PG8_SA(b, h) + aoff + m * 2048 + k * 1024); } while (0)
; #define PG8_LDB(dst, b, h) do { _Pragma("unroll") for (int n = 0; n < 2; ++n) _Pragma("unroll") for (int k = 0; k < 2; ++k) dst[n][k] = *(const LAS bf16x8*)(lds + PG8_SB(b, h) + boff + n * 2048 + k * 1024); } while (0)
; #define PG8_MMA(ai, bj, At, Bt) do { __builtin_amdgcn_s_setprio(1); _Pragma("unroll") for (int m = 0; m < 4; ++m) _Pragma("unroll") for (int n = 0; n < 2; ++n) _Pragma("unroll") for (int k = 0; k < 2; ++k) \
;         acc[ai][bj][m][n] = __builtin_amdgcn_mfma_f32_16x16x32_bf16(Bt[n][k], At[m][k], acc[ai][bj][m][n], 0, 0, 0); __builtin_amdgcn_s_setprio(0); } while (0)
; #define PG8_WAIT_V(n) asm volatile("s_waitcnt vmcnt(" #n ")" ::: "memory")
; #define PG8_WAIT_L(n) asm volatile("s_waitcnt lgkmcnt(" #n ")" ::: "memory")
; #define PG8_BAR __builtin_amdgcn_s_barrier()
; #define PG8_SCHED __builtin_amdgcn_sched_barrier(0)
; template <class Epi>
; __device__ __forceinline__ void gemm_phase(LAS unsigned char* lds, const Gemm g, const StaticOrder& S, const Epi& E) {
;     ...
;             PG8_LDB(B0, 0, 0); PG8_SCHED; PG8_LDA(At, 0, 0); PG8_STAGE(PG8_SA(1, 1), a1 + hstep, voffA);
;             PG8_WAIT_L(8); PG8_BAR; PG8_WAIT_L(0); PG8_MMA(0, 0, At, B0); PG8_BAR; PG8_SCHED;
;             PG8_LDB(B1, 0, 1); PG8_STAGE(PG8_SB(0, 0), b2, voffB);
;             PG8_BAR; PG8_WAIT_L(0); PG8_MMA(0, 1, At, B1); PG8_BAR;
;             PG8_LDA(At, 0, 1); PG8_STAGE(PG8_SA(0, 0), a2, voffA);
;             PG8_BAR; PG8_WAIT_L(0); PG8_MMA(1, 0, At, B0); PG8_BAR; PG8_SCHED;
;             PG8_STAGE(PG8_SB(0, 1), b2 + hstep, voffB);
;             PG8_WAIT_V(6); PG8_BAR; PG8_MMA(1, 1, At, B1); PG8_BAR;
.LBB0_283:
	ds_read_b128 v[148:151], v145
	ds_read_b128 v[152:155], v145 offset:1024
	ds_read_b128 v[160:163], v145 offset:2048
	ds_read_b128 v[164:167], v145 offset:3072
	s_add_u32 s50, s48, 0x100
	s_addc_u32 s51, s49, 0
	s_cmpk_eq_i32 s65, 0x54
	s_cselect_b32 s55, s47, s51
	s_cselect_b32 s54, s46, s50
	s_cselect_b32 s53, s5, s64
	s_cselect_b32 s52, s4, s63
	s_add_i32 m0, s23, 0xc000
	ds_read_b128 v[168:171], v146
	ds_read_b128 v[172:175], v146 offset:1024
	ds_read_b128 v[176:179], v146 offset:2048
	ds_read_b128 v[180:183], v146 offset:3072
	ds_read_b128 v[184:187], v146 offset:4096
	ds_read_b128 v[188:191], v146 offset:5120
	ds_read_b128 v[192:195], v146 offset:6144
	ds_read_b128 v[196:199], v146 offset:7168
	global_load_lds_dwordx4 v136, s[48:49]
	s_add_i32 m0, s23, 0xe000
	s_nop 0
	global_load_lds_dwordx4 v138, s[48:49]
	s_waitcnt lgkmcnt(8)
	s_barrier
	s_waitcnt lgkmcnt(0)
	s_setprio 1
	s_waitcnt lgkmcnt(0)
	v_mfma_f32_16x16x32_bf16 v[124:127], v[148:151], v[168:171], v[124:127]
	v_mfma_f32_16x16x32_bf16 v[120:123], v[160:163], v[168:171], v[120:123]
	v_mfma_f32_16x16x32_bf16 v[112:115], v[148:151], v[176:179], v[112:115]
	v_mfma_f32_16x16x32_bf16 v[104:107], v[160:163], v[176:179], v[104:107]
	v_mfma_f32_16x16x32_bf16 v[96:99], v[148:151], v[184:187], v[96:99]
	v_mfma_f32_16x16x32_bf16 v[88:91], v[160:163], v[184:187], v[88:91]
	v_mfma_f32_16x16x32_bf16 v[80:83], v[148:151], v[192:195], v[80:83]
	v_mfma_f32_16x16x32_bf16 v[72:75], v[160:163], v[192:195], v[72:75]
	v_mfma_f32_16x16x32_bf16 v[124:127], v[152:155], v[172:175], v[124:127]
	v_mfma_f32_16x16x32_bf16 v[120:123], v[164:167], v[172:175], v[120:123]
	v_mfma_f32_16x16x32_bf16 v[112:115], v[152:155], v[180:183], v[112:115]
	v_mfma_f32_16x16x32_bf16 v[104:107], v[164:167], v[180:183], v[104:107]
	v_mfma_f32_16x16x32_bf16 v[96:99], v[152:155], v[188:191], v[96:99]
	v_mfma_f32_16x16x32_bf16 v[88:91], v[164:167], v[188:191], v[88:91]
	v_mfma_f32_16x16x32_bf16 v[80:83], v[152:155], v[196:199], v[80:83]
	v_mfma_f32_16x16x32_bf16 v[72:75], v[164:167], v[196:199], v[72:75]
	s_setprio 0
	s_barrier
	s_add_i32 s48, s39, s13
	s_add_u32 s98, s52, s6
	s_addc_u32 s99, s53, s7
	s_mov_b32 m0, s48
	ds_read_b128 v[200:203], v147
	ds_read_b128 v[204:207], v147 offset:1024
	ds_read_b128 v[208:211], v147 offset:2048
	ds_read_b128 v[212:215], v147 offset:3072
	global_load_lds_dwordx4 v132, s[52:53]
	s_add_i32 m0, s48, 0x2000
	s_nop 0
	global_load_lds_dwordx4 v128, s[52:53]
	s_barrier
	s_waitcnt lgkmcnt(0)
	s_setprio 1
	s_waitcnt lgkmcnt(0)
	v_mfma_f32_16x16x32_bf16 v[116:119], v[200:203], v[168:171], v[116:119]
	v_mfma_f32_16x16x32_bf16 v[108:111], v[208:211], v[168:171], v[108:111]
	v_mfma_f32_16x16x32_bf16 v[100:103], v[200:203], v[176:179], v[100:103]
	v_mfma_f32_16x16x32_bf16 v[92:95], v[208:211], v[176:179], v[92:95]
	v_mfma_f32_16x16x32_bf16 v[84:87], v[200:203], v[184:187], v[84:87]
	v_mfma_f32_16x16x32_bf16 v[76:79], v[208:211], v[184:187], v[76:79]
	v_mfma_f32_16x16x32_bf16 v[68:71], v[200:203], v[192:195], v[68:71]
	v_mfma_f32_16x16x32_bf16 v[64:67], v[208:211], v[192:195], v[64:67]
	v_mfma_f32_16x16x32_bf16 v[116:119], v[204:207], v[172:175], v[116:119]
	v_mfma_f32_16x16x32_bf16 v[108:111], v[212:215], v[172:175], v[108:111]
	v_mfma_f32_16x16x32_bf16 v[100:103], v[204:207], v[180:183], v[100:103]
	v_mfma_f32_16x16x32_bf16 v[92:95], v[212:215], v[180:183], v[92:95]
	v_mfma_f32_16x16x32_bf16 v[84:87], v[204:207], v[188:191], v[84:87]
	v_mfma_f32_16x16x32_bf16 v[76:79], v[212:215], v[188:191], v[76:79]
	v_mfma_f32_16x16x32_bf16 v[68:71], v[204:207], v[196:199], v[68:71]
	v_mfma_f32_16x16x32_bf16 v[64:67], v[212:215], v[196:199], v[64:67]
	s_setprio 0
	s_mov_b32 m0, s23
	s_add_u32 s100, s54, s6
	s_addc_u32 s101, s55, s7
	s_barrier
	ds_read_b128 v[168:171], v146 offset:16384
	ds_read_b128 v[172:175], v146 offset:17408
	ds_read_b128 v[176:179], v146 offset:18432
	ds_read_b128 v[180:183], v146 offset:19456
	ds_read_b128 v[184:187], v146 offset:20480
	ds_read_b128 v[188:191], v146 offset:21504
	ds_read_b128 v[192:195], v146 offset:22528
	ds_read_b128 v[196:199], v146 offset:23552
	global_load_lds_dwordx4 v134, s[54:55]
	s_mov_b32 m0, s30
	s_nop 0
	global_load_lds_dwordx4 v130, s[54:55]
	s_barrier
	s_waitcnt lgkmcnt(0)
	s_setprio 1
	s_waitcnt lgkmcnt(0)
	v_mfma_f32_16x16x32_bf16 v[60:63], v[148:151], v[168:171], v[60:63]
	v_mfma_f32_16x16x32_bf16 v[56:59], v[160:163], v[168:171], v[56:59]
	v_mfma_f32_16x16x32_bf16 v[52:55], v[148:151], v[176:179], v[52:55]
	v_mfma_f32_16x16x32_bf16 v[44:47], v[160:163], v[176:179], v[44:47]
	v_mfma_f32_16x16x32_bf16 v[36:39], v[148:151], v[184:187], v[36:39]
	v_mfma_f32_16x16x32_bf16 v[28:31], v[160:163], v[184:187], v[28:31]
	v_mfma_f32_16x16x32_bf16 v[20:23], v[148:151], v[192:195], v[20:23]
	v_mfma_f32_16x16x32_bf16 v[12:15], v[160:163], v[192:195], v[12:15]
	v_mfma_f32_16x16x32_bf16 v[60:63], v[152:155], v[172:175], v[60:63]
	v_mfma_f32_16x16x32_bf16 v[56:59], v[164:167], v[172:175], v[56:59]
	v_mfma_f32_16x16x32_bf16 v[52:55], v[152:155], v[180:183], v[52:55]
	v_mfma_f32_16x16x32_bf16 v[44:47], v[164:167], v[180:183], v[44:47]
	v_mfma_f32_16x16x32_bf16 v[36:39], v[152:155], v[188:191], v[36:39]
	v_mfma_f32_16x16x32_bf16 v[28:31], v[164:167], v[188:191], v[28:31]
	v_mfma_f32_16x16x32_bf16 v[20:23], v[152:155], v[196:199], v[20:23]
	v_mfma_f32_16x16x32_bf16 v[12:15], v[164:167], v[196:199], v[12:15]
	s_setprio 0
	s_barrier
	s_add_u32 s48, s52, 0x160000
	s_addc_u32 s49, s53, 0
	s_add_i32 s66, s40, s13
	s_mov_b32 m0, s66
	s_nop 0
	global_load_lds_dwordx4 v132, s[48:49]
	s_add_i32 m0, s66, 0x2000
	s_nop 0
	global_load_lds_dwordx4 v128, s[48:49]
	s_waitcnt vmcnt(6)
	s_barrier
; #define PG8_STAGE(bufoff, gbase, voff) do { _Pragma("unroll") for (int _i = 0; _i < 2; ++_i) \
;         __builtin_amdgcn_global_load_lds((const unsigned*)((const char*)(gbase) + (voff)[_i]), (LAS unsigned*)(lds + (bufoff) + ldsw + _i * 8192), 16, 0, 0); } while (0)
; #define PG8_LDA(dst, b, h) do { _Pragma("unroll") for (int m = 0; m < 4; ++m) _Pragma("unroll") for (int k = 0; k < 2; ++k) dst[m][k] = *(const LAS bf16x8*)(lds + PG8_SA(b, h) + aoff + m * 2048 + k * 1024); } while (0)
; #define PG8_LDB(dst, b, h) do { _Pragma("unroll") for (int n = 0; n < 2; ++n) _Pragma("unroll") for (int k = 0; k < 2; ++k) dst[n][k] = *(const LAS bf16x8*)(lds + PG8_SB(b, h) + boff + n * 2048 + k * 1024); } while (0)
; #define PG8_MMA(ai, bj, At, Bt) do { __builtin_amdgcn_s_setprio(1); _Pragma("unroll") for (int m = 0; m < 4; ++m) _Pragma("unroll") for (int n = 0; n < 2; ++n) _Pragma("unroll") for (int k = 0; k < 2; ++k) \
;         acc[ai][bj][m][n] = __builtin_amdgcn_mfma_f32_16x16x32_bf16(Bt[n][k], At[m][k], acc[ai][bj][m][n], 0, 0, 0); __builtin_amdgcn_s_setprio(0); } while (0)
; #define PG8_WAIT_V(n) asm volatile("s_waitcnt vmcnt(" #n ")" ::: "memory")
; #define PG8_WAIT_L(n) asm volatile("s_waitcnt lgkmcnt(" #n ")" ::: "memory")
; #define PG8_BAR __builtin_amdgcn_s_barrier()
; #define PG8_SCHED __builtin_amdgcn_sched_barrier(0)
; template <class Epi>
; __device__ __forceinline__ void gemm_phase(LAS unsigned char* lds, const Gemm g, const StaticOrder& S, const Epi& E) {
;     ...
;             PG8_WAIT_V(6); PG8_BAR; PG8_MMA(1, 1, At, B1); PG8_BAR;
;             PG8_LDB(B0, 1, 0); PG8_SCHED; PG8_LDA(At, 1, 0); PG8_STAGE(PG8_SA(0, 1), a2 + hstep, voffA);
;             PG8_WAIT_L(8); PG8_BAR; PG8_WAIT_L(0); PG8_MMA(0, 0, At, B0); PG8_BAR; PG8_SCHED;
;             PG8_LDB(B1, 1, 1); PG8_STAGE(PG8_SB(1, 0), b3, voffB);
;             PG8_BAR; PG8_WAIT_L(0); PG8_MMA(0, 1, At, B1); PG8_BAR;
;             PG8_LDA(At, 1, 1); PG8_STAGE(PG8_SA(1, 0), a3, voffA);
;             PG8_BAR; PG8_WAIT_L(0); PG8_MMA(1, 0, At, B0); PG8_BAR; PG8_SCHED;
;             PG8_STAGE(PG8_SB(1, 1), b3 + hstep, voffB);
	s_setprio 1
	v_mfma_f32_16x16x32_bf16 v[48:51], v[200:203], v[168:171], v[48:51]
	v_mfma_f32_16x16x32_bf16 v[40:43], v[208:211], v[168:171], v[40:43]
	v_mfma_f32_16x16x32_bf16 v[32:35], v[200:203], v[176:179], v[32:35]
	v_mfma_f32_16x16x32_bf16 v[24:27], v[208:211], v[176:179], v[24:27]
	v_mfma_f32_16x16x32_bf16 v[16:19], v[200:203], v[184:187], v[16:19]
	v_mfma_f32_16x16x32_bf16 v[8:11], v[208:211], v[184:187], v[8:11]
	v_mfma_f32_16x16x32_bf16 v[4:7], v[200:203], v[192:195], v[4:7]
	v_mfma_f32_16x16x32_bf16 v[0:3], v[208:211], v[192:195], v[0:3]
	v_mfma_f32_16x16x32_bf16 v[48:51], v[204:207], v[172:175], v[48:51]
	v_mfma_f32_16x16x32_bf16 v[40:43], v[212:215], v[172:175], v[40:43]
	v_mfma_f32_16x16x32_bf16 v[32:35], v[204:207], v[180:183], v[32:35]
	v_mfma_f32_16x16x32_bf16 v[24:27], v[212:215], v[180:183], v[24:27]
	v_mfma_f32_16x16x32_bf16 v[16:19], v[204:207], v[188:191], v[16:19]
	v_mfma_f32_16x16x32_bf16 v[8:11], v[212:215], v[188:191], v[8:11]
	v_mfma_f32_16x16x32_bf16 v[4:7], v[204:207], v[196:199], v[4:7]
	v_mfma_f32_16x16x32_bf16 v[0:3], v[212:215], v[196:199], v[0:3]
	s_setprio 0
	s_add_i32 s66, 0, 0x18000
	v_add_u32_e32 v164, s66, v143
	s_barrier
	ds_read_b128 v[148:151], v164
	ds_read_b128 v[152:155], v164 offset:1024
	ds_read_b128 v[160:163], v164 offset:2048
	ds_read_b128 v[164:167], v164 offset:3072
	s_add_u32 s48, s54, 0x160000
	s_addc_u32 s49, s55, 0
	s_mov_b32 m0, s31
	ds_read_b128 v[168:171], v146 offset:32768
	ds_read_b128 v[172:175], v146 offset:33792
	ds_read_b128 v[176:179], v146 offset:34816
	ds_read_b128 v[180:183], v146 offset:35840
	ds_read_b128 v[184:187], v146 offset:36864
	ds_read_b128 v[188:191], v146 offset:37888
	ds_read_b128 v[192:195], v146 offset:38912
	ds_read_b128 v[196:199], v146 offset:39936
	global_load_lds_dwordx4 v134, s[48:49]
	s_mov_b32 m0, s33
	s_nop 0
	global_load_lds_dwordx4 v130, s[48:49]
	s_waitcnt lgkmcnt(8)
	s_barrier
	s_waitcnt lgkmcnt(0)
	s_setprio 1
	s_waitcnt lgkmcnt(0)
	v_mfma_f32_16x16x32_bf16 v[124:127], v[148:151], v[168:171], v[124:127]
	v_mfma_f32_16x16x32_bf16 v[120:123], v[160:163], v[168:171], v[120:123]
	v_mfma_f32_16x16x32_bf16 v[112:115], v[148:151], v[176:179], v[112:115]
	v_mfma_f32_16x16x32_bf16 v[104:107], v[160:163], v[176:179], v[104:107]
	v_mfma_f32_16x16x32_bf16 v[96:99], v[148:151], v[184:187], v[96:99]
	v_mfma_f32_16x16x32_bf16 v[88:91], v[160:163], v[184:187], v[88:91]
	v_mfma_f32_16x16x32_bf16 v[80:83], v[148:151], v[192:195], v[80:83]
	v_mfma_f32_16x16x32_bf16 v[72:75], v[160:163], v[192:195], v[72:75]
	v_mfma_f32_16x16x32_bf16 v[124:127], v[152:155], v[172:175], v[124:127]
	v_mfma_f32_16x16x32_bf16 v[120:123], v[164:167], v[172:175], v[120:123]
	v_mfma_f32_16x16x32_bf16 v[112:115], v[152:155], v[180:183], v[112:115]
	v_mfma_f32_16x16x32_bf16 v[104:107], v[164:167], v[180:183], v[104:107]
	v_mfma_f32_16x16x32_bf16 v[96:99], v[152:155], v[188:191], v[96:99]
	v_mfma_f32_16x16x32_bf16 v[88:91], v[164:167], v[188:191], v[88:91]
	v_mfma_f32_16x16x32_bf16 v[80:83], v[152:155], v[196:199], v[80:83]
	v_mfma_f32_16x16x32_bf16 v[72:75], v[164:167], v[196:199], v[72:75]
	s_setprio 0
	s_barrier
	s_add_i32 s54, 0, 0x1c000
	s_add_i32 s48, s66, s13
	v_add_u32_e32 v212, s54, v143
	s_mov_b32 m0, s48
	ds_read_b128 v[200:203], v212
	ds_read_b128 v[204:207], v212 offset:1024
	ds_read_b128 v[208:211], v212 offset:2048
	ds_read_b128 v[212:215], v212 offset:3072
	global_load_lds_dwordx4 v132, s[98:99]
	s_add_i32 m0, s48, 0x2000
	s_nop 0
	global_load_lds_dwordx4 v128, s[98:99]
	s_barrier
	s_waitcnt lgkmcnt(0)
	s_setprio 1
	s_waitcnt lgkmcnt(0)
	v_mfma_f32_16x16x32_bf16 v[116:119], v[200:203], v[168:171], v[116:119]
	v_mfma_f32_16x16x32_bf16 v[108:111], v[208:211], v[168:171], v[108:111]
	v_mfma_f32_16x16x32_bf16 v[100:103], v[200:203], v[176:179], v[100:103]
	v_mfma_f32_16x16x32_bf16 v[92:95], v[208:211], v[176:179], v[92:95]
	v_mfma_f32_16x16x32_bf16 v[84:87], v[200:203], v[184:187], v[84:87]
	v_mfma_f32_16x16x32_bf16 v[76:79], v[208:211], v[184:187], v[76:79]
	v_mfma_f32_16x16x32_bf16 v[68:71], v[200:203], v[192:195], v[68:71]
	v_mfma_f32_16x16x32_bf16 v[64:67], v[208:211], v[192:195], v[64:67]
	v_mfma_f32_16x16x32_bf16 v[116:119], v[204:207], v[172:175], v[116:119]
	v_mfma_f32_16x16x32_bf16 v[108:111], v[212:215], v[172:175], v[108:111]
	v_mfma_f32_16x16x32_bf16 v[100:103], v[204:207], v[180:183], v[100:103]
	v_mfma_f32_16x16x32_bf16 v[92:95], v[212:215], v[180:183], v[92:95]
	v_mfma_f32_16x16x32_bf16 v[84:87], v[204:207], v[188:191], v[84:87]
	v_mfma_f32_16x16x32_bf16 v[76:79], v[212:215], v[188:191], v[76:79]
	v_mfma_f32_16x16x32_bf16 v[68:71], v[204:207], v[196:199], v[68:71]
	v_mfma_f32_16x16x32_bf16 v[64:67], v[212:215], v[196:199], v[64:67]
	s_setprio 0
	s_mov_b32 m0, s34
	s_barrier
	ds_read_b128 v[168:171], v146 offset:49152
	ds_read_b128 v[172:175], v146 offset:50176
	ds_read_b128 v[176:179], v146 offset:51200
	ds_read_b128 v[180:183], v146 offset:52224
	ds_read_b128 v[184:187], v146 offset:53248
	ds_read_b128 v[188:191], v146 offset:54272
	ds_read_b128 v[192:195], v146 offset:55296
	ds_read_b128 v[196:199], v146 offset:56320
	global_load_lds_dwordx4 v134, s[100:101]
	s_mov_b32 m0, s36
	s_nop 0
	global_load_lds_dwordx4 v130, s[100:101]
	s_barrier
; #define PG8_STAGE(bufoff, gbase, voff) do { _Pragma("unroll") for (int _i = 0; _i < 2; ++_i) \
;         __builtin_amdgcn_global_load_lds((const unsigned*)((const char*)(gbase) + (voff)[_i]), (LAS unsigned*)(lds + (bufoff) + ldsw + _i * 8192), 16, 0, 0); } while (0)
; #define PG8_LDA(dst, b, h) do { _Pragma("unroll") for (int m = 0; m < 4; ++m) _Pragma("unroll") for (int k = 0; k < 2; ++k) dst[m][k] = *(const LAS bf16x8*)(lds + PG8_SA(b, h) + aoff + m * 2048 + k * 1024); } while (0)
; #define PG8_MMA(ai, bj, At, Bt) do { __builtin_amdgcn_s_setprio(1); _Pragma("unroll") for (int m = 0; m < 4; ++m) _Pragma("unroll") for (int n = 0; n < 2; ++n) _Pragma("unroll") for (int k = 0; k < 2; ++k) \
;         acc[ai][bj][m][n] = __builtin_amdgcn_mfma_f32_16x16x32_bf16(Bt[n][k], At[m][k], acc[ai][bj][m][n], 0, 0, 0); __builtin_amdgcn_s_setprio(0); } while (0)
; #define PG8_WAIT_V(n) asm volatile("s_waitcnt vmcnt(" #n ")" ::: "memory")
; #define PG8_WAIT_L(n) asm volatile("s_waitcnt lgkmcnt(" #n ")" ::: "memory")
; #define PG8_BAR __builtin_amdgcn_s_barrier()
; #define PG8_SCHED __builtin_amdgcn_sched_barrier(0)
; template <class Epi>
; __device__ __forceinline__ void gemm_phase(LAS unsigned char* lds, const Gemm g, const StaticOrder& S, const Epi& E) {
;     ...
;             PG8_BAR; PG8_WAIT_L(0); PG8_MMA(0, 1, At, B1); PG8_BAR;
;             PG8_LDA(At, 1, 1); PG8_STAGE(PG8_SA(1, 0), a3, voffA);
;             PG8_BAR; PG8_WAIT_L(0); PG8_MMA(1, 0, At, B0); PG8_BAR; PG8_SCHED;
;             PG8_STAGE(PG8_SB(1, 1), b3 + hstep, voffB);
;             PG8_WAIT_V(6); PG8_BAR; PG8_MMA(1, 1, At, B1); PG8_BAR;
	s_waitcnt lgkmcnt(0)
	s_setprio 1
	s_waitcnt lgkmcnt(0)
	v_mfma_f32_16x16x32_bf16 v[60:63], v[148:151], v[168:171], v[60:63]
	v_mfma_f32_16x16x32_bf16 v[56:59], v[160:163], v[168:171], v[56:59]
	v_mfma_f32_16x16x32_bf16 v[52:55], v[148:151], v[176:179], v[52:55]
	v_mfma_f32_16x16x32_bf16 v[44:47], v[160:163], v[176:179], v[44:47]
	v_mfma_f32_16x16x32_bf16 v[36:39], v[148:151], v[184:187], v[36:39]
	v_mfma_f32_16x16x32_bf16 v[28:31], v[160:163], v[184:187], v[28:31]
	v_mfma_f32_16x16x32_bf16 v[20:23], v[148:151], v[192:195], v[20:23]
	v_mfma_f32_16x16x32_bf16 v[12:15], v[160:163], v[192:195], v[12:15]
	v_mfma_f32_16x16x32_bf16 v[60:63], v[152:155], v[172:175], v[60:63]
	v_mfma_f32_16x16x32_bf16 v[56:59], v[164:167], v[172:175], v[56:59]
	v_mfma_f32_16x16x32_bf16 v[52:55], v[152:155], v[180:183], v[52:55]
	v_mfma_f32_16x16x32_bf16 v[44:47], v[164:167], v[180:183], v[44:47]
	v_mfma_f32_16x16x32_bf16 v[36:39], v[152:155], v[188:191], v[36:39]
	v_mfma_f32_16x16x32_bf16 v[28:31], v[164:167], v[188:191], v[28:31]
	v_mfma_f32_16x16x32_bf16 v[20:23], v[152:155], v[196:199], v[20:23]
	v_mfma_f32_16x16x32_bf16 v[12:15], v[164:167], v[196:199], v[12:15]
	s_setprio 0
	s_barrier
	s_add_u32 s48, s52, 0x160080
	s_addc_u32 s49, s53, 0
	s_add_i32 s52, s54, s13
	s_mov_b32 m0, s52
	s_nop 0
	global_load_lds_dwordx4 v132, s[48:49]
	s_add_i32 m0, s52, 0x2000
	s_nop 0
	global_load_lds_dwordx4 v128, s[48:49]
	s_waitcnt vmcnt(6)
	s_barrier
	s_setprio 1
	v_mfma_f32_16x16x32_bf16 v[48:51], v[200:203], v[168:171], v[48:51]
	v_mfma_f32_16x16x32_bf16 v[40:43], v[208:211], v[168:171], v[40:43]
	v_mfma_f32_16x16x32_bf16 v[32:35], v[200:203], v[176:179], v[32:35]
	v_mfma_f32_16x16x32_bf16 v[24:27], v[208:211], v[176:179], v[24:27]
	v_mfma_f32_16x16x32_bf16 v[16:19], v[200:203], v[184:187], v[16:19]
	v_mfma_f32_16x16x32_bf16 v[8:11], v[208:211], v[184:187], v[8:11]
	v_mfma_f32_16x16x32_bf16 v[4:7], v[200:203], v[192:195], v[4:7]
	v_mfma_f32_16x16x32_bf16 v[0:3], v[208:211], v[192:195], v[0:3]
	v_mfma_f32_16x16x32_bf16 v[48:51], v[204:207], v[172:175], v[48:51]
	v_mfma_f32_16x16x32_bf16 v[40:43], v[212:215], v[172:175], v[40:43]
	v_mfma_f32_16x16x32_bf16 v[32:35], v[204:207], v[180:183], v[32:35]
	v_mfma_f32_16x16x32_bf16 v[24:27], v[212:215], v[180:183], v[24:27]
	v_mfma_f32_16x16x32_bf16 v[16:19], v[204:207], v[188:191], v[16:19]
	v_mfma_f32_16x16x32_bf16 v[8:11], v[212:215], v[188:191], v[8:11]
	v_mfma_f32_16x16x32_bf16 v[4:7], v[204:207], v[196:199], v[4:7]
	v_mfma_f32_16x16x32_bf16 v[0:3], v[212:215], v[196:199], v[0:3]
	s_setprio 0
	s_add_i32 s65, s65, 2
	s_add_u32 s63, s63, 0x100
	s_addc_u32 s64, s64, 0
	s_cmpk_gt_u32 s65, 0x55
	s_mov_b64 s[48:49], s[50:51]
	s_barrier
	s_cbranch_scc0 .LBB0_283
; #define PG8_WAIT_V(n) asm volatile("s_waitcnt vmcnt(" #n ")" ::: "memory")
; #define PG8_BAR __builtin_amdgcn_s_barrier()
; __device__ __forceinline__ u32x4 pack8(f32x4 v0, f32x4 v1) { u32x4 w; w.x = cvt_pk_bf16(v0[0], v0[1]); w.y = cvt_pk_bf16(v0[2], v0[3]); w.z = cvt_pk_bf16(v1[0], v1[1]); w.w = cvt_pk_bf16(v1[2], v1[3]); return w; }
; template <class Epi>
; __device__ __forceinline__ void gemm_phase(LAS unsigned char* lds, const Gemm g, const StaticOrder& S, const Epi& E) {
;     ...
;     PG8_WAIT_V(0);
;     if (wr == 0) PG8_BAR;
;     PG8_BAR;
;     __device__ __forceinline__ void operator()(const f32x4 (&acc)[2][2][4][2], const Unit& u, int wr, int wc, int fr, int fq) const {
;         const int row0 = u.pm * BM + wr * 64 + fr, col0 = u.pn * BM + wc * 32 + 8 * fq;
; #pragma unroll
;         for (int ai = 0; ai < 2; ++ai)
; #pragma unroll
;             for (int m = 0; m < 4; ++m) { bf16_t* rowp = O + (size_t)(row0 + ai * HALF + m * 16) * ldc + col0;
; #pragma unroll
;                 for (int bj = 0; bj < 2; ++bj) *(u32x4*)(rowp + bj * HALF) = pack8(acc[ai][bj][m][0], acc[ai][bj][m][1]); }
;     }
	v_lshl_add_u32 v148, s61, 8, v142
	v_lshl_or_b32 v140, s62, 8, v144
	v_ashrrev_i32_e32 v149, 31, v148
	v_ashrrev_i32_e32 v141, 31, v140
	v_lshlrev_b64 v[150:151], 12, v[148:149]
	v_lshl_add_u64 v[150:151], s[24:25], 0, v[150:151]
	v_lshlrev_b64 v[152:153], 1, v[140:141]
	v_lshl_add_u64 v[140:141], v[150:151], 0, v[152:153]
	v_cvt_pk_bf16_f32 v124, v124, v125
	v_cvt_pk_bf16_f32 v125, v126, v127
	v_cvt_pk_bf16_f32 v126, v120, v121
	v_cvt_pk_bf16_f32 v127, v122, v123
	global_store_dwordx4 v[140:141], v[124:127], off
	v_cvt_pk_bf16_f32 v116, v116, v117
	v_cvt_pk_bf16_f32 v117, v118, v119
	v_cvt_pk_bf16_f32 v118, v108, v109
	v_or_b32_e32 v108, 16, v148
	v_ashrrev_i32_e32 v109, 31, v108
	v_lshlrev_b64 v[108:109], 12, v[108:109]
	v_lshl_add_u64 v[108:109], s[24:25], 0, v[108:109]
	v_cvt_pk_bf16_f32 v119, v110, v111
	global_store_dwordx4 v[140:141], v[116:119], off offset:256
	s_mov_b32 s62, s59
	s_mov_b32 s61, s60
	v_lshl_add_u64 v[116:117], v[108:109], 0, v[152:153]
	v_cvt_pk_bf16_f32 v108, v112, v113
	v_cvt_pk_bf16_f32 v109, v114, v115
	v_cvt_pk_bf16_f32 v110, v104, v105
	v_cvt_pk_bf16_f32 v111, v106, v107
	global_store_dwordx4 v[116:117], v[108:111], off
	v_cvt_pk_bf16_f32 v100, v100, v101
	v_cvt_pk_bf16_f32 v101, v102, v103
	v_cvt_pk_bf16_f32 v102, v92, v93
	v_or_b32_e32 v92, 32, v148
	v_ashrrev_i32_e32 v93, 31, v92
	v_lshlrev_b64 v[92:93], 12, v[92:93]
	v_lshl_add_u64 v[92:93], s[24:25], 0, v[92:93]
	v_cvt_pk_bf16_f32 v103, v94, v95
	global_store_dwordx4 v[116:117], v[100:103], off offset:256
	s_mov_b64 s[50:51], s[4:5]
	s_mov_b64 s[48:49], s[46:47]
	v_lshl_add_u64 v[100:101], v[92:93], 0, v[152:153]
	v_cvt_pk_bf16_f32 v92, v96, v97
	v_cvt_pk_bf16_f32 v93, v98, v99
	v_cvt_pk_bf16_f32 v94, v88, v89
	v_cvt_pk_bf16_f32 v95, v90, v91
	global_store_dwordx4 v[100:101], v[92:95], off
	v_cvt_pk_bf16_f32 v84, v84, v85
	v_cvt_pk_bf16_f32 v85, v86, v87
	v_cvt_pk_bf16_f32 v86, v76, v77
	v_or_b32_e32 v76, 48, v148
	v_ashrrev_i32_e32 v77, 31, v76
	v_lshlrev_b64 v[76:77], 12, v[76:77]
	v_lshl_add_u64 v[76:77], s[24:25], 0, v[76:77]
	v_cvt_pk_bf16_f32 v87, v78, v79
	global_store_dwordx4 v[100:101], v[84:87], off offset:256
	s_nop 1
	v_lshl_add_u64 v[84:85], v[76:77], 0, v[152:153]
	v_cvt_pk_bf16_f32 v76, v80, v81
	v_cvt_pk_bf16_f32 v77, v82, v83
	v_cvt_pk_bf16_f32 v78, v72, v73
	v_cvt_pk_bf16_f32 v79, v74, v75
	global_store_dwordx4 v[84:85], v[76:79], off
	v_cvt_pk_bf16_f32 v68, v68, v69
	v_cvt_pk_bf16_f32 v69, v70, v71
	v_cvt_pk_bf16_f32 v70, v64, v65
	v_cvt_pk_bf16_f32 v71, v66, v67
	global_store_dwordx4 v[84:85], v[68:71], off offset:256
	v_cvt_pk_bf16_f32 v60, v60, v61
	v_cvt_pk_bf16_f32 v61, v62, v63
	v_cvt_pk_bf16_f32 v62, v56, v57
	v_add_co_u32_e32 v56, vcc, s41, v140
	v_lshl_add_u64 v[64:65], v[140:141], 0, s[8:9]
	s_nop 0
	v_addc_co_u32_e32 v57, vcc, 0, v141, vcc
	v_cvt_pk_bf16_f32 v63, v58, v59
	global_store_dwordx4 v[56:57], v[60:63], off
	v_cvt_pk_bf16_f32 v48, v48, v49
	v_cvt_pk_bf16_f32 v49, v50, v51
	v_cvt_pk_bf16_f32 v50, v40, v41
	v_cvt_pk_bf16_f32 v51, v42, v43
	global_store_dwordx4 v[64:65], v[48:51], off offset:256
	v_cvt_pk_bf16_f32 v40, v52, v53
	v_cvt_pk_bf16_f32 v41, v54, v55
	v_cvt_pk_bf16_f32 v42, v44, v45
	v_add_co_u32_e32 v44, vcc, s56, v140
	s_nop 0
	v_lshl_add_u64 v[48:49], v[140:141], 0, s[26:27]
	v_addc_co_u32_e32 v45, vcc, 0, v141, vcc
	v_cvt_pk_bf16_f32 v43, v46, v47
	global_store_dwordx4 v[44:45], v[40:43], off
	v_cvt_pk_bf16_f32 v32, v32, v33
	v_cvt_pk_bf16_f32 v33, v34, v35
	v_cvt_pk_bf16_f32 v34, v24, v25
	v_cvt_pk_bf16_f32 v35, v26, v27
	global_store_dwordx4 v[48:49], v[32:35], off offset:256
	v_cvt_pk_bf16_f32 v24, v36, v37
	v_cvt_pk_bf16_f32 v25, v38, v39
	v_cvt_pk_bf16_f32 v26, v28, v29
	v_add_co_u32_e32 v28, vcc, s57, v140
	s_nop 0
	v_lshl_add_u64 v[32:33], v[140:141], 0, s[28:29]
	v_addc_co_u32_e32 v29, vcc, 0, v141, vcc
	v_cvt_pk_bf16_f32 v27, v30, v31
	global_store_dwordx4 v[28:29], v[24:27], off
	v_cvt_pk_bf16_f32 v16, v16, v17
	v_cvt_pk_bf16_f32 v17, v18, v19
	v_cvt_pk_bf16_f32 v18, v8, v9
	v_cvt_pk_bf16_f32 v19, v10, v11
	global_store_dwordx4 v[32:33], v[16:19], off offset:256
	v_cvt_pk_bf16_f32 v8, v20, v21
	v_cvt_pk_bf16_f32 v9, v22, v23
	v_cvt_pk_bf16_f32 v10, v12, v13
	v_add_co_u32_e32 v12, vcc, s58, v140
	s_nop 0
	v_lshl_add_u64 v[16:17], v[140:141], 0, s[42:43]
	v_addc_co_u32_e32 v13, vcc, 0, v141, vcc
	s_and_b64 vcc, exec, s[44:45]
	v_cvt_pk_bf16_f32 v11, v14, v15
	global_store_dwordx4 v[12:13], v[8:11], off
	v_cvt_pk_bf16_f32 v4, v4, v5
	v_cvt_pk_bf16_f32 v5, v6, v7
	v_cvt_pk_bf16_f32 v6, v0, v1
	v_cvt_pk_bf16_f32 v7, v2, v3
	global_store_dwordx4 v[16:17], v[4:7], off offset:256
	s_cbranch_vccz .LBB0_276
	s_waitcnt vmcnt(0)
	s_cmpk_gt_u32 s3, 0xff
	v_readlane_b32 s62, v232, 20
	s_cbranch_scc1 .LBB0_287
	s_barrier

; #define PG8_STAGE(bufoff, gbase, voff) do { _Pragma("unroll") for (int _i = 0; _i < 2; ++_i) \
;         __builtin_amdgcn_global_load_lds((const unsigned*)((const char*)(gbase) + (voff)[_i]), (LAS unsigned*)(lds + (bufoff) + ldsw + _i * 8192), 16, 0, 0); } while (0)
; #define PG8_LDA(dst, b, h) do { _Pragma("unroll") for (int m = 0; m < 4; ++m) _Pragma("unroll") for (int k = 0; k < 2; ++k) dst[m][k] = *(const LAS bf16x8*)(lds + PG8_SA(b, h) + aoff + m * 2048 + k * 1024); } while (0)
; #define PG8_LDB(dst, b, h) do { _Pragma("unroll") for (int n = 0; n < 2; ++n) _Pragma("unroll") for (int k = 0; k < 2; ++k) dst[n][k] = *(const LAS bf16x8*)(lds + PG8_SB(b, h) + boff + n * 2048 + k * 1024); } while (0)
; #define PG8_MMA(ai, bj, At, Bt) do { __builtin_amdgcn_s_setprio(1); _Pragma("unroll") for (int m = 0; m < 4; ++m) _Pragma("unroll") for (int n = 0; n < 2; ++n) _Pragma("unroll") for (int k = 0; k < 2; ++k) \
;         acc[ai][bj][m][n] = __builtin_amdgcn_mfma_f32_16x16x32_bf16(Bt[n][k], At[m][k], acc[ai][bj][m][n], 0, 0, 0); __builtin_amdgcn_s_setprio(0); } while (0)
; #define PG8_WAIT_V(n) asm volatile("s_waitcnt vmcnt(" #n ")" ::: "memory")
; #define PG8_WAIT_L(n) asm volatile("s_waitcnt lgkmcnt(" #n ")" ::: "memory")
; #define PG8_BAR __builtin_amdgcn_s_barrier()
; #define PG8_SCHED __builtin_amdgcn_sched_barrier(0)
; template <class Epi>
; __device__ __forceinline__ void gemm_phase(LAS unsigned char* lds, const Gemm g, const StaticOrder& S, const Epi& E) {
;     ...
;             PG8_LDB(B0, 0, 0); PG8_SCHED; PG8_LDA(At, 0, 0); PG8_STAGE(PG8_SA(1, 1), a1 + hstep, voffA);
;             PG8_WAIT_L(8); PG8_BAR; PG8_WAIT_L(0); PG8_MMA(0, 0, At, B0); PG8_BAR; PG8_SCHED;
;             PG8_LDB(B1, 0, 1); PG8_STAGE(PG8_SB(0, 0), b2, voffB);
;             PG8_BAR; PG8_WAIT_L(0); PG8_MMA(0, 1, At, B1); PG8_BAR;
;             PG8_LDA(At, 0, 1); PG8_STAGE(PG8_SA(0, 0), a2, voffA);
;             PG8_BAR; PG8_WAIT_L(0); PG8_MMA(1, 0, At, B0); PG8_BAR; PG8_SCHED;
;             PG8_STAGE(PG8_SB(0, 1), b2 + hstep, voffB);
;             PG8_WAIT_V(6); PG8_BAR; PG8_MMA(1, 1, At, B1); PG8_BAR;
.LBB0_407:
	ds_read_b128 v[150:153], v164
	ds_read_b128 v[154:157], v164 offset:1024
	ds_read_b128 v[168:171], v164 offset:2048
	ds_read_b128 v[172:175], v164 offset:3072
	s_add_u32 s48, s46, 0xfff80080
	s_addc_u32 s49, s47, -1
	s_cmp_eq_u32 s57, 28
	s_cselect_b32 s51, s9, s49
	s_cselect_b32 s50, s45, s48
	s_cselect_b32 s49, s7, s56
	s_cselect_b32 s48, s54, s55
	s_add_i32 m0, s27, 0xc000
	ds_read_b128 v[176:179], v165
	ds_read_b128 v[180:183], v165 offset:1024
	ds_read_b128 v[184:187], v165 offset:2048
	ds_read_b128 v[188:191], v165 offset:3072
	ds_read_b128 v[192:195], v165 offset:4096
	ds_read_b128 v[196:199], v165 offset:5120
	ds_read_b128 v[200:203], v165 offset:6144
	ds_read_b128 v[204:207], v165 offset:7168
	global_load_lds_dwordx4 v142, s[46:47]
	s_add_i32 m0, s27, 0xe000
	s_nop 0
	global_load_lds_dwordx4 v144, s[46:47]
	s_waitcnt lgkmcnt(8)
	s_barrier
	s_waitcnt lgkmcnt(0)
	s_setprio 1
	s_waitcnt lgkmcnt(0)
	v_mfma_f32_16x16x32_bf16 v[124:127], v[150:153], v[176:179], v[124:127]
	v_mfma_f32_16x16x32_bf16 v[120:123], v[168:171], v[176:179], v[120:123]
	v_mfma_f32_16x16x32_bf16 v[108:111], v[150:153], v[184:187], v[108:111]
	v_mfma_f32_16x16x32_bf16 v[104:107], v[168:171], v[184:187], v[104:107]
	v_mfma_f32_16x16x32_bf16 v[92:95], v[150:153], v[192:195], v[92:95]
	v_mfma_f32_16x16x32_bf16 v[88:91], v[168:171], v[192:195], v[88:91]
	v_mfma_f32_16x16x32_bf16 v[76:79], v[150:153], v[200:203], v[76:79]
	v_mfma_f32_16x16x32_bf16 v[72:75], v[168:171], v[200:203], v[72:75]
	v_mfma_f32_16x16x32_bf16 v[124:127], v[154:157], v[180:183], v[124:127]
	v_mfma_f32_16x16x32_bf16 v[120:123], v[172:175], v[180:183], v[120:123]
	v_mfma_f32_16x16x32_bf16 v[108:111], v[154:157], v[188:191], v[108:111]
	v_mfma_f32_16x16x32_bf16 v[104:107], v[172:175], v[188:191], v[104:107]
	v_mfma_f32_16x16x32_bf16 v[92:95], v[154:157], v[196:199], v[92:95]
	v_mfma_f32_16x16x32_bf16 v[88:91], v[172:175], v[196:199], v[88:91]
	v_mfma_f32_16x16x32_bf16 v[76:79], v[154:157], v[204:207], v[76:79]
	v_mfma_f32_16x16x32_bf16 v[72:75], v[172:175], v[204:207], v[72:75]
	s_setprio 0
	s_barrier
	s_add_i32 s58, s41, s23
	s_add_u32 s98, s48, s2
	s_addc_u32 s99, s49, s3
	s_mov_b32 m0, s58
	ds_read_b128 v[208:211], v166
	ds_read_b128 v[212:215], v166 offset:1024
	ds_read_b128 v[216:219], v166 offset:2048
	ds_read_b128 v[220:223], v166 offset:3072
	global_load_lds_dwordx4 v132, s[48:49]
	s_add_i32 m0, s58, 0x2000
	s_nop 0
	global_load_lds_dwordx4 v128, s[48:49]
	s_barrier
	s_waitcnt lgkmcnt(0)
	s_setprio 1
	s_waitcnt lgkmcnt(0)
	v_mfma_f32_16x16x32_bf16 v[116:119], v[208:211], v[176:179], v[116:119]
	v_mfma_f32_16x16x32_bf16 v[112:115], v[216:219], v[176:179], v[112:115]
	v_mfma_f32_16x16x32_bf16 v[100:103], v[208:211], v[184:187], v[100:103]
	v_mfma_f32_16x16x32_bf16 v[96:99], v[216:219], v[184:187], v[96:99]
	v_mfma_f32_16x16x32_bf16 v[84:87], v[208:211], v[192:195], v[84:87]
	v_mfma_f32_16x16x32_bf16 v[80:83], v[216:219], v[192:195], v[80:83]
	v_mfma_f32_16x16x32_bf16 v[68:71], v[208:211], v[200:203], v[68:71]
	v_mfma_f32_16x16x32_bf16 v[64:67], v[216:219], v[200:203], v[64:67]
	v_mfma_f32_16x16x32_bf16 v[116:119], v[212:215], v[180:183], v[116:119]
	v_mfma_f32_16x16x32_bf16 v[112:115], v[220:223], v[180:183], v[112:115]
	v_mfma_f32_16x16x32_bf16 v[100:103], v[212:215], v[188:191], v[100:103]
	v_mfma_f32_16x16x32_bf16 v[96:99], v[220:223], v[188:191], v[96:99]
	v_mfma_f32_16x16x32_bf16 v[84:87], v[212:215], v[196:199], v[84:87]
	v_mfma_f32_16x16x32_bf16 v[80:83], v[220:223], v[196:199], v[80:83]
	v_mfma_f32_16x16x32_bf16 v[68:71], v[212:215], v[204:207], v[68:71]
	v_mfma_f32_16x16x32_bf16 v[64:67], v[220:223], v[204:207], v[64:67]
	s_setprio 0
	s_mov_b32 m0, s27
	s_add_u32 s100, s50, s2
	s_addc_u32 s101, s51, s3
	s_barrier
	ds_read_b128 v[176:179], v165 offset:16384
	ds_read_b128 v[180:183], v165 offset:17408
	ds_read_b128 v[184:187], v165 offset:18432
	ds_read_b128 v[188:191], v165 offset:19456
	ds_read_b128 v[192:195], v165 offset:20480
	ds_read_b128 v[196:199], v165 offset:21504
	ds_read_b128 v[200:203], v165 offset:22528
	ds_read_b128 v[204:207], v165 offset:23552
	global_load_lds_dwordx4 v134, s[50:51]
	s_mov_b32 m0, s30
	s_nop 0
	global_load_lds_dwordx4 v130, s[50:51]
	s_barrier
	s_waitcnt lgkmcnt(0)
	s_setprio 1
	s_waitcnt lgkmcnt(0)
	v_mfma_f32_16x16x32_bf16 v[60:63], v[150:153], v[176:179], v[60:63]
	v_mfma_f32_16x16x32_bf16 v[56:59], v[168:171], v[176:179], v[56:59]
	v_mfma_f32_16x16x32_bf16 v[44:47], v[150:153], v[184:187], v[44:47]
	v_mfma_f32_16x16x32_bf16 v[40:43], v[168:171], v[184:187], v[40:43]
	v_mfma_f32_16x16x32_bf16 v[28:31], v[150:153], v[192:195], v[28:31]
	v_mfma_f32_16x16x32_bf16 v[24:27], v[168:171], v[192:195], v[24:27]
	v_mfma_f32_16x16x32_bf16 v[12:15], v[150:153], v[200:203], v[12:15]
	v_mfma_f32_16x16x32_bf16 v[8:11], v[168:171], v[200:203], v[8:11]
	v_mfma_f32_16x16x32_bf16 v[60:63], v[154:157], v[180:183], v[60:63]
	v_mfma_f32_16x16x32_bf16 v[56:59], v[172:175], v[180:183], v[56:59]
	v_mfma_f32_16x16x32_bf16 v[44:47], v[154:157], v[188:191], v[44:47]
	v_mfma_f32_16x16x32_bf16 v[40:43], v[172:175], v[188:191], v[40:43]
	v_mfma_f32_16x16x32_bf16 v[28:31], v[154:157], v[196:199], v[28:31]
	v_mfma_f32_16x16x32_bf16 v[24:27], v[172:175], v[196:199], v[24:27]
	v_mfma_f32_16x16x32_bf16 v[12:15], v[154:157], v[204:207], v[12:15]
	v_mfma_f32_16x16x32_bf16 v[8:11], v[172:175], v[204:207], v[8:11]
	s_setprio 0
	s_barrier
	s_add_u32 s58, s48, 0x80000
	s_addc_u32 s59, s49, 0
	s_add_i32 s60, s52, s23
	s_mov_b32 m0, s60
	s_nop 0
	global_load_lds_dwordx4 v132, s[58:59]
	s_add_i32 m0, s60, 0x2000
	s_nop 0
	global_load_lds_dwordx4 v128, s[58:59]
	s_waitcnt vmcnt(6)
	s_barrier
; #define PG8_STAGE(bufoff, gbase, voff) do { _Pragma("unroll") for (int _i = 0; _i < 2; ++_i) \
;         __builtin_amdgcn_global_load_lds((const unsigned*)((const char*)(gbase) + (voff)[_i]), (LAS unsigned*)(lds + (bufoff) + ldsw + _i * 8192), 16, 0, 0); } while (0)
; #define PG8_LDA(dst, b, h) do { _Pragma("unroll") for (int m = 0; m < 4; ++m) _Pragma("unroll") for (int k = 0; k < 2; ++k) dst[m][k] = *(const LAS bf16x8*)(lds + PG8_SA(b, h) + aoff + m * 2048 + k * 1024); } while (0)
; #define PG8_LDB(dst, b, h) do { _Pragma("unroll") for (int n = 0; n < 2; ++n) _Pragma("unroll") for (int k = 0; k < 2; ++k) dst[n][k] = *(const LAS bf16x8*)(lds + PG8_SB(b, h) + boff + n * 2048 + k * 1024); } while (0)
; #define PG8_MMA(ai, bj, At, Bt) do { __builtin_amdgcn_s_setprio(1); _Pragma("unroll") for (int m = 0; m < 4; ++m) _Pragma("unroll") for (int n = 0; n < 2; ++n) _Pragma("unroll") for (int k = 0; k < 2; ++k) \
;         acc[ai][bj][m][n] = __builtin_amdgcn_mfma_f32_16x16x32_bf16(Bt[n][k], At[m][k], acc[ai][bj][m][n], 0, 0, 0); __builtin_amdgcn_s_setprio(0); } while (0)
; #define PG8_WAIT_V(n) asm volatile("s_waitcnt vmcnt(" #n ")" ::: "memory")
; #define PG8_WAIT_L(n) asm volatile("s_waitcnt lgkmcnt(" #n ")" ::: "memory")
; #define PG8_BAR __builtin_amdgcn_s_barrier()
; #define PG8_SCHED __builtin_amdgcn_sched_barrier(0)
; template <class Epi>
; __device__ __forceinline__ void gemm_phase(LAS unsigned char* lds, const Gemm g, const StaticOrder& S, const Epi& E) {
;     ...
;             PG8_WAIT_V(6); PG8_BAR; PG8_MMA(1, 1, At, B1); PG8_BAR;
;             PG8_LDB(B0, 1, 0); PG8_SCHED; PG8_LDA(At, 1, 0); PG8_STAGE(PG8_SA(0, 1), a2 + hstep, voffA);
;             PG8_WAIT_L(8); PG8_BAR; PG8_WAIT_L(0); PG8_MMA(0, 0, At, B0); PG8_BAR; PG8_SCHED;
;             PG8_LDB(B1, 1, 1); PG8_STAGE(PG8_SB(1, 0), b3, voffB);
;             PG8_BAR; PG8_WAIT_L(0); PG8_MMA(0, 1, At, B1); PG8_BAR;
;             PG8_LDA(At, 1, 1); PG8_STAGE(PG8_SA(1, 0), a3, voffA);
;             PG8_BAR; PG8_WAIT_L(0); PG8_MMA(1, 0, At, B0); PG8_BAR; PG8_SCHED;
;             PG8_STAGE(PG8_SB(1, 1), b3 + hstep, voffB);
	s_setprio 1
	v_mfma_f32_16x16x32_bf16 v[52:55], v[208:211], v[176:179], v[52:55]
	v_mfma_f32_16x16x32_bf16 v[48:51], v[216:219], v[176:179], v[48:51]
	v_mfma_f32_16x16x32_bf16 v[36:39], v[208:211], v[184:187], v[36:39]
	v_mfma_f32_16x16x32_bf16 v[32:35], v[216:219], v[184:187], v[32:35]
	v_mfma_f32_16x16x32_bf16 v[20:23], v[208:211], v[192:195], v[20:23]
	v_mfma_f32_16x16x32_bf16 v[16:19], v[216:219], v[192:195], v[16:19]
	v_mfma_f32_16x16x32_bf16 v[4:7], v[208:211], v[200:203], v[4:7]
	v_mfma_f32_16x16x32_bf16 v[0:3], v[216:219], v[200:203], v[0:3]
	v_mfma_f32_16x16x32_bf16 v[52:55], v[212:215], v[180:183], v[52:55]
	v_mfma_f32_16x16x32_bf16 v[48:51], v[220:223], v[180:183], v[48:51]
	v_mfma_f32_16x16x32_bf16 v[36:39], v[212:215], v[188:191], v[36:39]
	v_mfma_f32_16x16x32_bf16 v[32:35], v[220:223], v[188:191], v[32:35]
	v_mfma_f32_16x16x32_bf16 v[20:23], v[212:215], v[196:199], v[20:23]
	v_mfma_f32_16x16x32_bf16 v[16:19], v[220:223], v[196:199], v[16:19]
	v_mfma_f32_16x16x32_bf16 v[4:7], v[212:215], v[204:207], v[4:7]
	v_mfma_f32_16x16x32_bf16 v[0:3], v[220:223], v[204:207], v[0:3]
	s_setprio 0
	s_add_i32 s58, 0, 0x18000
	v_add_u32_e32 v136, s58, v161
	s_barrier
	ds_read_b128 v[150:153], v136
	ds_read_b128 v[154:157], v136 offset:1024
	ds_read_b128 v[168:171], v136 offset:2048
	ds_read_b128 v[172:175], v136 offset:3072
	s_add_u32 s50, s50, 0x80000
	s_addc_u32 s51, s51, 0
	s_mov_b32 m0, s31
	ds_read_b128 v[176:179], v165 offset:32768
	ds_read_b128 v[180:183], v165 offset:33792
	ds_read_b128 v[184:187], v165 offset:34816
	ds_read_b128 v[188:191], v165 offset:35840
	ds_read_b128 v[192:195], v165 offset:36864
	ds_read_b128 v[196:199], v165 offset:37888
	ds_read_b128 v[200:203], v165 offset:38912
	ds_read_b128 v[204:207], v165 offset:39936
	global_load_lds_dwordx4 v134, s[50:51]
	s_mov_b32 m0, s33
	s_nop 0
	global_load_lds_dwordx4 v130, s[50:51]
	s_waitcnt lgkmcnt(8)
	s_barrier
	s_waitcnt lgkmcnt(0)
	s_setprio 1
	s_waitcnt lgkmcnt(0)
	v_mfma_f32_16x16x32_bf16 v[124:127], v[150:153], v[176:179], v[124:127]
	v_mfma_f32_16x16x32_bf16 v[120:123], v[168:171], v[176:179], v[120:123]
	v_mfma_f32_16x16x32_bf16 v[108:111], v[150:153], v[184:187], v[108:111]
	v_mfma_f32_16x16x32_bf16 v[104:107], v[168:171], v[184:187], v[104:107]
	v_mfma_f32_16x16x32_bf16 v[92:95], v[150:153], v[192:195], v[92:95]
	v_mfma_f32_16x16x32_bf16 v[88:91], v[168:171], v[192:195], v[88:91]
	v_mfma_f32_16x16x32_bf16 v[76:79], v[150:153], v[200:203], v[76:79]
	v_mfma_f32_16x16x32_bf16 v[72:75], v[168:171], v[200:203], v[72:75]
	v_mfma_f32_16x16x32_bf16 v[124:127], v[154:157], v[180:183], v[124:127]
	v_mfma_f32_16x16x32_bf16 v[120:123], v[172:175], v[180:183], v[120:123]
	v_mfma_f32_16x16x32_bf16 v[108:111], v[154:157], v[188:191], v[108:111]
	v_mfma_f32_16x16x32_bf16 v[104:107], v[172:175], v[188:191], v[104:107]
	v_mfma_f32_16x16x32_bf16 v[92:95], v[154:157], v[196:199], v[92:95]
	v_mfma_f32_16x16x32_bf16 v[88:91], v[172:175], v[196:199], v[88:91]
	v_mfma_f32_16x16x32_bf16 v[76:79], v[154:157], v[204:207], v[76:79]
	v_mfma_f32_16x16x32_bf16 v[72:75], v[172:175], v[204:207], v[72:75]
	s_setprio 0
	s_barrier
	s_add_i32 s50, 0, 0x1c000
	s_add_i32 s51, s58, s23
	v_add_u32_e32 v136, s50, v161
	s_mov_b32 m0, s51
	ds_read_b128 v[208:211], v136
	ds_read_b128 v[212:215], v136 offset:1024
	ds_read_b128 v[216:219], v136 offset:2048
	ds_read_b128 v[220:223], v136 offset:3072
	global_load_lds_dwordx4 v132, s[98:99]
	s_add_i32 m0, s51, 0x2000
	s_nop 0
	global_load_lds_dwordx4 v128, s[98:99]
	s_barrier
	s_waitcnt lgkmcnt(0)
	s_setprio 1
	s_waitcnt lgkmcnt(0)
	v_mfma_f32_16x16x32_bf16 v[116:119], v[208:211], v[176:179], v[116:119]
	v_mfma_f32_16x16x32_bf16 v[112:115], v[216:219], v[176:179], v[112:115]
	v_mfma_f32_16x16x32_bf16 v[100:103], v[208:211], v[184:187], v[100:103]
	v_mfma_f32_16x16x32_bf16 v[96:99], v[216:219], v[184:187], v[96:99]
	v_mfma_f32_16x16x32_bf16 v[84:87], v[208:211], v[192:195], v[84:87]
	v_mfma_f32_16x16x32_bf16 v[80:83], v[216:219], v[192:195], v[80:83]
	v_mfma_f32_16x16x32_bf16 v[68:71], v[208:211], v[200:203], v[68:71]
	v_mfma_f32_16x16x32_bf16 v[64:67], v[216:219], v[200:203], v[64:67]
	v_mfma_f32_16x16x32_bf16 v[116:119], v[212:215], v[180:183], v[116:119]
	v_mfma_f32_16x16x32_bf16 v[112:115], v[220:223], v[180:183], v[112:115]
	v_mfma_f32_16x16x32_bf16 v[100:103], v[212:215], v[188:191], v[100:103]
	v_mfma_f32_16x16x32_bf16 v[96:99], v[220:223], v[188:191], v[96:99]
	v_mfma_f32_16x16x32_bf16 v[84:87], v[212:215], v[196:199], v[84:87]
	v_mfma_f32_16x16x32_bf16 v[80:83], v[220:223], v[196:199], v[80:83]
	v_mfma_f32_16x16x32_bf16 v[68:71], v[212:215], v[204:207], v[68:71]
	v_mfma_f32_16x16x32_bf16 v[64:67], v[220:223], v[204:207], v[64:67]
	s_setprio 0
	s_mov_b32 m0, s37
	s_barrier
	ds_read_b128 v[176:179], v165 offset:49152
	ds_read_b128 v[180:183], v165 offset:50176
	ds_read_b128 v[184:187], v165 offset:51200
	ds_read_b128 v[188:191], v165 offset:52224
	ds_read_b128 v[192:195], v165 offset:53248
	ds_read_b128 v[196:199], v165 offset:54272
	ds_read_b128 v[200:203], v165 offset:55296
	ds_read_b128 v[204:207], v165 offset:56320
	global_load_lds_dwordx4 v134, s[100:101]
	s_mov_b32 m0, s38
	s_nop 0
	global_load_lds_dwordx4 v130, s[100:101]
	s_barrier
; #define PG8_STAGE(bufoff, gbase, voff) do { _Pragma("unroll") for (int _i = 0; _i < 2; ++_i) \
;         __builtin_amdgcn_global_load_lds((const unsigned*)((const char*)(gbase) + (voff)[_i]), (LAS unsigned*)(lds + (bufoff) + ldsw + _i * 8192), 16, 0, 0); } while (0)
; #define PG8_LDA(dst, b, h) do { _Pragma("unroll") for (int m = 0; m < 4; ++m) _Pragma("unroll") for (int k = 0; k < 2; ++k) dst[m][k] = *(const LAS bf16x8*)(lds + PG8_SA(b, h) + aoff + m * 2048 + k * 1024); } while (0)
; #define PG8_MMA(ai, bj, At, Bt) do { __builtin_amdgcn_s_setprio(1); _Pragma("unroll") for (int m = 0; m < 4; ++m) _Pragma("unroll") for (int n = 0; n < 2; ++n) _Pragma("unroll") for (int k = 0; k < 2; ++k) \
;         acc[ai][bj][m][n] = __builtin_amdgcn_mfma_f32_16x16x32_bf16(Bt[n][k], At[m][k], acc[ai][bj][m][n], 0, 0, 0); __builtin_amdgcn_s_setprio(0); } while (0)
; #define PG8_WAIT_V(n) asm volatile("s_waitcnt vmcnt(" #n ")" ::: "memory")
; #define PG8_WAIT_L(n) asm volatile("s_waitcnt lgkmcnt(" #n ")" ::: "memory")
; #define PG8_BAR __builtin_amdgcn_s_barrier()
; #define PG8_SCHED __builtin_amdgcn_sched_barrier(0)
; template <class Epi>
; __device__ __forceinline__ void gemm_phase(LAS unsigned char* lds, const Gemm g, const StaticOrder& S, const Epi& E) {
;     ...
;             PG8_BAR; PG8_WAIT_L(0); PG8_MMA(0, 1, At, B1); PG8_BAR;
;             PG8_LDA(At, 1, 1); PG8_STAGE(PG8_SA(1, 0), a3, voffA);
;             PG8_BAR; PG8_WAIT_L(0); PG8_MMA(1, 0, At, B0); PG8_BAR; PG8_SCHED;
;             PG8_STAGE(PG8_SB(1, 1), b3 + hstep, voffB);
;             PG8_WAIT_V(6); PG8_BAR; PG8_MMA(1, 1, At, B1); PG8_BAR;
;     __device__ __forceinline__ void operator()(const f32x4 (&acc)[2][2][4][2], const Unit& u, int wr, int wc, int fr, int fq) const {
;     ...
;             const int col0 = u.pn * BM + wc * 32 + 8 * fq; const float sc = (u.pn < 2) ? QSCALE : 1.0f;
; #pragma unroll
;             for (int ai = 0; ai < 2; ++ai)
; #pragma unroll
;                 for (int m = 0; m < 4; ++m) { bf16_t* rowp = O + (size_t)(row0 + ai * HALF + m * 16) * NQKV + col0; const float scr_ = sc * rowsc[row0 + ai * HALF + m * 16];
; #pragma unroll
;                     for (int bj = 0; bj < 2; ++bj) *(u32x4*)(rowp + bj * HALF) = pack8(acc[ai][bj][m][0] * scr_, acc[ai][bj][m][1] * scr_); }
	s_waitcnt lgkmcnt(0)
	s_setprio 1
	s_waitcnt lgkmcnt(0)
	v_mfma_f32_16x16x32_bf16 v[60:63], v[150:153], v[176:179], v[60:63]
	v_mfma_f32_16x16x32_bf16 v[56:59], v[168:171], v[176:179], v[56:59]
	v_mfma_f32_16x16x32_bf16 v[44:47], v[150:153], v[184:187], v[44:47]
	v_mfma_f32_16x16x32_bf16 v[40:43], v[168:171], v[184:187], v[40:43]
	v_mfma_f32_16x16x32_bf16 v[28:31], v[150:153], v[192:195], v[28:31]
	v_mfma_f32_16x16x32_bf16 v[24:27], v[168:171], v[192:195], v[24:27]
	v_mfma_f32_16x16x32_bf16 v[12:15], v[150:153], v[200:203], v[12:15]
	v_mfma_f32_16x16x32_bf16 v[8:11], v[168:171], v[200:203], v[8:11]
	v_mfma_f32_16x16x32_bf16 v[60:63], v[154:157], v[180:183], v[60:63]
	v_mfma_f32_16x16x32_bf16 v[56:59], v[172:175], v[180:183], v[56:59]
	v_mfma_f32_16x16x32_bf16 v[44:47], v[154:157], v[188:191], v[44:47]
	v_mfma_f32_16x16x32_bf16 v[40:43], v[172:175], v[188:191], v[40:43]
	v_mfma_f32_16x16x32_bf16 v[28:31], v[154:157], v[196:199], v[28:31]
	v_mfma_f32_16x16x32_bf16 v[24:27], v[172:175], v[196:199], v[24:27]
	v_mfma_f32_16x16x32_bf16 v[12:15], v[154:157], v[204:207], v[12:15]
	v_mfma_f32_16x16x32_bf16 v[8:11], v[172:175], v[204:207], v[8:11]
	s_setprio 0
	s_barrier
	s_add_u32 s48, s48, 0x80080
	s_addc_u32 s49, s49, 0
	s_add_i32 s50, s50, s23
	s_mov_b32 m0, s50
	s_nop 0
	global_load_lds_dwordx4 v132, s[48:49]
	s_add_i32 m0, s50, 0x2000
	s_nop 0
	global_load_lds_dwordx4 v128, s[48:49]
	s_waitcnt vmcnt(6)
	s_barrier
	s_setprio 1
	v_mfma_f32_16x16x32_bf16 v[52:55], v[208:211], v[176:179], v[52:55]
	v_mfma_f32_16x16x32_bf16 v[48:51], v[216:219], v[176:179], v[48:51]
	v_mfma_f32_16x16x32_bf16 v[36:39], v[208:211], v[184:187], v[36:39]
	v_mfma_f32_16x16x32_bf16 v[32:35], v[216:219], v[184:187], v[32:35]
	v_mfma_f32_16x16x32_bf16 v[20:23], v[208:211], v[192:195], v[20:23]
	v_mfma_f32_16x16x32_bf16 v[16:19], v[216:219], v[192:195], v[16:19]
	v_mfma_f32_16x16x32_bf16 v[4:7], v[208:211], v[200:203], v[4:7]
	v_mfma_f32_16x16x32_bf16 v[0:3], v[216:219], v[200:203], v[0:3]
	v_mfma_f32_16x16x32_bf16 v[52:55], v[212:215], v[180:183], v[52:55]
	v_mfma_f32_16x16x32_bf16 v[48:51], v[220:223], v[180:183], v[48:51]
	v_mfma_f32_16x16x32_bf16 v[36:39], v[212:215], v[188:191], v[36:39]
	v_mfma_f32_16x16x32_bf16 v[32:35], v[220:223], v[188:191], v[32:35]
	v_mfma_f32_16x16x32_bf16 v[20:23], v[212:215], v[196:199], v[20:23]
	v_mfma_f32_16x16x32_bf16 v[16:19], v[220:223], v[196:199], v[16:19]
	v_mfma_f32_16x16x32_bf16 v[4:7], v[212:215], v[204:207], v[4:7]
	v_mfma_f32_16x16x32_bf16 v[0:3], v[220:223], v[204:207], v[0:3]
	s_setprio 0
	s_add_i32 s57, s57, 2
	s_add_u32 s46, s46, 0x100
	s_addc_u32 s47, s47, 0
	s_add_u32 s55, s55, 0x100
	s_addc_u32 s56, s56, 0
	s_cmp_gt_u32 s57, 29
	s_barrier
	s_cbranch_scc0 .LBB0_407
	v_lshl_add_u32 v154, s44, 8, v160
	s_add_i32 s9, s34, -6
	s_lshl_b32 s7, s34, 8
	s_cmp_gt_u32 s9, 11
	s_mov_b64 s[44:45], -1
	v_ashrrev_i32_e32 v155, 31, v154
	v_or_b32_e32 v174, 16, v154
	v_or_b32_e32 v173, 32, v154
	v_or_b32_e32 v172, 48, v154
	v_add_u32_e32 v171, 0x80, v154
	v_add_u32_e32 v170, 0x90, v154
	v_add_u32_e32 v169, 0xa0, v154
	v_add_u32_e32 v168, 0xb0, v154
	s_cbranch_scc0 .LBB0_410
	v_lshl_add_u64 v[150:151], v[154:155], 2, s[14:15]
	global_load_dword v136, v[150:151], off
	global_load_dword v204, v[150:151], off offset:64
	global_load_dword v205, v[150:151], off offset:128
	global_load_dword v206, v[150:151], off offset:192
	global_load_dword v207, v[150:151], off offset:512
	global_load_dword v208, v[150:151], off offset:576
	global_load_dword v209, v[150:151], off offset:640
	global_load_dword v210, v[150:151], off offset:704
	s_cmp_lt_i32 s34, 2
	v_or_b32_e32 v156, s7, v162
	s_cselect_b64 vcc, -1, 0
	v_mov_b64_e32 v[152:153], s[20:21]
	v_cndmask_b32_e32 v175, 1.0, v167, vcc
	v_ashrrev_i32_e32 v157, 31, v156
	v_mad_i64_i32 v[176:177], s[44:45], v154, s53, v[152:153]
	v_lshlrev_b64 v[156:157], 1, v[156:157]
	v_lshl_add_u64 v[180:181], v[176:177], 0, v[156:157]
	s_waitcnt vmcnt(0)
	v_mul_f32_e32 v136, v175, v136
	v_pk_mul_f32 v[178:179], v[126:127], v[136:137] op_sel_hi:[1,0]
	v_pk_mul_f32 v[176:177], v[124:125], v[136:137] op_sel_hi:[1,0]
	v_pk_mul_f32 v[182:183], v[122:123], v[136:137] op_sel_hi:[1,0]
	v_pk_mul_f32 v[184:185], v[120:121], v[136:137] op_sel_hi:[1,0]
	v_cvt_pk_bf16_f32 v176, v176, v177
	v_cvt_pk_bf16_f32 v177, v178, v179
	v_pk_mul_f32 v[186:187], v[118:119], v[136:137] op_sel_hi:[1,0]
	v_cvt_pk_bf16_f32 v178, v184, v185
	v_cvt_pk_bf16_f32 v179, v182, v183
	v_pk_mul_f32 v[188:189], v[116:117], v[136:137] op_sel_hi:[1,0]
	v_pk_mul_f32 v[190:191], v[114:115], v[136:137] op_sel_hi:[1,0]
	v_pk_mul_f32 v[192:193], v[112:113], v[136:137] op_sel_hi:[1,0]
	global_store_dwordx4 v[180:181], v[176:179], off
	s_nop 1
	v_cvt_pk_bf16_f32 v176, v188, v189
	v_cvt_pk_bf16_f32 v177, v186, v187
	v_cvt_pk_bf16_f32 v178, v192, v193
	v_cvt_pk_bf16_f32 v179, v190, v191
	global_store_dwordx4 v[180:181], v[176:179], off offset:256
	s_nop 1
	v_mov_b32_e32 v136, v204
	v_mul_f32_e32 v136, v175, v136
	v_mad_i64_i32 v[176:177], s[44:45], v174, s53, v[152:153]
	v_lshl_add_u64 v[180:181], v[176:177], 0, v[156:157]
	v_pk_mul_f32 v[178:179], v[110:111], v[136:137] op_sel_hi:[1,0]
	v_pk_mul_f32 v[176:177], v[108:109], v[136:137] op_sel_hi:[1,0]
	v_pk_mul_f32 v[182:183], v[106:107], v[136:137] op_sel_hi:[1,0]
	v_pk_mul_f32 v[184:185], v[104:105], v[136:137] op_sel_hi:[1,0]
	v_cvt_pk_bf16_f32 v176, v176, v177
	v_cvt_pk_bf16_f32 v177, v178, v179
	v_pk_mul_f32 v[186:187], v[102:103], v[136:137] op_sel_hi:[1,0]
	v_cvt_pk_bf16_f32 v178, v184, v185
	v_cvt_pk_bf16_f32 v179, v182, v183
	v_pk_mul_f32 v[188:189], v[100:101], v[136:137] op_sel_hi:[1,0]
; __device__ __forceinline__ u32x4 pack8(f32x4 v0, f32x4 v1) { u32x4 w; w.x = cvt_pk_bf16(v0[0], v0[1]); w.y = cvt_pk_bf16(v0[2], v0[3]); w.z = cvt_pk_bf16(v1[0], v1[1]); w.w = cvt_pk_bf16(v1[2], v1[3]); return w; }
;     __device__ __forceinline__ void operator()(const f32x4 (&acc)[2][2][4][2], const Unit& u, int wr, int wc, int fr, int fq) const {
;     ...
;             for (int ai = 0; ai < 2; ++ai)
; #pragma unroll
;                 for (int m = 0; m < 4; ++m) { bf16_t* rowp = O + (size_t)(row0 + ai * HALF + m * 16) * NQKV + col0; const float scr_ = sc * rowsc[row0 + ai * HALF + m * 16];
; #pragma unroll
;                     for (int bj = 0; bj < 2; ++bj) *(u32x4*)(rowp + bj * HALF) = pack8(acc[ai][bj][m][0] * scr_, acc[ai][bj][m][1] * scr_); }
	v_pk_mul_f32 v[190:191], v[98:99], v[136:137] op_sel_hi:[1,0]
	v_pk_mul_f32 v[192:193], v[96:97], v[136:137] op_sel_hi:[1,0]
	global_store_dwordx4 v[180:181], v[176:179], off
	s_nop 1
	v_cvt_pk_bf16_f32 v176, v188, v189
	v_cvt_pk_bf16_f32 v177, v186, v187
	v_cvt_pk_bf16_f32 v178, v192, v193
	v_cvt_pk_bf16_f32 v179, v190, v191
	global_store_dwordx4 v[180:181], v[176:179], off offset:256
	s_nop 1
	v_mov_b32_e32 v136, v205
	v_mul_f32_e32 v136, v175, v136
	v_mad_i64_i32 v[176:177], s[44:45], v173, s53, v[152:153]
	v_lshl_add_u64 v[180:181], v[176:177], 0, v[156:157]
	v_pk_mul_f32 v[178:179], v[94:95], v[136:137] op_sel_hi:[1,0]
	v_pk_mul_f32 v[176:177], v[92:93], v[136:137] op_sel_hi:[1,0]
	v_pk_mul_f32 v[182:183], v[90:91], v[136:137] op_sel_hi:[1,0]
	v_pk_mul_f32 v[184:185], v[88:89], v[136:137] op_sel_hi:[1,0]
	v_cvt_pk_bf16_f32 v176, v176, v177
	v_cvt_pk_bf16_f32 v177, v178, v179
	v_pk_mul_f32 v[186:187], v[86:87], v[136:137] op_sel_hi:[1,0]
	v_cvt_pk_bf16_f32 v178, v184, v185
	v_cvt_pk_bf16_f32 v179, v182, v183
	v_pk_mul_f32 v[188:189], v[84:85], v[136:137] op_sel_hi:[1,0]
	v_pk_mul_f32 v[190:191], v[82:83], v[136:137] op_sel_hi:[1,0]
	v_pk_mul_f32 v[192:193], v[80:81], v[136:137] op_sel_hi:[1,0]
	global_store_dwordx4 v[180:181], v[176:179], off
	s_nop 1
	v_cvt_pk_bf16_f32 v176, v188, v189
	v_cvt_pk_bf16_f32 v177, v186, v187
	v_cvt_pk_bf16_f32 v178, v192, v193
	v_cvt_pk_bf16_f32 v179, v190, v191
	global_store_dwordx4 v[180:181], v[176:179], off offset:256
	s_nop 1
	v_mov_b32_e32 v136, v206
	v_mul_f32_e32 v136, v175, v136
	v_mad_i64_i32 v[176:177], s[44:45], v172, s53, v[152:153]
	v_lshl_add_u64 v[180:181], v[176:177], 0, v[156:157]
	v_pk_mul_f32 v[178:179], v[78:79], v[136:137] op_sel_hi:[1,0]
	v_pk_mul_f32 v[176:177], v[76:77], v[136:137] op_sel_hi:[1,0]
	v_pk_mul_f32 v[182:183], v[74:75], v[136:137] op_sel_hi:[1,0]
	v_pk_mul_f32 v[184:185], v[72:73], v[136:137] op_sel_hi:[1,0]
	v_cvt_pk_bf16_f32 v176, v176, v177
	v_cvt_pk_bf16_f32 v177, v178, v179
	v_pk_mul_f32 v[186:187], v[70:71], v[136:137] op_sel_hi:[1,0]
	v_cvt_pk_bf16_f32 v178, v184, v185
	v_cvt_pk_bf16_f32 v179, v182, v183
	v_pk_mul_f32 v[188:189], v[68:69], v[136:137] op_sel_hi:[1,0]
	v_pk_mul_f32 v[190:191], v[66:67], v[136:137] op_sel_hi:[1,0]
	v_pk_mul_f32 v[192:193], v[64:65], v[136:137] op_sel_hi:[1,0]
	global_store_dwordx4 v[180:181], v[176:179], off
	s_nop 1
	v_cvt_pk_bf16_f32 v176, v188, v189
	v_cvt_pk_bf16_f32 v177, v186, v187
	v_cvt_pk_bf16_f32 v178, v192, v193
	v_cvt_pk_bf16_f32 v179, v190, v191
	global_store_dwordx4 v[180:181], v[176:179], off offset:256
	s_nop 1
	v_mov_b32_e32 v136, v207
	v_mul_f32_e32 v136, v175, v136
	v_mad_i64_i32 v[176:177], s[44:45], v171, s53, v[152:153]
	v_lshl_add_u64 v[180:181], v[176:177], 0, v[156:157]
	v_pk_mul_f32 v[178:179], v[62:63], v[136:137] op_sel_hi:[1,0]
	v_pk_mul_f32 v[176:177], v[60:61], v[136:137] op_sel_hi:[1,0]
	v_pk_mul_f32 v[182:183], v[58:59], v[136:137] op_sel_hi:[1,0]
	v_pk_mul_f32 v[184:185], v[56:57], v[136:137] op_sel_hi:[1,0]
	v_cvt_pk_bf16_f32 v176, v176, v177
	v_cvt_pk_bf16_f32 v177, v178, v179
	v_pk_mul_f32 v[186:187], v[54:55], v[136:137] op_sel_hi:[1,0]
	v_cvt_pk_bf16_f32 v178, v184, v185
	v_cvt_pk_bf16_f32 v179, v182, v183
	v_pk_mul_f32 v[188:189], v[52:53], v[136:137] op_sel_hi:[1,0]
	v_pk_mul_f32 v[190:191], v[50:51], v[136:137] op_sel_hi:[1,0]
	v_pk_mul_f32 v[192:193], v[48:49], v[136:137] op_sel_hi:[1,0]
	global_store_dwordx4 v[180:181], v[176:179], off
	s_nop 1
	v_cvt_pk_bf16_f32 v176, v188, v189
	v_cvt_pk_bf16_f32 v177, v186, v187
	v_cvt_pk_bf16_f32 v178, v192, v193
	v_cvt_pk_bf16_f32 v179, v190, v191
	global_store_dwordx4 v[180:181], v[176:179], off offset:256
	s_nop 1
	v_mov_b32_e32 v136, v208
	v_mul_f32_e32 v136, v175, v136
	v_mad_i64_i32 v[176:177], s[44:45], v170, s53, v[152:153]
	v_lshl_add_u64 v[180:181], v[176:177], 0, v[156:157]
	v_pk_mul_f32 v[178:179], v[46:47], v[136:137] op_sel_hi:[1,0]
	v_pk_mul_f32 v[176:177], v[44:45], v[136:137] op_sel_hi:[1,0]
	v_pk_mul_f32 v[182:183], v[42:43], v[136:137] op_sel_hi:[1,0]
	v_pk_mul_f32 v[184:185], v[40:41], v[136:137] op_sel_hi:[1,0]
	v_cvt_pk_bf16_f32 v176, v176, v177
	v_cvt_pk_bf16_f32 v177, v178, v179
	v_pk_mul_f32 v[186:187], v[38:39], v[136:137] op_sel_hi:[1,0]
	v_cvt_pk_bf16_f32 v178, v184, v185
	v_cvt_pk_bf16_f32 v179, v182, v183
	v_pk_mul_f32 v[188:189], v[36:37], v[136:137] op_sel_hi:[1,0]
	v_pk_mul_f32 v[190:191], v[34:35], v[136:137] op_sel_hi:[1,0]
	v_pk_mul_f32 v[192:193], v[32:33], v[136:137] op_sel_hi:[1,0]
	global_store_dwordx4 v[180:181], v[176:179], off
	s_nop 1
	v_cvt_pk_bf16_f32 v176, v188, v189
	v_cvt_pk_bf16_f32 v177, v186, v187
	v_cvt_pk_bf16_f32 v178, v192, v193
	v_cvt_pk_bf16_f32 v179, v190, v191
	global_store_dwordx4 v[180:181], v[176:179], off offset:256
	s_nop 1
	v_mov_b32_e32 v136, v209
	v_mul_f32_e32 v136, v175, v136
	v_mad_i64_i32 v[176:177], s[44:45], v169, s53, v[152:153]
	v_lshl_add_u64 v[180:181], v[176:177], 0, v[156:157]
	v_pk_mul_f32 v[178:179], v[30:31], v[136:137] op_sel_hi:[1,0]
	v_pk_mul_f32 v[176:177], v[28:29], v[136:137] op_sel_hi:[1,0]
	v_pk_mul_f32 v[182:183], v[26:27], v[136:137] op_sel_hi:[1,0]
	v_pk_mul_f32 v[184:185], v[24:25], v[136:137] op_sel_hi:[1,0]
	v_cvt_pk_bf16_f32 v176, v176, v177
	v_cvt_pk_bf16_f32 v177, v178, v179
	v_pk_mul_f32 v[186:187], v[22:23], v[136:137] op_sel_hi:[1,0]
	v_cvt_pk_bf16_f32 v178, v184, v185
	v_cvt_pk_bf16_f32 v179, v182, v183
	v_pk_mul_f32 v[188:189], v[20:21], v[136:137] op_sel_hi:[1,0]
	v_pk_mul_f32 v[190:191], v[18:19], v[136:137] op_sel_hi:[1,0]
	v_pk_mul_f32 v[192:193], v[16:17], v[136:137] op_sel_hi:[1,0]
	global_store_dwordx4 v[180:181], v[176:179], off
	s_nop 1
	v_cvt_pk_bf16_f32 v176, v188, v189
	v_cvt_pk_bf16_f32 v177, v186, v187
	v_cvt_pk_bf16_f32 v178, v192, v193
	v_cvt_pk_bf16_f32 v179, v190, v191
	global_store_dwordx4 v[180:181], v[176:179], off offset:256
	s_nop 1
	v_mov_b32_e32 v136, v210
	v_mad_i64_i32 v[150:151], s[44:45], v168, s53, v[152:153]
	v_lshl_add_u64 v[156:157], v[150:151], 0, v[156:157]
	s_mov_b64 s[44:45], 0
	v_mul_f32_e32 v136, v175, v136
	v_pk_mul_f32 v[152:153], v[14:15], v[136:137] op_sel_hi:[1,0]
	v_pk_mul_f32 v[150:151], v[12:13], v[136:137] op_sel_hi:[1,0]
	v_pk_mul_f32 v[176:177], v[10:11], v[136:137] op_sel_hi:[1,0]
	v_pk_mul_f32 v[178:179], v[8:9], v[136:137] op_sel_hi:[1,0]
	v_cvt_pk_bf16_f32 v150, v150, v151
	v_cvt_pk_bf16_f32 v151, v152, v153
	v_pk_mul_f32 v[180:181], v[6:7], v[136:137] op_sel_hi:[1,0]
	v_cvt_pk_bf16_f32 v152, v178, v179
	v_cvt_pk_bf16_f32 v153, v176, v177
	v_pk_mul_f32 v[182:183], v[4:5], v[136:137] op_sel_hi:[1,0]
	v_pk_mul_f32 v[184:185], v[2:3], v[136:137] op_sel_hi:[1,0]
	v_pk_mul_f32 v[186:187], v[0:1], v[136:137] op_sel_hi:[1,0]
	global_store_dwordx4 v[156:157], v[150:153], off
	s_nop 1
	v_cvt_pk_bf16_f32 v150, v182, v183
	v_cvt_pk_bf16_f32 v151, v180, v181
	v_cvt_pk_bf16_f32 v152, v186, v187
	v_cvt_pk_bf16_f32 v153, v184, v185
	global_store_dwordx4 v[156:157], v[150:153], off offset:256

; #define PG8_STAGE(bufoff, gbase, voff) do { _Pragma("unroll") for (int _i = 0; _i < 2; ++_i) \
;         __builtin_amdgcn_global_load_lds((const unsigned*)((const char*)(gbase) + (voff)[_i]), (LAS unsigned*)(lds + (bufoff) + ldsw + _i * 8192), 16, 0, 0); } while (0)
; #define PG8_LDA(dst, b, h) do { _Pragma("unroll") for (int m = 0; m < 4; ++m) _Pragma("unroll") for (int k = 0; k < 2; ++k) dst[m][k] = *(const LAS bf16x8*)(lds + PG8_SA(b, h) + aoff + m * 2048 + k * 1024); } while (0)
; #define PG8_LDB(dst, b, h) do { _Pragma("unroll") for (int n = 0; n < 2; ++n) _Pragma("unroll") for (int k = 0; k < 2; ++k) dst[n][k] = *(const LAS bf16x8*)(lds + PG8_SB(b, h) + boff + n * 2048 + k * 1024); } while (0)
; #define PG8_MMA(ai, bj, At, Bt) do { __builtin_amdgcn_s_setprio(1); _Pragma("unroll") for (int m = 0; m < 4; ++m) _Pragma("unroll") for (int n = 0; n < 2; ++n) _Pragma("unroll") for (int k = 0; k < 2; ++k) \
;         acc[ai][bj][m][n] = __builtin_amdgcn_mfma_f32_16x16x32_bf16(Bt[n][k], At[m][k], acc[ai][bj][m][n], 0, 0, 0); __builtin_amdgcn_s_setprio(0); } while (0)
; #define PG8_WAIT_V(n) asm volatile("s_waitcnt vmcnt(" #n ")" ::: "memory")
; #define PG8_WAIT_L(n) asm volatile("s_waitcnt lgkmcnt(" #n ")" ::: "memory")
; #define PG8_BAR __builtin_amdgcn_s_barrier()
; #define PG8_SCHED __builtin_amdgcn_sched_barrier(0)
; template <class Epi>
; __device__ __forceinline__ void gemm_phase(LAS unsigned char* lds, const Gemm g, const StaticOrder& S, const Epi& E) {
;     ...
;             PG8_LDB(B0, 0, 0); PG8_SCHED; PG8_LDA(At, 0, 0); PG8_STAGE(PG8_SA(1, 1), a1 + hstep, voffA);
;             PG8_WAIT_L(8); PG8_BAR; PG8_WAIT_L(0); PG8_MMA(0, 0, At, B0); PG8_BAR; PG8_SCHED;
;             PG8_LDB(B1, 0, 1); PG8_STAGE(PG8_SB(0, 0), b2, voffB);
;             PG8_BAR; PG8_WAIT_L(0); PG8_MMA(0, 1, At, B1); PG8_BAR;
;             PG8_LDA(At, 0, 1); PG8_STAGE(PG8_SA(0, 0), a2, voffA);
;             PG8_BAR; PG8_WAIT_L(0); PG8_MMA(1, 0, At, B0); PG8_BAR; PG8_SCHED;
;             PG8_STAGE(PG8_SB(0, 1), b2 + hstep, voffB);
;             PG8_WAIT_V(6); PG8_BAR; PG8_MMA(1, 1, At, B1); PG8_BAR;
.LBB0_673:
	ds_read_b128 v[148:151], v145
	ds_read_b128 v[152:155], v145 offset:1024
	ds_read_b128 v[160:163], v145 offset:2048
	ds_read_b128 v[164:167], v145 offset:3072
	s_add_u32 s52, s50, 0xfff80080
	s_addc_u32 s53, s51, -1
	s_cmp_eq_u32 s69, 28
	s_cselect_b32 s55, s43, s53
	s_cselect_b32 s54, s65, s52
	s_cselect_b32 s53, s41, s68
	s_cselect_b32 s52, s66, s67
	s_add_i32 m0, s28, 0xc000
	ds_read_b128 v[168:171], v146
	ds_read_b128 v[172:175], v146 offset:1024
	ds_read_b128 v[176:179], v146 offset:2048
	ds_read_b128 v[180:183], v146 offset:3072
	ds_read_b128 v[184:187], v146 offset:4096
	ds_read_b128 v[188:191], v146 offset:5120
	ds_read_b128 v[192:195], v146 offset:6144
	ds_read_b128 v[196:199], v146 offset:7168
	global_load_lds_dwordx4 v136, s[50:51]
	s_add_i32 m0, s28, 0xe000
	s_nop 0
	global_load_lds_dwordx4 v138, s[50:51]
	s_waitcnt lgkmcnt(8)
	s_barrier
	s_waitcnt lgkmcnt(0)
	s_setprio 1
	s_waitcnt lgkmcnt(0)
	v_mfma_f32_16x16x32_bf16 v[124:127], v[148:151], v[168:171], v[124:127]
	v_mfma_f32_16x16x32_bf16 v[120:123], v[160:163], v[168:171], v[120:123]
	v_mfma_f32_16x16x32_bf16 v[112:115], v[148:151], v[176:179], v[112:115]
	v_mfma_f32_16x16x32_bf16 v[104:107], v[160:163], v[176:179], v[104:107]
	v_mfma_f32_16x16x32_bf16 v[96:99], v[148:151], v[184:187], v[96:99]
	v_mfma_f32_16x16x32_bf16 v[88:91], v[160:163], v[184:187], v[88:91]
	v_mfma_f32_16x16x32_bf16 v[80:83], v[148:151], v[192:195], v[80:83]
	v_mfma_f32_16x16x32_bf16 v[72:75], v[160:163], v[192:195], v[72:75]
	v_mfma_f32_16x16x32_bf16 v[124:127], v[152:155], v[172:175], v[124:127]
	v_mfma_f32_16x16x32_bf16 v[120:123], v[164:167], v[172:175], v[120:123]
	v_mfma_f32_16x16x32_bf16 v[112:115], v[152:155], v[180:183], v[112:115]
	v_mfma_f32_16x16x32_bf16 v[104:107], v[164:167], v[180:183], v[104:107]
	v_mfma_f32_16x16x32_bf16 v[96:99], v[152:155], v[188:191], v[96:99]
	v_mfma_f32_16x16x32_bf16 v[88:91], v[164:167], v[188:191], v[88:91]
	v_mfma_f32_16x16x32_bf16 v[80:83], v[152:155], v[196:199], v[80:83]
	v_mfma_f32_16x16x32_bf16 v[72:75], v[164:167], v[196:199], v[72:75]
	s_setprio 0
	s_barrier
	s_add_i32 s70, s58, s23
	s_add_u32 s98, s52, s6
	s_addc_u32 s99, s53, s7
	s_mov_b32 m0, s70
	ds_read_b128 v[200:203], v147
	ds_read_b128 v[204:207], v147 offset:1024
	ds_read_b128 v[208:211], v147 offset:2048
	ds_read_b128 v[212:215], v147 offset:3072
	global_load_lds_dwordx4 v132, s[52:53]
	s_add_i32 m0, s70, 0x2000
	s_nop 0
	global_load_lds_dwordx4 v128, s[52:53]
	s_barrier
	s_waitcnt lgkmcnt(0)
	s_setprio 1
	s_waitcnt lgkmcnt(0)
	v_mfma_f32_16x16x32_bf16 v[116:119], v[200:203], v[168:171], v[116:119]
	v_mfma_f32_16x16x32_bf16 v[108:111], v[208:211], v[168:171], v[108:111]
	v_mfma_f32_16x16x32_bf16 v[100:103], v[200:203], v[176:179], v[100:103]
	v_mfma_f32_16x16x32_bf16 v[92:95], v[208:211], v[176:179], v[92:95]
	v_mfma_f32_16x16x32_bf16 v[84:87], v[200:203], v[184:187], v[84:87]
	v_mfma_f32_16x16x32_bf16 v[76:79], v[208:211], v[184:187], v[76:79]
	v_mfma_f32_16x16x32_bf16 v[68:71], v[200:203], v[192:195], v[68:71]
	v_mfma_f32_16x16x32_bf16 v[64:67], v[208:211], v[192:195], v[64:67]
	v_mfma_f32_16x16x32_bf16 v[116:119], v[204:207], v[172:175], v[116:119]
	v_mfma_f32_16x16x32_bf16 v[108:111], v[212:215], v[172:175], v[108:111]
	v_mfma_f32_16x16x32_bf16 v[100:103], v[204:207], v[180:183], v[100:103]
	v_mfma_f32_16x16x32_bf16 v[92:95], v[212:215], v[180:183], v[92:95]
	v_mfma_f32_16x16x32_bf16 v[84:87], v[204:207], v[188:191], v[84:87]
	v_mfma_f32_16x16x32_bf16 v[76:79], v[212:215], v[188:191], v[76:79]
	v_mfma_f32_16x16x32_bf16 v[68:71], v[204:207], v[196:199], v[68:71]
	v_mfma_f32_16x16x32_bf16 v[64:67], v[212:215], v[196:199], v[64:67]
	s_setprio 0
	s_mov_b32 m0, s28
	s_add_u32 s100, s54, s6
	s_addc_u32 s101, s55, s7
	s_barrier
	ds_read_b128 v[168:171], v146 offset:16384
	ds_read_b128 v[172:175], v146 offset:17408
	ds_read_b128 v[176:179], v146 offset:18432
	ds_read_b128 v[180:183], v146 offset:19456
	ds_read_b128 v[184:187], v146 offset:20480
	ds_read_b128 v[188:191], v146 offset:21504
	ds_read_b128 v[192:195], v146 offset:22528
	ds_read_b128 v[196:199], v146 offset:23552
	global_load_lds_dwordx4 v134, s[54:55]
	s_mov_b32 m0, s29
	s_nop 0
	global_load_lds_dwordx4 v130, s[54:55]
	s_barrier
	s_waitcnt lgkmcnt(0)
	s_setprio 1
	s_waitcnt lgkmcnt(0)
	v_mfma_f32_16x16x32_bf16 v[60:63], v[148:151], v[168:171], v[60:63]
	v_mfma_f32_16x16x32_bf16 v[56:59], v[160:163], v[168:171], v[56:59]
	v_mfma_f32_16x16x32_bf16 v[52:55], v[148:151], v[176:179], v[52:55]
	v_mfma_f32_16x16x32_bf16 v[44:47], v[160:163], v[176:179], v[44:47]
	v_mfma_f32_16x16x32_bf16 v[36:39], v[148:151], v[184:187], v[36:39]
	v_mfma_f32_16x16x32_bf16 v[28:31], v[160:163], v[184:187], v[28:31]
	v_mfma_f32_16x16x32_bf16 v[20:23], v[148:151], v[192:195], v[20:23]
	v_mfma_f32_16x16x32_bf16 v[12:15], v[160:163], v[192:195], v[12:15]
	v_mfma_f32_16x16x32_bf16 v[60:63], v[152:155], v[172:175], v[60:63]
	v_mfma_f32_16x16x32_bf16 v[56:59], v[164:167], v[172:175], v[56:59]
	v_mfma_f32_16x16x32_bf16 v[52:55], v[152:155], v[180:183], v[52:55]
	v_mfma_f32_16x16x32_bf16 v[44:47], v[164:167], v[180:183], v[44:47]
	v_mfma_f32_16x16x32_bf16 v[36:39], v[152:155], v[188:191], v[36:39]
	v_mfma_f32_16x16x32_bf16 v[28:31], v[164:167], v[188:191], v[28:31]
	v_mfma_f32_16x16x32_bf16 v[20:23], v[152:155], v[196:199], v[20:23]
	v_mfma_f32_16x16x32_bf16 v[12:15], v[164:167], v[196:199], v[12:15]
	s_setprio 0
	s_barrier
	s_add_u32 s70, s52, 0x80000
	s_addc_u32 s71, s53, 0
	s_add_i32 s72, s59, s23
	s_mov_b32 m0, s72
	s_nop 0
	global_load_lds_dwordx4 v132, s[70:71]
	s_add_i32 m0, s72, 0x2000
	s_nop 0
	global_load_lds_dwordx4 v128, s[70:71]
	s_waitcnt vmcnt(6)
	s_barrier
; #define PG8_STAGE(bufoff, gbase, voff) do { _Pragma("unroll") for (int _i = 0; _i < 2; ++_i) \
;         __builtin_amdgcn_global_load_lds((const unsigned*)((const char*)(gbase) + (voff)[_i]), (LAS unsigned*)(lds + (bufoff) + ldsw + _i * 8192), 16, 0, 0); } while (0)
; #define PG8_LDA(dst, b, h) do { _Pragma("unroll") for (int m = 0; m < 4; ++m) _Pragma("unroll") for (int k = 0; k < 2; ++k) dst[m][k] = *(const LAS bf16x8*)(lds + PG8_SA(b, h) + aoff + m * 2048 + k * 1024); } while (0)
; #define PG8_LDB(dst, b, h) do { _Pragma("unroll") for (int n = 0; n < 2; ++n) _Pragma("unroll") for (int k = 0; k < 2; ++k) dst[n][k] = *(const LAS bf16x8*)(lds + PG8_SB(b, h) + boff + n * 2048 + k * 1024); } while (0)
; #define PG8_MMA(ai, bj, At, Bt) do { __builtin_amdgcn_s_setprio(1); _Pragma("unroll") for (int m = 0; m < 4; ++m) _Pragma("unroll") for (int n = 0; n < 2; ++n) _Pragma("unroll") for (int k = 0; k < 2; ++k) \
;         acc[ai][bj][m][n] = __builtin_amdgcn_mfma_f32_16x16x32_bf16(Bt[n][k], At[m][k], acc[ai][bj][m][n], 0, 0, 0); __builtin_amdgcn_s_setprio(0); } while (0)
; #define PG8_WAIT_V(n) asm volatile("s_waitcnt vmcnt(" #n ")" ::: "memory")
; #define PG8_WAIT_L(n) asm volatile("s_waitcnt lgkmcnt(" #n ")" ::: "memory")
; #define PG8_BAR __builtin_amdgcn_s_barrier()
; #define PG8_SCHED __builtin_amdgcn_sched_barrier(0)
; template <class Epi>
; __device__ __forceinline__ void gemm_phase(LAS unsigned char* lds, const Gemm g, const StaticOrder& S, const Epi& E) {
;     ...
;             PG8_WAIT_V(6); PG8_BAR; PG8_MMA(1, 1, At, B1); PG8_BAR;
;             PG8_LDB(B0, 1, 0); PG8_SCHED; PG8_LDA(At, 1, 0); PG8_STAGE(PG8_SA(0, 1), a2 + hstep, voffA);
;             PG8_WAIT_L(8); PG8_BAR; PG8_WAIT_L(0); PG8_MMA(0, 0, At, B0); PG8_BAR; PG8_SCHED;
;             PG8_LDB(B1, 1, 1); PG8_STAGE(PG8_SB(1, 0), b3, voffB);
;             PG8_BAR; PG8_WAIT_L(0); PG8_MMA(0, 1, At, B1); PG8_BAR;
;             PG8_LDA(At, 1, 1); PG8_STAGE(PG8_SA(1, 0), a3, voffA);
;             PG8_BAR; PG8_WAIT_L(0); PG8_MMA(1, 0, At, B0); PG8_BAR; PG8_SCHED;
;             PG8_STAGE(PG8_SB(1, 1), b3 + hstep, voffB);
	s_setprio 1
	v_mfma_f32_16x16x32_bf16 v[48:51], v[200:203], v[168:171], v[48:51]
	v_mfma_f32_16x16x32_bf16 v[40:43], v[208:211], v[168:171], v[40:43]
	v_mfma_f32_16x16x32_bf16 v[32:35], v[200:203], v[176:179], v[32:35]
	v_mfma_f32_16x16x32_bf16 v[24:27], v[208:211], v[176:179], v[24:27]
	v_mfma_f32_16x16x32_bf16 v[16:19], v[200:203], v[184:187], v[16:19]
	v_mfma_f32_16x16x32_bf16 v[8:11], v[208:211], v[184:187], v[8:11]
	v_mfma_f32_16x16x32_bf16 v[4:7], v[200:203], v[192:195], v[4:7]
	v_mfma_f32_16x16x32_bf16 v[0:3], v[208:211], v[192:195], v[0:3]
	v_mfma_f32_16x16x32_bf16 v[48:51], v[204:207], v[172:175], v[48:51]
	v_mfma_f32_16x16x32_bf16 v[40:43], v[212:215], v[172:175], v[40:43]
	v_mfma_f32_16x16x32_bf16 v[32:35], v[204:207], v[180:183], v[32:35]
	v_mfma_f32_16x16x32_bf16 v[24:27], v[212:215], v[180:183], v[24:27]
	v_mfma_f32_16x16x32_bf16 v[16:19], v[204:207], v[188:191], v[16:19]
	v_mfma_f32_16x16x32_bf16 v[8:11], v[212:215], v[188:191], v[8:11]
	v_mfma_f32_16x16x32_bf16 v[4:7], v[204:207], v[196:199], v[4:7]
	v_mfma_f32_16x16x32_bf16 v[0:3], v[212:215], v[196:199], v[0:3]
	s_setprio 0
	s_add_i32 s70, 0, 0x18000
	v_add_u32_e32 v164, s70, v143
	s_barrier
	ds_read_b128 v[148:151], v164
	ds_read_b128 v[152:155], v164 offset:1024
	ds_read_b128 v[160:163], v164 offset:2048
	ds_read_b128 v[164:167], v164 offset:3072
	s_add_u32 s54, s54, 0x80000
	s_addc_u32 s55, s55, 0
	s_mov_b32 m0, s33
	ds_read_b128 v[168:171], v146 offset:32768
	ds_read_b128 v[172:175], v146 offset:33792
	ds_read_b128 v[176:179], v146 offset:34816
	ds_read_b128 v[180:183], v146 offset:35840
	ds_read_b128 v[184:187], v146 offset:36864
	ds_read_b128 v[188:191], v146 offset:37888
	ds_read_b128 v[192:195], v146 offset:38912
	ds_read_b128 v[196:199], v146 offset:39936
	global_load_lds_dwordx4 v134, s[54:55]
	s_mov_b32 m0, s36
	s_nop 0
	global_load_lds_dwordx4 v130, s[54:55]
	s_waitcnt lgkmcnt(8)
	s_barrier
	s_waitcnt lgkmcnt(0)
	s_setprio 1
	s_waitcnt lgkmcnt(0)
	v_mfma_f32_16x16x32_bf16 v[124:127], v[148:151], v[168:171], v[124:127]
	v_mfma_f32_16x16x32_bf16 v[120:123], v[160:163], v[168:171], v[120:123]
	v_mfma_f32_16x16x32_bf16 v[112:115], v[148:151], v[176:179], v[112:115]
	v_mfma_f32_16x16x32_bf16 v[104:107], v[160:163], v[176:179], v[104:107]
	v_mfma_f32_16x16x32_bf16 v[96:99], v[148:151], v[184:187], v[96:99]
	v_mfma_f32_16x16x32_bf16 v[88:91], v[160:163], v[184:187], v[88:91]
	v_mfma_f32_16x16x32_bf16 v[80:83], v[148:151], v[192:195], v[80:83]
	v_mfma_f32_16x16x32_bf16 v[72:75], v[160:163], v[192:195], v[72:75]
	v_mfma_f32_16x16x32_bf16 v[124:127], v[152:155], v[172:175], v[124:127]
	v_mfma_f32_16x16x32_bf16 v[120:123], v[164:167], v[172:175], v[120:123]
	v_mfma_f32_16x16x32_bf16 v[112:115], v[152:155], v[180:183], v[112:115]
	v_mfma_f32_16x16x32_bf16 v[104:107], v[164:167], v[180:183], v[104:107]
	v_mfma_f32_16x16x32_bf16 v[96:99], v[152:155], v[188:191], v[96:99]
	v_mfma_f32_16x16x32_bf16 v[88:91], v[164:167], v[188:191], v[88:91]
	v_mfma_f32_16x16x32_bf16 v[80:83], v[152:155], v[196:199], v[80:83]
	v_mfma_f32_16x16x32_bf16 v[72:75], v[164:167], v[196:199], v[72:75]
	s_setprio 0
	s_barrier
	s_add_i32 s54, 0, 0x1c000
	s_add_i32 s55, s70, s23
	v_add_u32_e32 v212, s54, v143
	s_mov_b32 m0, s55
	ds_read_b128 v[200:203], v212
	ds_read_b128 v[204:207], v212 offset:1024
	ds_read_b128 v[208:211], v212 offset:2048
	ds_read_b128 v[212:215], v212 offset:3072
	global_load_lds_dwordx4 v132, s[98:99]
	s_add_i32 m0, s55, 0x2000
	s_nop 0
	global_load_lds_dwordx4 v128, s[98:99]
	s_barrier
	s_waitcnt lgkmcnt(0)
	s_setprio 1
	s_waitcnt lgkmcnt(0)
	v_mfma_f32_16x16x32_bf16 v[116:119], v[200:203], v[168:171], v[116:119]
	v_mfma_f32_16x16x32_bf16 v[108:111], v[208:211], v[168:171], v[108:111]
	v_mfma_f32_16x16x32_bf16 v[100:103], v[200:203], v[176:179], v[100:103]
	v_mfma_f32_16x16x32_bf16 v[92:95], v[208:211], v[176:179], v[92:95]
	v_mfma_f32_16x16x32_bf16 v[84:87], v[200:203], v[184:187], v[84:87]
	v_mfma_f32_16x16x32_bf16 v[76:79], v[208:211], v[184:187], v[76:79]
	v_mfma_f32_16x16x32_bf16 v[68:71], v[200:203], v[192:195], v[68:71]
	v_mfma_f32_16x16x32_bf16 v[64:67], v[208:211], v[192:195], v[64:67]
	v_mfma_f32_16x16x32_bf16 v[116:119], v[204:207], v[172:175], v[116:119]
	v_mfma_f32_16x16x32_bf16 v[108:111], v[212:215], v[172:175], v[108:111]
	v_mfma_f32_16x16x32_bf16 v[100:103], v[204:207], v[180:183], v[100:103]
	v_mfma_f32_16x16x32_bf16 v[92:95], v[212:215], v[180:183], v[92:95]
	v_mfma_f32_16x16x32_bf16 v[84:87], v[204:207], v[188:191], v[84:87]
	v_mfma_f32_16x16x32_bf16 v[76:79], v[212:215], v[188:191], v[76:79]
	v_mfma_f32_16x16x32_bf16 v[68:71], v[204:207], v[196:199], v[68:71]
	v_mfma_f32_16x16x32_bf16 v[64:67], v[212:215], v[196:199], v[64:67]
	s_setprio 0
	s_mov_b32 m0, s49
	s_barrier
	ds_read_b128 v[168:171], v146 offset:49152
	ds_read_b128 v[172:175], v146 offset:50176
	ds_read_b128 v[176:179], v146 offset:51200
	ds_read_b128 v[180:183], v146 offset:52224
	ds_read_b128 v[184:187], v146 offset:53248
	ds_read_b128 v[188:191], v146 offset:54272
	ds_read_b128 v[192:195], v146 offset:55296
	ds_read_b128 v[196:199], v146 offset:56320
	global_load_lds_dwordx4 v134, s[100:101]
	s_mov_b32 m0, s56
	s_nop 0
	global_load_lds_dwordx4 v130, s[100:101]
	s_barrier
; #define PG8_STAGE(bufoff, gbase, voff) do { _Pragma("unroll") for (int _i = 0; _i < 2; ++_i) \
;         __builtin_amdgcn_global_load_lds((const unsigned*)((const char*)(gbase) + (voff)[_i]), (LAS unsigned*)(lds + (bufoff) + ldsw + _i * 8192), 16, 0, 0); } while (0)
; #define PG8_LDA(dst, b, h) do { _Pragma("unroll") for (int m = 0; m < 4; ++m) _Pragma("unroll") for (int k = 0; k < 2; ++k) dst[m][k] = *(const LAS bf16x8*)(lds + PG8_SA(b, h) + aoff + m * 2048 + k * 1024); } while (0)
; #define PG8_MMA(ai, bj, At, Bt) do { __builtin_amdgcn_s_setprio(1); _Pragma("unroll") for (int m = 0; m < 4; ++m) _Pragma("unroll") for (int n = 0; n < 2; ++n) _Pragma("unroll") for (int k = 0; k < 2; ++k) \
;         acc[ai][bj][m][n] = __builtin_amdgcn_mfma_f32_16x16x32_bf16(Bt[n][k], At[m][k], acc[ai][bj][m][n], 0, 0, 0); __builtin_amdgcn_s_setprio(0); } while (0)
; #define PG8_WAIT_V(n) asm volatile("s_waitcnt vmcnt(" #n ")" ::: "memory")
; #define PG8_WAIT_L(n) asm volatile("s_waitcnt lgkmcnt(" #n ")" ::: "memory")
; #define PG8_BAR __builtin_amdgcn_s_barrier()
; #define PG8_SCHED __builtin_amdgcn_sched_barrier(0)
; template <class Epi>
; __device__ __forceinline__ void gemm_phase(LAS unsigned char* lds, const Gemm g, const StaticOrder& S, const Epi& E) {
;     ...
;             PG8_BAR; PG8_WAIT_L(0); PG8_MMA(0, 1, At, B1); PG8_BAR;
;             PG8_LDA(At, 1, 1); PG8_STAGE(PG8_SA(1, 0), a3, voffA);
;             PG8_BAR; PG8_WAIT_L(0); PG8_MMA(1, 0, At, B0); PG8_BAR; PG8_SCHED;
;             PG8_STAGE(PG8_SB(1, 1), b3 + hstep, voffB);
;             PG8_WAIT_V(6); PG8_BAR; PG8_MMA(1, 1, At, B1); PG8_BAR;
	s_waitcnt lgkmcnt(0)
	s_setprio 1
	s_waitcnt lgkmcnt(0)
	v_mfma_f32_16x16x32_bf16 v[60:63], v[148:151], v[168:171], v[60:63]
	v_mfma_f32_16x16x32_bf16 v[56:59], v[160:163], v[168:171], v[56:59]
	v_mfma_f32_16x16x32_bf16 v[52:55], v[148:151], v[176:179], v[52:55]
	v_mfma_f32_16x16x32_bf16 v[44:47], v[160:163], v[176:179], v[44:47]
	v_mfma_f32_16x16x32_bf16 v[36:39], v[148:151], v[184:187], v[36:39]
	v_mfma_f32_16x16x32_bf16 v[28:31], v[160:163], v[184:187], v[28:31]
	v_mfma_f32_16x16x32_bf16 v[20:23], v[148:151], v[192:195], v[20:23]
	v_mfma_f32_16x16x32_bf16 v[12:15], v[160:163], v[192:195], v[12:15]
	v_mfma_f32_16x16x32_bf16 v[60:63], v[152:155], v[172:175], v[60:63]
	v_mfma_f32_16x16x32_bf16 v[56:59], v[164:167], v[172:175], v[56:59]
	v_mfma_f32_16x16x32_bf16 v[52:55], v[152:155], v[180:183], v[52:55]
	v_mfma_f32_16x16x32_bf16 v[44:47], v[164:167], v[180:183], v[44:47]
	v_mfma_f32_16x16x32_bf16 v[36:39], v[152:155], v[188:191], v[36:39]
	v_mfma_f32_16x16x32_bf16 v[28:31], v[164:167], v[188:191], v[28:31]
	v_mfma_f32_16x16x32_bf16 v[20:23], v[152:155], v[196:199], v[20:23]
	v_mfma_f32_16x16x32_bf16 v[12:15], v[164:167], v[196:199], v[12:15]
	s_setprio 0
	s_barrier
	s_add_u32 s52, s52, 0x80080
	s_addc_u32 s53, s53, 0
	s_add_i32 s54, s54, s23
	s_mov_b32 m0, s54
	s_nop 0
	global_load_lds_dwordx4 v132, s[52:53]
	s_add_i32 m0, s54, 0x2000
	s_nop 0
	global_load_lds_dwordx4 v128, s[52:53]
	s_waitcnt vmcnt(6)
	s_barrier
	s_setprio 1
	v_mfma_f32_16x16x32_bf16 v[48:51], v[200:203], v[168:171], v[48:51]
	v_mfma_f32_16x16x32_bf16 v[40:43], v[208:211], v[168:171], v[40:43]
	v_mfma_f32_16x16x32_bf16 v[32:35], v[200:203], v[176:179], v[32:35]
	v_mfma_f32_16x16x32_bf16 v[24:27], v[208:211], v[176:179], v[24:27]
	v_mfma_f32_16x16x32_bf16 v[16:19], v[200:203], v[184:187], v[16:19]
	v_mfma_f32_16x16x32_bf16 v[8:11], v[208:211], v[184:187], v[8:11]
	v_mfma_f32_16x16x32_bf16 v[4:7], v[200:203], v[192:195], v[4:7]
	v_mfma_f32_16x16x32_bf16 v[0:3], v[208:211], v[192:195], v[0:3]
	v_mfma_f32_16x16x32_bf16 v[48:51], v[204:207], v[172:175], v[48:51]
	v_mfma_f32_16x16x32_bf16 v[40:43], v[212:215], v[172:175], v[40:43]
	v_mfma_f32_16x16x32_bf16 v[32:35], v[204:207], v[180:183], v[32:35]
	v_mfma_f32_16x16x32_bf16 v[24:27], v[212:215], v[180:183], v[24:27]
	v_mfma_f32_16x16x32_bf16 v[16:19], v[204:207], v[188:191], v[16:19]
	v_mfma_f32_16x16x32_bf16 v[8:11], v[212:215], v[188:191], v[8:11]
	v_mfma_f32_16x16x32_bf16 v[4:7], v[204:207], v[196:199], v[4:7]
	v_mfma_f32_16x16x32_bf16 v[0:3], v[212:215], v[196:199], v[0:3]
	s_setprio 0
	s_add_i32 s69, s69, 2
	s_add_u32 s50, s50, 0x100
	s_addc_u32 s51, s51, 0
	s_add_u32 s67, s67, 0x100
	s_addc_u32 s68, s68, 0
	s_cmp_gt_u32 s69, 29
	s_barrier
	s_cbranch_scc0 .LBB0_673
; #define PG8_WAIT_V(n) asm volatile("s_waitcnt vmcnt(" #n ")" ::: "memory")
; #define PG8_BAR __builtin_amdgcn_s_barrier()
; __device__ __forceinline__ u32x4 pack8(f32x4 v0, f32x4 v1) { u32x4 w; w.x = cvt_pk_bf16(v0[0], v0[1]); w.y = cvt_pk_bf16(v0[2], v0[3]); w.z = cvt_pk_bf16(v1[0], v1[1]); w.w = cvt_pk_bf16(v1[2], v1[3]); return w; }
; template <class Epi>
; __device__ __forceinline__ void gemm_phase(LAS unsigned char* lds, const Gemm g, const StaticOrder& S, const Epi& E) {
;     ...
;     PG8_WAIT_V(0);
;     if (wr == 0) PG8_BAR;
;     PG8_BAR;
;     __device__ __forceinline__ void operator()(const f32x4 (&acc)[2][2][4][2], const Unit& u, int wr, int wc, int fr, int fq) const {
;         const int row0 = u.pm * BM + wr * 64 + fr, col0 = u.pn * BM + wc * 32 + 8 * fq;
; #pragma unroll
;         for (int ai = 0; ai < 2; ++ai)
; #pragma unroll
;             for (int m = 0; m < 4; ++m) { bf16_t* rowp = O + (size_t)(row0 + ai * HALF + m * 16) * ldc + col0;
; #pragma unroll
;                 for (int bj = 0; bj < 2; ++bj) *(u32x4*)(rowp + bj * HALF) = pack8(acc[ai][bj][m][0], acc[ai][bj][m][1]); }
;     }
	v_lshl_add_u32 v148, s48, 8, v142
	v_lshl_or_b32 v140, s64, 8, v144
	v_ashrrev_i32_e32 v149, 31, v148
	v_ashrrev_i32_e32 v141, 31, v140
	v_lshlrev_b64 v[150:151], 12, v[148:149]
	v_lshl_add_u64 v[150:151], s[24:25], 0, v[150:151]
	v_lshlrev_b64 v[152:153], 1, v[140:141]
	v_lshl_add_u64 v[140:141], v[150:151], 0, v[152:153]
	v_cvt_pk_bf16_f32 v124, v124, v125
	v_cvt_pk_bf16_f32 v125, v126, v127
	v_cvt_pk_bf16_f32 v126, v120, v121
	v_cvt_pk_bf16_f32 v127, v122, v123
	global_store_dwordx4 v[140:141], v[124:127], off
	v_cvt_pk_bf16_f32 v116, v116, v117
	v_cvt_pk_bf16_f32 v117, v118, v119
	v_cvt_pk_bf16_f32 v118, v108, v109
	v_or_b32_e32 v108, 16, v148
	v_ashrrev_i32_e32 v109, 31, v108
	v_lshlrev_b64 v[108:109], 12, v[108:109]
	v_lshl_add_u64 v[108:109], s[24:25], 0, v[108:109]
	v_cvt_pk_bf16_f32 v119, v110, v111
	global_store_dwordx4 v[140:141], v[116:119], off offset:256
	s_mov_b32 s64, s40
	s_mov_b32 s48, s42
	v_lshl_add_u64 v[116:117], v[108:109], 0, v[152:153]
	v_cvt_pk_bf16_f32 v108, v112, v113
	v_cvt_pk_bf16_f32 v109, v114, v115
	v_cvt_pk_bf16_f32 v110, v104, v105
	v_cvt_pk_bf16_f32 v111, v106, v107
	global_store_dwordx4 v[116:117], v[108:111], off
	v_cvt_pk_bf16_f32 v100, v100, v101
	v_cvt_pk_bf16_f32 v101, v102, v103
	v_cvt_pk_bf16_f32 v102, v92, v93
	v_or_b32_e32 v92, 32, v148
	v_ashrrev_i32_e32 v93, 31, v92
	v_lshlrev_b64 v[92:93], 12, v[92:93]
	v_lshl_add_u64 v[92:93], s[24:25], 0, v[92:93]
	v_cvt_pk_bf16_f32 v103, v94, v95
	global_store_dwordx4 v[116:117], v[100:103], off offset:256
	s_mov_b64 s[52:53], s[46:47]
	s_mov_b64 s[50:51], s[44:45]
	v_lshl_add_u64 v[100:101], v[92:93], 0, v[152:153]
	v_cvt_pk_bf16_f32 v92, v96, v97
	v_cvt_pk_bf16_f32 v93, v98, v99
	v_cvt_pk_bf16_f32 v94, v88, v89
	v_cvt_pk_bf16_f32 v95, v90, v91
	global_store_dwordx4 v[100:101], v[92:95], off
	v_cvt_pk_bf16_f32 v84, v84, v85
	v_cvt_pk_bf16_f32 v85, v86, v87
	v_cvt_pk_bf16_f32 v86, v76, v77
	v_or_b32_e32 v76, 48, v148
	v_ashrrev_i32_e32 v77, 31, v76
	v_lshlrev_b64 v[76:77], 12, v[76:77]
	v_lshl_add_u64 v[76:77], s[24:25], 0, v[76:77]
	v_cvt_pk_bf16_f32 v87, v78, v79
	global_store_dwordx4 v[100:101], v[84:87], off offset:256
	s_nop 1
	v_lshl_add_u64 v[84:85], v[76:77], 0, v[152:153]
	v_cvt_pk_bf16_f32 v76, v80, v81
	v_cvt_pk_bf16_f32 v77, v82, v83
	v_cvt_pk_bf16_f32 v78, v72, v73
	v_cvt_pk_bf16_f32 v79, v74, v75
	global_store_dwordx4 v[84:85], v[76:79], off
	v_cvt_pk_bf16_f32 v68, v68, v69
	v_cvt_pk_bf16_f32 v69, v70, v71
	v_cvt_pk_bf16_f32 v70, v64, v65
	v_cvt_pk_bf16_f32 v71, v66, v67
	global_store_dwordx4 v[84:85], v[68:71], off offset:256
	v_cvt_pk_bf16_f32 v60, v60, v61
	v_cvt_pk_bf16_f32 v61, v62, v63
	v_cvt_pk_bf16_f32 v62, v56, v57
	v_add_co_u32_e32 v56, vcc, s60, v140
	v_lshl_add_u64 v[64:65], v[140:141], 0, s[2:3]
	s_nop 0
	v_addc_co_u32_e32 v57, vcc, 0, v141, vcc
	v_cvt_pk_bf16_f32 v63, v58, v59
	global_store_dwordx4 v[56:57], v[60:63], off
	v_cvt_pk_bf16_f32 v48, v48, v49
	v_cvt_pk_bf16_f32 v49, v50, v51
	v_cvt_pk_bf16_f32 v50, v40, v41
	v_cvt_pk_bf16_f32 v51, v42, v43
	global_store_dwordx4 v[64:65], v[48:51], off offset:256
	v_cvt_pk_bf16_f32 v40, v52, v53
	v_cvt_pk_bf16_f32 v41, v54, v55
	v_cvt_pk_bf16_f32 v42, v44, v45
	v_add_co_u32_e32 v44, vcc, s61, v140
	s_nop 0
	v_lshl_add_u64 v[48:49], v[140:141], 0, s[8:9]
	v_addc_co_u32_e32 v45, vcc, 0, v141, vcc
	v_cvt_pk_bf16_f32 v43, v46, v47
	global_store_dwordx4 v[44:45], v[40:43], off
	v_cvt_pk_bf16_f32 v32, v32, v33
	v_cvt_pk_bf16_f32 v33, v34, v35
	v_cvt_pk_bf16_f32 v34, v24, v25
	v_cvt_pk_bf16_f32 v35, v26, v27
	global_store_dwordx4 v[48:49], v[32:35], off offset:256
	v_cvt_pk_bf16_f32 v24, v36, v37
	v_cvt_pk_bf16_f32 v25, v38, v39
	v_cvt_pk_bf16_f32 v26, v28, v29
	v_add_co_u32_e32 v28, vcc, s62, v140
	s_nop 0
	v_lshl_add_u64 v[32:33], v[140:141], 0, s[30:31]
	v_addc_co_u32_e32 v29, vcc, 0, v141, vcc
	v_cvt_pk_bf16_f32 v27, v30, v31
	global_store_dwordx4 v[28:29], v[24:27], off
	v_cvt_pk_bf16_f32 v16, v16, v17
	v_cvt_pk_bf16_f32 v17, v18, v19
	v_cvt_pk_bf16_f32 v18, v8, v9
	v_cvt_pk_bf16_f32 v19, v10, v11
	global_store_dwordx4 v[32:33], v[16:19], off offset:256
	v_cvt_pk_bf16_f32 v8, v20, v21
	v_cvt_pk_bf16_f32 v9, v22, v23
	v_cvt_pk_bf16_f32 v10, v12, v13
	v_add_co_u32_e32 v12, vcc, s63, v140
	s_nop 0
	v_lshl_add_u64 v[16:17], v[140:141], 0, s[34:35]
	v_addc_co_u32_e32 v13, vcc, 0, v141, vcc
	s_and_b64 vcc, exec, s[38:39]
	v_cvt_pk_bf16_f32 v11, v14, v15
	global_store_dwordx4 v[12:13], v[8:11], off
	v_cvt_pk_bf16_f32 v4, v4, v5
	v_cvt_pk_bf16_f32 v5, v6, v7
	v_cvt_pk_bf16_f32 v6, v0, v1
	v_cvt_pk_bf16_f32 v7, v2, v3
	global_store_dwordx4 v[16:17], v[4:7], off offset:256
	s_cbranch_vccz .LBB0_670
	s_waitcnt vmcnt(0)
	s_cmpk_gt_u32 s10, 0xff
	v_readlane_b32 s62, v232, 20
	v_readlane_b32 s61, v232, 21
	s_cbranch_scc1 .LBB0_677
	s_barrier

; #define PG8_STAGE(bufoff, gbase, voff) do { _Pragma("unroll") for (int _i = 0; _i < 2; ++_i) \
;         __builtin_amdgcn_global_load_lds((const unsigned*)((const char*)(gbase) + (voff)[_i]), (LAS unsigned*)(lds + (bufoff) + ldsw + _i * 8192), 16, 0, 0); } while (0)
; #define PG8_LDA(dst, b, h) do { _Pragma("unroll") for (int m = 0; m < 4; ++m) _Pragma("unroll") for (int k = 0; k < 2; ++k) dst[m][k] = *(const LAS bf16x8*)(lds + PG8_SA(b, h) + aoff + m * 2048 + k * 1024); } while (0)
; #define PG8_LDB(dst, b, h) do { _Pragma("unroll") for (int n = 0; n < 2; ++n) _Pragma("unroll") for (int k = 0; k < 2; ++k) dst[n][k] = *(const LAS bf16x8*)(lds + PG8_SB(b, h) + boff + n * 2048 + k * 1024); } while (0)
; #define PG8_MMA(ai, bj, At, Bt) do { __builtin_amdgcn_s_setprio(1); _Pragma("unroll") for (int m = 0; m < 4; ++m) _Pragma("unroll") for (int n = 0; n < 2; ++n) _Pragma("unroll") for (int k = 0; k < 2; ++k) \
;         acc[ai][bj][m][n] = __builtin_amdgcn_mfma_f32_16x16x32_bf16(Bt[n][k], At[m][k], acc[ai][bj][m][n], 0, 0, 0); __builtin_amdgcn_s_setprio(0); } while (0)
; #define PG8_WAIT_V(n) asm volatile("s_waitcnt vmcnt(" #n ")" ::: "memory")
; #define PG8_WAIT_L(n) asm volatile("s_waitcnt lgkmcnt(" #n ")" ::: "memory")
; #define PG8_BAR __builtin_amdgcn_s_barrier()
; #define PG8_SCHED __builtin_amdgcn_sched_barrier(0)
; template <class Epi>
; __device__ __forceinline__ void gemm_phase(LAS unsigned char* lds, const Gemm g, const StaticOrder& S, const Epi& E) {
;     ...
;             PG8_LDB(B0, 0, 0); PG8_SCHED; PG8_LDA(At, 0, 0); PG8_STAGE(PG8_SA(1, 1), a1 + hstep, voffA);
;             PG8_WAIT_L(8); PG8_BAR; PG8_WAIT_L(0); PG8_MMA(0, 0, At, B0); PG8_BAR; PG8_SCHED;
;             PG8_LDB(B1, 0, 1); PG8_STAGE(PG8_SB(0, 0), b2, voffB);
;             PG8_BAR; PG8_WAIT_L(0); PG8_MMA(0, 1, At, B1); PG8_BAR;
;             PG8_LDA(At, 0, 1); PG8_STAGE(PG8_SA(0, 0), a2, voffA);
;             PG8_BAR; PG8_WAIT_L(0); PG8_MMA(1, 0, At, B0); PG8_BAR; PG8_SCHED;
;             PG8_STAGE(PG8_SB(0, 1), b2 + hstep, voffB);
;             PG8_WAIT_V(6); PG8_BAR; PG8_MMA(1, 1, At, B1); PG8_BAR;
.LBB0_796:
	ds_read_b128 v[144:147], v155
	ds_read_b128 v[148:151], v155 offset:1024
	ds_read_b128 v[160:163], v155 offset:2048
	ds_read_b128 v[164:167], v155 offset:3072
	s_add_u32 s42, s40, 0xfff80080
	s_addc_u32 s43, s41, -1
	s_cmp_eq_u32 s58, 28
	s_cselect_b32 s45, s31, s43
	s_cselect_b32 s44, s54, s42
	s_cselect_b32 s43, s9, s57
	s_cselect_b32 s42, s55, s56
	s_add_i32 m0, s27, 0xc000
	ds_read_b128 v[168:171], v156
	ds_read_b128 v[172:175], v156 offset:1024
	ds_read_b128 v[176:179], v156 offset:2048
	ds_read_b128 v[180:183], v156 offset:3072
	ds_read_b128 v[184:187], v156 offset:4096
	ds_read_b128 v[188:191], v156 offset:5120
	ds_read_b128 v[192:195], v156 offset:6144
	ds_read_b128 v[196:199], v156 offset:7168
	global_load_lds_dwordx4 v136, s[40:41]
	s_add_i32 m0, s27, 0xe000
	s_nop 0
	global_load_lds_dwordx4 v138, s[40:41]
	s_waitcnt lgkmcnt(8)
	s_barrier
	s_waitcnt lgkmcnt(0)
	s_setprio 1
	s_waitcnt lgkmcnt(0)
	v_mfma_f32_16x16x32_bf16 v[124:127], v[144:147], v[168:171], v[124:127]
	v_mfma_f32_16x16x32_bf16 v[120:123], v[160:163], v[168:171], v[120:123]
	v_mfma_f32_16x16x32_bf16 v[108:111], v[144:147], v[176:179], v[108:111]
	v_mfma_f32_16x16x32_bf16 v[104:107], v[160:163], v[176:179], v[104:107]
	v_mfma_f32_16x16x32_bf16 v[92:95], v[144:147], v[184:187], v[92:95]
	v_mfma_f32_16x16x32_bf16 v[88:91], v[160:163], v[184:187], v[88:91]
	v_mfma_f32_16x16x32_bf16 v[76:79], v[144:147], v[192:195], v[76:79]
	v_mfma_f32_16x16x32_bf16 v[72:75], v[160:163], v[192:195], v[72:75]
	v_mfma_f32_16x16x32_bf16 v[124:127], v[148:151], v[172:175], v[124:127]
	v_mfma_f32_16x16x32_bf16 v[120:123], v[164:167], v[172:175], v[120:123]
	v_mfma_f32_16x16x32_bf16 v[108:111], v[148:151], v[180:183], v[108:111]
	v_mfma_f32_16x16x32_bf16 v[104:107], v[164:167], v[180:183], v[104:107]
	v_mfma_f32_16x16x32_bf16 v[92:95], v[148:151], v[188:191], v[92:95]
	v_mfma_f32_16x16x32_bf16 v[88:91], v[164:167], v[188:191], v[88:91]
	v_mfma_f32_16x16x32_bf16 v[76:79], v[148:151], v[196:199], v[76:79]
	v_mfma_f32_16x16x32_bf16 v[72:75], v[164:167], v[196:199], v[72:75]
	s_setprio 0
	s_barrier
	s_add_i32 s59, s50, s23
	s_add_u32 s98, s42, s2
	s_addc_u32 s99, s43, s3
	s_mov_b32 m0, s59
	ds_read_b128 v[200:203], v157
	ds_read_b128 v[204:207], v157 offset:1024
	ds_read_b128 v[208:211], v157 offset:2048
	ds_read_b128 v[212:215], v157 offset:3072
	global_load_lds_dwordx4 v132, s[42:43]
	s_add_i32 m0, s59, 0x2000
	s_nop 0
	global_load_lds_dwordx4 v128, s[42:43]
	s_barrier
	s_waitcnt lgkmcnt(0)
	s_setprio 1
	s_waitcnt lgkmcnt(0)
	v_mfma_f32_16x16x32_bf16 v[116:119], v[200:203], v[168:171], v[116:119]
	v_mfma_f32_16x16x32_bf16 v[112:115], v[208:211], v[168:171], v[112:115]
	v_mfma_f32_16x16x32_bf16 v[100:103], v[200:203], v[176:179], v[100:103]
	v_mfma_f32_16x16x32_bf16 v[96:99], v[208:211], v[176:179], v[96:99]
	v_mfma_f32_16x16x32_bf16 v[84:87], v[200:203], v[184:187], v[84:87]
	v_mfma_f32_16x16x32_bf16 v[80:83], v[208:211], v[184:187], v[80:83]
	v_mfma_f32_16x16x32_bf16 v[68:71], v[200:203], v[192:195], v[68:71]
	v_mfma_f32_16x16x32_bf16 v[64:67], v[208:211], v[192:195], v[64:67]
	v_mfma_f32_16x16x32_bf16 v[116:119], v[204:207], v[172:175], v[116:119]
	v_mfma_f32_16x16x32_bf16 v[112:115], v[212:215], v[172:175], v[112:115]
	v_mfma_f32_16x16x32_bf16 v[100:103], v[204:207], v[180:183], v[100:103]
	v_mfma_f32_16x16x32_bf16 v[96:99], v[212:215], v[180:183], v[96:99]
	v_mfma_f32_16x16x32_bf16 v[84:87], v[204:207], v[188:191], v[84:87]
	v_mfma_f32_16x16x32_bf16 v[80:83], v[212:215], v[188:191], v[80:83]
	v_mfma_f32_16x16x32_bf16 v[68:71], v[204:207], v[196:199], v[68:71]
	v_mfma_f32_16x16x32_bf16 v[64:67], v[212:215], v[196:199], v[64:67]
	s_setprio 0
	s_mov_b32 m0, s27
	s_add_u32 s100, s44, s2
	s_addc_u32 s101, s45, s3
	s_barrier
	ds_read_b128 v[168:171], v156 offset:16384
	ds_read_b128 v[172:175], v156 offset:17408
	ds_read_b128 v[176:179], v156 offset:18432
	ds_read_b128 v[180:183], v156 offset:19456
	ds_read_b128 v[184:187], v156 offset:20480
	ds_read_b128 v[188:191], v156 offset:21504
	ds_read_b128 v[192:195], v156 offset:22528
	ds_read_b128 v[196:199], v156 offset:23552
	global_load_lds_dwordx4 v134, s[44:45]
	s_mov_b32 m0, s28
	s_nop 0
	global_load_lds_dwordx4 v130, s[44:45]
	s_barrier
	s_waitcnt lgkmcnt(0)
	s_setprio 1
	s_waitcnt lgkmcnt(0)
	v_mfma_f32_16x16x32_bf16 v[60:63], v[144:147], v[168:171], v[60:63]
	v_mfma_f32_16x16x32_bf16 v[56:59], v[160:163], v[168:171], v[56:59]
	v_mfma_f32_16x16x32_bf16 v[44:47], v[144:147], v[176:179], v[44:47]
	v_mfma_f32_16x16x32_bf16 v[40:43], v[160:163], v[176:179], v[40:43]
	v_mfma_f32_16x16x32_bf16 v[28:31], v[144:147], v[184:187], v[28:31]
	v_mfma_f32_16x16x32_bf16 v[24:27], v[160:163], v[184:187], v[24:27]
	v_mfma_f32_16x16x32_bf16 v[12:15], v[144:147], v[192:195], v[12:15]
	v_mfma_f32_16x16x32_bf16 v[8:11], v[160:163], v[192:195], v[8:11]
	v_mfma_f32_16x16x32_bf16 v[60:63], v[148:151], v[172:175], v[60:63]
	v_mfma_f32_16x16x32_bf16 v[56:59], v[164:167], v[172:175], v[56:59]
	v_mfma_f32_16x16x32_bf16 v[44:47], v[148:151], v[180:183], v[44:47]
	v_mfma_f32_16x16x32_bf16 v[40:43], v[164:167], v[180:183], v[40:43]
	v_mfma_f32_16x16x32_bf16 v[28:31], v[148:151], v[188:191], v[28:31]
	v_mfma_f32_16x16x32_bf16 v[24:27], v[164:167], v[188:191], v[24:27]
	v_mfma_f32_16x16x32_bf16 v[12:15], v[148:151], v[196:199], v[12:15]
	v_mfma_f32_16x16x32_bf16 v[8:11], v[164:167], v[196:199], v[8:11]
	s_setprio 0
	s_barrier
	s_add_u32 s60, s42, 0x80000
	s_addc_u32 s61, s43, 0
	s_add_i32 s59, s51, s23
	s_mov_b32 m0, s59
	s_nop 0
	global_load_lds_dwordx4 v132, s[60:61]
	s_add_i32 m0, s59, 0x2000
	s_nop 0
	global_load_lds_dwordx4 v128, s[60:61]
	s_waitcnt vmcnt(6)
	s_barrier
; #define PG8_STAGE(bufoff, gbase, voff) do { _Pragma("unroll") for (int _i = 0; _i < 2; ++_i) \
;         __builtin_amdgcn_global_load_lds((const unsigned*)((const char*)(gbase) + (voff)[_i]), (LAS unsigned*)(lds + (bufoff) + ldsw + _i * 8192), 16, 0, 0); } while (0)
; #define PG8_LDA(dst, b, h) do { _Pragma("unroll") for (int m = 0; m < 4; ++m) _Pragma("unroll") for (int k = 0; k < 2; ++k) dst[m][k] = *(const LAS bf16x8*)(lds + PG8_SA(b, h) + aoff + m * 2048 + k * 1024); } while (0)
; #define PG8_LDB(dst, b, h) do { _Pragma("unroll") for (int n = 0; n < 2; ++n) _Pragma("unroll") for (int k = 0; k < 2; ++k) dst[n][k] = *(const LAS bf16x8*)(lds + PG8_SB(b, h) + boff + n * 2048 + k * 1024); } while (0)
; #define PG8_MMA(ai, bj, At, Bt) do { __builtin_amdgcn_s_setprio(1); _Pragma("unroll") for (int m = 0; m < 4; ++m) _Pragma("unroll") for (int n = 0; n < 2; ++n) _Pragma("unroll") for (int k = 0; k < 2; ++k) \
;         acc[ai][bj][m][n] = __builtin_amdgcn_mfma_f32_16x16x32_bf16(Bt[n][k], At[m][k], acc[ai][bj][m][n], 0, 0, 0); __builtin_amdgcn_s_setprio(0); } while (0)
; #define PG8_WAIT_V(n) asm volatile("s_waitcnt vmcnt(" #n ")" ::: "memory")
; #define PG8_WAIT_L(n) asm volatile("s_waitcnt lgkmcnt(" #n ")" ::: "memory")
; #define PG8_BAR __builtin_amdgcn_s_barrier()
; #define PG8_SCHED __builtin_amdgcn_sched_barrier(0)
; template <class Epi>
; __device__ __forceinline__ void gemm_phase(LAS unsigned char* lds, const Gemm g, const StaticOrder& S, const Epi& E) {
;     ...
;             PG8_WAIT_V(6); PG8_BAR; PG8_MMA(1, 1, At, B1); PG8_BAR;
;             PG8_LDB(B0, 1, 0); PG8_SCHED; PG8_LDA(At, 1, 0); PG8_STAGE(PG8_SA(0, 1), a2 + hstep, voffA);
;             PG8_WAIT_L(8); PG8_BAR; PG8_WAIT_L(0); PG8_MMA(0, 0, At, B0); PG8_BAR; PG8_SCHED;
;             PG8_LDB(B1, 1, 1); PG8_STAGE(PG8_SB(1, 0), b3, voffB);
;             PG8_BAR; PG8_WAIT_L(0); PG8_MMA(0, 1, At, B1); PG8_BAR;
;             PG8_LDA(At, 1, 1); PG8_STAGE(PG8_SA(1, 0), a3, voffA);
;             PG8_BAR; PG8_WAIT_L(0); PG8_MMA(1, 0, At, B0); PG8_BAR; PG8_SCHED;
;             PG8_STAGE(PG8_SB(1, 1), b3 + hstep, voffB);
	s_setprio 1
	v_mfma_f32_16x16x32_bf16 v[52:55], v[200:203], v[168:171], v[52:55]
	v_mfma_f32_16x16x32_bf16 v[48:51], v[208:211], v[168:171], v[48:51]
	v_mfma_f32_16x16x32_bf16 v[36:39], v[200:203], v[176:179], v[36:39]
	v_mfma_f32_16x16x32_bf16 v[32:35], v[208:211], v[176:179], v[32:35]
	v_mfma_f32_16x16x32_bf16 v[20:23], v[200:203], v[184:187], v[20:23]
	v_mfma_f32_16x16x32_bf16 v[16:19], v[208:211], v[184:187], v[16:19]
	v_mfma_f32_16x16x32_bf16 v[4:7], v[200:203], v[192:195], v[4:7]
	v_mfma_f32_16x16x32_bf16 v[0:3], v[208:211], v[192:195], v[0:3]
	v_mfma_f32_16x16x32_bf16 v[52:55], v[204:207], v[172:175], v[52:55]
	v_mfma_f32_16x16x32_bf16 v[48:51], v[212:215], v[172:175], v[48:51]
	v_mfma_f32_16x16x32_bf16 v[36:39], v[204:207], v[180:183], v[36:39]
	v_mfma_f32_16x16x32_bf16 v[32:35], v[212:215], v[180:183], v[32:35]
	v_mfma_f32_16x16x32_bf16 v[20:23], v[204:207], v[188:191], v[20:23]
	v_mfma_f32_16x16x32_bf16 v[16:19], v[212:215], v[188:191], v[16:19]
	v_mfma_f32_16x16x32_bf16 v[4:7], v[204:207], v[196:199], v[4:7]
	v_mfma_f32_16x16x32_bf16 v[0:3], v[212:215], v[196:199], v[0:3]
	s_setprio 0
	s_add_i32 s59, 0, 0x18000
	v_add_u32_e32 v164, s59, v153
	s_barrier
	ds_read_b128 v[144:147], v164
	ds_read_b128 v[148:151], v164 offset:1024
	ds_read_b128 v[160:163], v164 offset:2048
	ds_read_b128 v[164:167], v164 offset:3072
	s_add_u32 s44, s44, 0x80000
	s_addc_u32 s45, s45, 0
	s_mov_b32 m0, s29
	ds_read_b128 v[168:171], v156 offset:32768
	ds_read_b128 v[172:175], v156 offset:33792
	ds_read_b128 v[176:179], v156 offset:34816
	ds_read_b128 v[180:183], v156 offset:35840
	ds_read_b128 v[184:187], v156 offset:36864
	ds_read_b128 v[188:191], v156 offset:37888
	ds_read_b128 v[192:195], v156 offset:38912
	ds_read_b128 v[196:199], v156 offset:39936
	global_load_lds_dwordx4 v134, s[44:45]
	s_mov_b32 m0, s33
	s_nop 0
	global_load_lds_dwordx4 v130, s[44:45]
	s_waitcnt lgkmcnt(8)
	s_barrier
	s_waitcnt lgkmcnt(0)
	s_setprio 1
	s_waitcnt lgkmcnt(0)
	v_mfma_f32_16x16x32_bf16 v[124:127], v[144:147], v[168:171], v[124:127]
	v_mfma_f32_16x16x32_bf16 v[120:123], v[160:163], v[168:171], v[120:123]
	v_mfma_f32_16x16x32_bf16 v[108:111], v[144:147], v[176:179], v[108:111]
	v_mfma_f32_16x16x32_bf16 v[104:107], v[160:163], v[176:179], v[104:107]
	v_mfma_f32_16x16x32_bf16 v[92:95], v[144:147], v[184:187], v[92:95]
	v_mfma_f32_16x16x32_bf16 v[88:91], v[160:163], v[184:187], v[88:91]
	v_mfma_f32_16x16x32_bf16 v[76:79], v[144:147], v[192:195], v[76:79]
	v_mfma_f32_16x16x32_bf16 v[72:75], v[160:163], v[192:195], v[72:75]
	v_mfma_f32_16x16x32_bf16 v[124:127], v[148:151], v[172:175], v[124:127]
	v_mfma_f32_16x16x32_bf16 v[120:123], v[164:167], v[172:175], v[120:123]
	v_mfma_f32_16x16x32_bf16 v[108:111], v[148:151], v[180:183], v[108:111]
	v_mfma_f32_16x16x32_bf16 v[104:107], v[164:167], v[180:183], v[104:107]
	v_mfma_f32_16x16x32_bf16 v[92:95], v[148:151], v[188:191], v[92:95]
	v_mfma_f32_16x16x32_bf16 v[88:91], v[164:167], v[188:191], v[88:91]
	v_mfma_f32_16x16x32_bf16 v[76:79], v[148:151], v[196:199], v[76:79]
	v_mfma_f32_16x16x32_bf16 v[72:75], v[164:167], v[196:199], v[72:75]
	s_setprio 0
	s_barrier
	s_add_i32 s44, 0, 0x1c000
	s_add_i32 s45, s59, s23
	v_add_u32_e32 v212, s44, v153
	s_mov_b32 m0, s45
	ds_read_b128 v[200:203], v212
	ds_read_b128 v[204:207], v212 offset:1024
	ds_read_b128 v[208:211], v212 offset:2048
	ds_read_b128 v[212:215], v212 offset:3072
	global_load_lds_dwordx4 v132, s[98:99]
	s_add_i32 m0, s45, 0x2000
	s_nop 0
	global_load_lds_dwordx4 v128, s[98:99]
	s_barrier
	s_waitcnt lgkmcnt(0)
	s_setprio 1
	s_waitcnt lgkmcnt(0)
	v_mfma_f32_16x16x32_bf16 v[116:119], v[200:203], v[168:171], v[116:119]
	v_mfma_f32_16x16x32_bf16 v[112:115], v[208:211], v[168:171], v[112:115]
	v_mfma_f32_16x16x32_bf16 v[100:103], v[200:203], v[176:179], v[100:103]
	v_mfma_f32_16x16x32_bf16 v[96:99], v[208:211], v[176:179], v[96:99]
	v_mfma_f32_16x16x32_bf16 v[84:87], v[200:203], v[184:187], v[84:87]
	v_mfma_f32_16x16x32_bf16 v[80:83], v[208:211], v[184:187], v[80:83]
	v_mfma_f32_16x16x32_bf16 v[68:71], v[200:203], v[192:195], v[68:71]
	v_mfma_f32_16x16x32_bf16 v[64:67], v[208:211], v[192:195], v[64:67]
	v_mfma_f32_16x16x32_bf16 v[116:119], v[204:207], v[172:175], v[116:119]
	v_mfma_f32_16x16x32_bf16 v[112:115], v[212:215], v[172:175], v[112:115]
	v_mfma_f32_16x16x32_bf16 v[100:103], v[204:207], v[180:183], v[100:103]
	v_mfma_f32_16x16x32_bf16 v[96:99], v[212:215], v[180:183], v[96:99]
	v_mfma_f32_16x16x32_bf16 v[84:87], v[204:207], v[188:191], v[84:87]
	v_mfma_f32_16x16x32_bf16 v[80:83], v[212:215], v[188:191], v[80:83]
	v_mfma_f32_16x16x32_bf16 v[68:71], v[204:207], v[196:199], v[68:71]
	v_mfma_f32_16x16x32_bf16 v[64:67], v[212:215], v[196:199], v[64:67]
	s_setprio 0
	s_mov_b32 m0, s46
	s_barrier
	ds_read_b128 v[168:171], v156 offset:49152
	ds_read_b128 v[172:175], v156 offset:50176
	ds_read_b128 v[176:179], v156 offset:51200
	ds_read_b128 v[180:183], v156 offset:52224
	ds_read_b128 v[184:187], v156 offset:53248
	ds_read_b128 v[188:191], v156 offset:54272
	ds_read_b128 v[192:195], v156 offset:55296
	ds_read_b128 v[196:199], v156 offset:56320
	global_load_lds_dwordx4 v134, s[100:101]
	s_mov_b32 m0, s47
	s_nop 0
	global_load_lds_dwordx4 v130, s[100:101]
	s_barrier
; __device__ __forceinline__ float fast_rcp(float x) { return __builtin_amdgcn_rcpf(x); }
; __device__ __forceinline__ float fast_exp2(float x) { return __builtin_amdgcn_exp2f(x); }
; #define PG8_STAGE(bufoff, gbase, voff) do { _Pragma("unroll") for (int _i = 0; _i < 2; ++_i) \
;         __builtin_amdgcn_global_load_lds((const unsigned*)((const char*)(gbase) + (voff)[_i]), (LAS unsigned*)(lds + (bufoff) + ldsw + _i * 8192), 16, 0, 0); } while (0)
; #define PG8_LDA(dst, b, h) do { _Pragma("unroll") for (int m = 0; m < 4; ++m) _Pragma("unroll") for (int k = 0; k < 2; ++k) dst[m][k] = *(const LAS bf16x8*)(lds + PG8_SA(b, h) + aoff + m * 2048 + k * 1024); } while (0)
; #define PG8_MMA(ai, bj, At, Bt) do { __builtin_amdgcn_s_setprio(1); _Pragma("unroll") for (int m = 0; m < 4; ++m) _Pragma("unroll") for (int n = 0; n < 2; ++n) _Pragma("unroll") for (int k = 0; k < 2; ++k) \
;         acc[ai][bj][m][n] = __builtin_amdgcn_mfma_f32_16x16x32_bf16(Bt[n][k], At[m][k], acc[ai][bj][m][n], 0, 0, 0); __builtin_amdgcn_s_setprio(0); } while (0)
; #define PG8_WAIT_V(n) asm volatile("s_waitcnt vmcnt(" #n ")" ::: "memory")
; template <class Epi>
; __device__ __forceinline__ void gemm_phase(LAS unsigned char* lds, const Gemm g, const StaticOrder& S, const Epi& E) {
;     ...
;             PG8_BAR; PG8_WAIT_L(0); PG8_MMA(0, 1, At, B1); PG8_BAR;
;             PG8_LDA(At, 1, 1); PG8_STAGE(PG8_SA(1, 0), a3, voffA);
;             PG8_BAR; PG8_WAIT_L(0); PG8_MMA(1, 0, At, B0); PG8_BAR; PG8_SCHED;
;             PG8_STAGE(PG8_SB(1, 1), b3 + hstep, voffB);
;             PG8_WAIT_V(6); PG8_BAR; PG8_MMA(1, 1, At, B1); PG8_BAR;
;     __device__ __forceinline__ void operator()(const f32x4 (&acc)[2][2][4][2], const Unit& u, int wr, int wc, int fr, int fq) const {
;     ...
;             for (int m = 0; m < 4; ++m) { bf16_t* rowp = O + (size_t)(row0 + ai * HALF + m * 16) * DFF + col0;
;                 const float r = rs[row0 + ai * HALF + m * 16], r2 = r * r;
;                 f32x4 h0, h1;
; #pragma unroll
;                 for (int j = 0; j < 4; ++j) {
;                     const float g0 = acc[ai][0][m][0][j], g1 = acc[ai][0][m][1][j];
;                     h0[j] = g0 * r2 * fast_rcp(1.0f + fast_exp2(g0 * (-LOG2E * r))) * acc[ai][1][m][0][j];
;                     h1[j] = g1 * r2 * fast_rcp(1.0f + fast_exp2(g1 * (-LOG2E * r))) * acc[ai][1][m][1][j]; }
;                 *(u32x4*)rowp = pack8(h0, h1); }
	s_waitcnt lgkmcnt(0)
	s_setprio 1
	s_waitcnt lgkmcnt(0)
	v_mfma_f32_16x16x32_bf16 v[60:63], v[144:147], v[168:171], v[60:63]
	v_mfma_f32_16x16x32_bf16 v[56:59], v[160:163], v[168:171], v[56:59]
	v_mfma_f32_16x16x32_bf16 v[44:47], v[144:147], v[176:179], v[44:47]
	v_mfma_f32_16x16x32_bf16 v[40:43], v[160:163], v[176:179], v[40:43]
	v_mfma_f32_16x16x32_bf16 v[28:31], v[144:147], v[184:187], v[28:31]
	v_mfma_f32_16x16x32_bf16 v[24:27], v[160:163], v[184:187], v[24:27]
	v_mfma_f32_16x16x32_bf16 v[12:15], v[144:147], v[192:195], v[12:15]
	v_mfma_f32_16x16x32_bf16 v[8:11], v[160:163], v[192:195], v[8:11]
	v_mfma_f32_16x16x32_bf16 v[60:63], v[148:151], v[172:175], v[60:63]
	v_mfma_f32_16x16x32_bf16 v[56:59], v[164:167], v[172:175], v[56:59]
	v_mfma_f32_16x16x32_bf16 v[44:47], v[148:151], v[180:183], v[44:47]
	v_mfma_f32_16x16x32_bf16 v[40:43], v[164:167], v[180:183], v[40:43]
	v_mfma_f32_16x16x32_bf16 v[28:31], v[148:151], v[188:191], v[28:31]
	v_mfma_f32_16x16x32_bf16 v[24:27], v[164:167], v[188:191], v[24:27]
	v_mfma_f32_16x16x32_bf16 v[12:15], v[148:151], v[196:199], v[12:15]
	v_mfma_f32_16x16x32_bf16 v[8:11], v[164:167], v[196:199], v[8:11]
	s_setprio 0
	s_barrier
	s_add_u32 s42, s42, 0x80080
	s_addc_u32 s43, s43, 0
	s_add_i32 s44, s44, s23
	s_mov_b32 m0, s44
	s_nop 0
	global_load_lds_dwordx4 v132, s[42:43]
	s_add_i32 m0, s44, 0x2000
	s_nop 0
	global_load_lds_dwordx4 v128, s[42:43]
	s_waitcnt vmcnt(6)
	s_barrier
	s_setprio 1
	v_mfma_f32_16x16x32_bf16 v[52:55], v[200:203], v[168:171], v[52:55]
	v_mfma_f32_16x16x32_bf16 v[48:51], v[208:211], v[168:171], v[48:51]
	v_mfma_f32_16x16x32_bf16 v[36:39], v[200:203], v[176:179], v[36:39]
	v_mfma_f32_16x16x32_bf16 v[32:35], v[208:211], v[176:179], v[32:35]
	v_mfma_f32_16x16x32_bf16 v[20:23], v[200:203], v[184:187], v[20:23]
	v_mfma_f32_16x16x32_bf16 v[16:19], v[208:211], v[184:187], v[16:19]
	v_mfma_f32_16x16x32_bf16 v[4:7], v[200:203], v[192:195], v[4:7]
	v_mfma_f32_16x16x32_bf16 v[0:3], v[208:211], v[192:195], v[0:3]
	v_mfma_f32_16x16x32_bf16 v[52:55], v[204:207], v[172:175], v[52:55]
	v_mfma_f32_16x16x32_bf16 v[48:51], v[212:215], v[172:175], v[48:51]
	v_mfma_f32_16x16x32_bf16 v[36:39], v[204:207], v[180:183], v[36:39]
	v_mfma_f32_16x16x32_bf16 v[32:35], v[212:215], v[180:183], v[32:35]
	v_mfma_f32_16x16x32_bf16 v[20:23], v[204:207], v[188:191], v[20:23]
	v_mfma_f32_16x16x32_bf16 v[16:19], v[212:215], v[188:191], v[16:19]
	v_mfma_f32_16x16x32_bf16 v[4:7], v[204:207], v[196:199], v[4:7]
	v_mfma_f32_16x16x32_bf16 v[0:3], v[212:215], v[196:199], v[0:3]
	s_setprio 0
	s_add_i32 s58, s58, 2
	s_add_u32 s40, s40, 0x100
	s_addc_u32 s41, s41, 0
	s_add_u32 s56, s56, 0x100
	s_addc_u32 s57, s57, 0
	s_cmp_gt_u32 s58, 29
	s_barrier
	s_cbranch_scc0 .LBB0_796
	v_lshl_add_u32 v144, s38, 8, v152
	v_ashrrev_i32_e32 v145, 31, v144
	v_lshl_add_u64 v[150:151], v[144:145], 2, s[14:15]
	v_mov_b32_e32 v145, v224
	v_mov_b32_e32 v204, v225
	v_mov_b32_e32 v205, v226
	v_mov_b32_e32 v206, v227
	v_mov_b32_e32 v207, v228
	v_mov_b32_e32 v208, v229
	v_mov_b32_e32 v209, v230
	v_mov_b32_e32 v210, v231
	v_lshl_or_b32 v148, s53, 7, v154
	v_mov_b64_e32 v[146:147], s[20:21]
	v_ashrrev_i32_e32 v149, 31, v148
	v_mad_i64_i32 v[160:161], s[40:41], v144, s52, v[146:147]
	v_lshlrev_b64 v[148:149], 1, v[148:149]
	v_lshl_add_u64 v[160:161], v[160:161], 0, v[148:149]
	s_and_b64 vcc, exec, s[6:7]
	s_mov_b32 s53, s8
	s_mov_b32 s38, s30
	s_mov_b64 s[42:43], s[36:37]
	v_mul_f32_e32 v162, v145, v145
	v_mul_f32_e32 v145, 0xbfb8aa3b, v145
	v_mul_f32_e32 v163, v124, v162
	v_mul_f32_e32 v164, v120, v162
	v_mul_f32_e32 v120, v120, v145
	v_mul_f32_e32 v165, v125, v162
	v_mul_f32_e32 v125, v125, v145
	v_mul_f32_e32 v166, v121, v162
	v_mul_f32_e32 v121, v121, v145
	v_mul_f32_e32 v167, v126, v162
	v_mul_f32_e32 v126, v126, v145
	v_mul_f32_e32 v168, v122, v162
	v_mul_f32_e32 v122, v122, v145
	v_mul_f32_e32 v169, v127, v162
	v_mul_f32_e32 v127, v127, v145
	v_mul_f32_e32 v162, v123, v162
	v_mul_f32_e32 v123, v123, v145
	v_mul_f32_e32 v124, v124, v145
	v_exp_f32_e32 v120, v120
	v_exp_f32_e32 v125, v125
	v_exp_f32_e32 v121, v121
	v_exp_f32_e32 v126, v126
	v_exp_f32_e32 v122, v122
	v_exp_f32_e32 v127, v127
	v_exp_f32_e32 v123, v123
	v_exp_f32_e32 v124, v124
	v_add_f32_e32 v120, 1.0, v120
	v_add_f32_e32 v125, 1.0, v125
	v_add_f32_e32 v121, 1.0, v121
	v_add_f32_e32 v126, 1.0, v126
	v_add_f32_e32 v122, 1.0, v122
	v_add_f32_e32 v127, 1.0, v127
	v_add_f32_e32 v123, 1.0, v123
	v_add_f32_e32 v124, 1.0, v124
	v_rcp_f32_e32 v120, v120
	v_rcp_f32_e32 v125, v125
	v_rcp_f32_e32 v121, v121
	v_rcp_f32_e32 v126, v126
	v_rcp_f32_e32 v122, v122
	v_rcp_f32_e32 v127, v127
	v_rcp_f32_e32 v123, v123
	v_rcp_f32_e32 v124, v124
	v_mul_f32_e32 v120, v164, v120
	v_mul_f32_e32 v125, v165, v125
	v_mul_f32_e32 v121, v166, v121
	v_mul_f32_e32 v126, v167, v126
	v_mul_f32_e32 v122, v168, v122
	v_mul_f32_e32 v127, v169, v127
	v_mul_f32_e32 v123, v162, v123
	v_mul_f32_e32 v124, v163, v124
	v_mul_f32_e32 v120, v112, v120
	v_mul_f32_e32 v112, v117, v125
	v_mul_f32_e32 v117, v113, v121
	v_mul_f32_e32 v113, v118, v126
	v_mul_f32_e32 v118, v114, v122
	v_mul_f32_e32 v114, v119, v127
	v_mul_f32_e32 v115, v115, v123
	v_mul_f32_e32 v116, v116, v124
	v_cvt_pk_bf16_f32 v112, v116, v112
	v_cvt_pk_bf16_f32 v113, v113, v114
	v_cvt_pk_bf16_f32 v114, v120, v117
	v_cvt_pk_bf16_f32 v115, v118, v115
	global_store_dwordx4 v[160:161], v[112:115], off
	s_nop 1
	v_mov_b32_e32 v114, v204
	s_nop 0
	v_or_b32_e32 v112, 16, v144
	v_mad_i64_i32 v[112:113], s[40:41], v112, s52, v[146:147]
	v_lshl_add_u64 v[112:113], v[112:113], 0, v[148:149]
	v_mul_f32_e32 v115, v114, v114
	v_mul_f32_e32 v114, 0xbfb8aa3b, v114
; __device__ __forceinline__ float fast_rcp(float x) { return __builtin_amdgcn_rcpf(x); }
; __device__ __forceinline__ float fast_exp2(float x) { return __builtin_amdgcn_exp2f(x); }
; __device__ __forceinline__ u32x4 pack8(f32x4 v0, f32x4 v1) { u32x4 w; w.x = cvt_pk_bf16(v0[0], v0[1]); w.y = cvt_pk_bf16(v0[2], v0[3]); w.z = cvt_pk_bf16(v1[0], v1[1]); w.w = cvt_pk_bf16(v1[2], v1[3]); return w; }
;     __device__ __forceinline__ void operator()(const f32x4 (&acc)[2][2][4][2], const Unit& u, int wr, int wc, int fr, int fq) const {
;     ...
;             for (int m = 0; m < 4; ++m) { bf16_t* rowp = O + (size_t)(row0 + ai * HALF + m * 16) * DFF + col0;
;                 const float r = rs[row0 + ai * HALF + m * 16], r2 = r * r;
;                 f32x4 h0, h1;
; #pragma unroll
;                 for (int j = 0; j < 4; ++j) {
;                     const float g0 = acc[ai][0][m][0][j], g1 = acc[ai][0][m][1][j];
;                     h0[j] = g0 * r2 * fast_rcp(1.0f + fast_exp2(g0 * (-LOG2E * r))) * acc[ai][1][m][0][j];
;                     h1[j] = g1 * r2 * fast_rcp(1.0f + fast_exp2(g1 * (-LOG2E * r))) * acc[ai][1][m][1][j]; }
;                 *(u32x4*)rowp = pack8(h0, h1); }
	v_mul_f32_e32 v116, v108, v115
	v_mul_f32_e32 v117, v104, v115
	v_mul_f32_e32 v104, v104, v114
	v_mul_f32_e32 v118, v109, v115
	v_mul_f32_e32 v109, v109, v114
	v_mul_f32_e32 v119, v105, v115
	v_mul_f32_e32 v105, v105, v114
	v_mul_f32_e32 v120, v110, v115
	v_mul_f32_e32 v110, v110, v114
	v_mul_f32_e32 v121, v106, v115
	v_mul_f32_e32 v106, v106, v114
	v_mul_f32_e32 v122, v111, v115
	v_mul_f32_e32 v111, v111, v114
	v_mul_f32_e32 v115, v107, v115
	v_mul_f32_e32 v107, v107, v114
	v_mul_f32_e32 v108, v108, v114
	v_exp_f32_e32 v104, v104
	v_exp_f32_e32 v109, v109
	v_exp_f32_e32 v105, v105
	v_exp_f32_e32 v110, v110
	v_exp_f32_e32 v106, v106
	v_exp_f32_e32 v111, v111
	v_exp_f32_e32 v107, v107
	v_exp_f32_e32 v108, v108
	v_add_f32_e32 v104, 1.0, v104
	v_add_f32_e32 v109, 1.0, v109
	v_add_f32_e32 v105, 1.0, v105
	v_add_f32_e32 v110, 1.0, v110
	v_add_f32_e32 v106, 1.0, v106
	v_add_f32_e32 v111, 1.0, v111
	v_add_f32_e32 v107, 1.0, v107
	v_add_f32_e32 v108, 1.0, v108
	v_rcp_f32_e32 v104, v104
	v_rcp_f32_e32 v109, v109
	v_rcp_f32_e32 v105, v105
	v_rcp_f32_e32 v110, v110
	v_rcp_f32_e32 v106, v106
	v_rcp_f32_e32 v111, v111
	v_rcp_f32_e32 v107, v107
	v_rcp_f32_e32 v108, v108
	v_mul_f32_e32 v104, v117, v104
	v_mul_f32_e32 v109, v118, v109
	v_mul_f32_e32 v105, v119, v105
	v_mul_f32_e32 v110, v120, v110
	v_mul_f32_e32 v106, v121, v106
	v_mul_f32_e32 v111, v122, v111
	v_mul_f32_e32 v107, v115, v107
	v_mul_f32_e32 v108, v116, v108
	v_mul_f32_e32 v104, v96, v104
	v_mul_f32_e32 v96, v101, v109
	v_mul_f32_e32 v101, v97, v105
	v_mul_f32_e32 v97, v102, v110
	v_mul_f32_e32 v102, v98, v106
	v_mul_f32_e32 v98, v103, v111
	v_mul_f32_e32 v99, v99, v107
	v_mul_f32_e32 v100, v100, v108
	v_cvt_pk_bf16_f32 v96, v100, v96
	v_cvt_pk_bf16_f32 v97, v97, v98
	v_cvt_pk_bf16_f32 v98, v104, v101
	v_cvt_pk_bf16_f32 v99, v102, v99
	global_store_dwordx4 v[112:113], v[96:99], off
	s_nop 1
	v_mov_b32_e32 v98, v205
	s_nop 0
	v_or_b32_e32 v96, 32, v144
	v_mad_i64_i32 v[96:97], s[40:41], v96, s52, v[146:147]
	v_lshl_add_u64 v[96:97], v[96:97], 0, v[148:149]
	v_mul_f32_e32 v99, v98, v98
	v_mul_f32_e32 v98, 0xbfb8aa3b, v98
	v_mul_f32_e32 v100, v92, v99
	v_mul_f32_e32 v101, v88, v99
	v_mul_f32_e32 v88, v88, v98
	v_mul_f32_e32 v102, v93, v99
	v_mul_f32_e32 v93, v93, v98
	v_mul_f32_e32 v103, v89, v99
	v_mul_f32_e32 v89, v89, v98
	v_mul_f32_e32 v104, v94, v99
	v_mul_f32_e32 v94, v94, v98
	v_mul_f32_e32 v105, v90, v99
	v_mul_f32_e32 v90, v90, v98
	v_mul_f32_e32 v106, v95, v99
	v_mul_f32_e32 v95, v95, v98
	v_mul_f32_e32 v99, v91, v99
	v_mul_f32_e32 v91, v91, v98
	v_mul_f32_e32 v92, v92, v98
	v_exp_f32_e32 v88, v88
	v_exp_f32_e32 v93, v93
	v_exp_f32_e32 v89, v89
	v_exp_f32_e32 v94, v94
	v_exp_f32_e32 v90, v90
	v_exp_f32_e32 v95, v95
	v_exp_f32_e32 v91, v91
	v_exp_f32_e32 v92, v92
	v_add_f32_e32 v88, 1.0, v88
	v_add_f32_e32 v93, 1.0, v93
	v_add_f32_e32 v89, 1.0, v89
	v_add_f32_e32 v94, 1.0, v94
	v_add_f32_e32 v90, 1.0, v90
	v_add_f32_e32 v95, 1.0, v95
	v_add_f32_e32 v91, 1.0, v91
	v_add_f32_e32 v92, 1.0, v92
	v_rcp_f32_e32 v88, v88
	v_rcp_f32_e32 v93, v93
	v_rcp_f32_e32 v89, v89
	v_rcp_f32_e32 v94, v94
	v_rcp_f32_e32 v90, v90
	v_rcp_f32_e32 v95, v95
	v_rcp_f32_e32 v91, v91
	v_rcp_f32_e32 v92, v92
	v_mul_f32_e32 v88, v101, v88
	v_mul_f32_e32 v93, v102, v93
	v_mul_f32_e32 v89, v103, v89
	v_mul_f32_e32 v94, v104, v94
	v_mul_f32_e32 v90, v105, v90
	v_mul_f32_e32 v95, v106, v95
	v_mul_f32_e32 v91, v99, v91
	v_mul_f32_e32 v92, v100, v92
	v_mul_f32_e32 v88, v80, v88
	v_mul_f32_e32 v80, v85, v93
	v_mul_f32_e32 v85, v81, v89
	v_mul_f32_e32 v81, v86, v94
	v_mul_f32_e32 v86, v82, v90
	v_mul_f32_e32 v82, v87, v95
	v_mul_f32_e32 v83, v83, v91
	v_mul_f32_e32 v84, v84, v92
	v_cvt_pk_bf16_f32 v80, v84, v80
	v_cvt_pk_bf16_f32 v81, v81, v82
	v_cvt_pk_bf16_f32 v82, v88, v85
	v_cvt_pk_bf16_f32 v83, v86, v83
	global_store_dwordx4 v[96:97], v[80:83], off
	s_nop 1
	v_mov_b32_e32 v82, v206
	s_nop 0
	v_or_b32_e32 v80, 48, v144
	v_mad_i64_i32 v[80:81], s[40:41], v80, s52, v[146:147]
	v_lshl_add_u64 v[80:81], v[80:81], 0, v[148:149]
	v_mul_f32_e32 v83, v82, v82
	v_mul_f32_e32 v82, 0xbfb8aa3b, v82
	v_mul_f32_e32 v84, v76, v83
	v_mul_f32_e32 v85, v72, v83
	v_mul_f32_e32 v72, v72, v82
	v_mul_f32_e32 v86, v77, v83
	v_mul_f32_e32 v77, v77, v82
	v_mul_f32_e32 v87, v73, v83
	v_mul_f32_e32 v73, v73, v82
	v_mul_f32_e32 v88, v78, v83
	v_mul_f32_e32 v78, v78, v82
	v_mul_f32_e32 v89, v74, v83
	v_mul_f32_e32 v74, v74, v82
	v_mul_f32_e32 v90, v79, v83
	v_mul_f32_e32 v79, v79, v82
	v_mul_f32_e32 v83, v75, v83
	v_mul_f32_e32 v75, v75, v82
	v_mul_f32_e32 v76, v76, v82
	v_exp_f32_e32 v72, v72
	v_exp_f32_e32 v77, v77
	v_exp_f32_e32 v73, v73
	v_exp_f32_e32 v78, v78
	v_exp_f32_e32 v74, v74
	v_exp_f32_e32 v79, v79
	v_exp_f32_e32 v75, v75
	v_exp_f32_e32 v76, v76
	v_add_f32_e32 v72, 1.0, v72
	v_add_f32_e32 v77, 1.0, v77
	v_add_f32_e32 v73, 1.0, v73
	v_add_f32_e32 v78, 1.0, v78
	v_add_f32_e32 v74, 1.0, v74
	v_add_f32_e32 v79, 1.0, v79
	v_add_f32_e32 v75, 1.0, v75
	v_add_f32_e32 v76, 1.0, v76
	v_rcp_f32_e32 v72, v72
	v_rcp_f32_e32 v77, v77
	v_rcp_f32_e32 v73, v73
	v_rcp_f32_e32 v78, v78
	v_rcp_f32_e32 v74, v74
	v_rcp_f32_e32 v79, v79
	v_rcp_f32_e32 v75, v75
	v_rcp_f32_e32 v76, v76
	v_mul_f32_e32 v72, v85, v72
	v_mul_f32_e32 v77, v86, v77
	v_mul_f32_e32 v73, v87, v73
	v_mul_f32_e32 v78, v88, v78
	v_mul_f32_e32 v74, v89, v74
	v_mul_f32_e32 v79, v90, v79
	v_mul_f32_e32 v75, v83, v75
	v_mul_f32_e32 v76, v84, v76
	v_mul_f32_e32 v72, v64, v72
	v_mul_f32_e32 v64, v69, v77
	v_mul_f32_e32 v69, v65, v73
	v_mul_f32_e32 v65, v70, v78
	v_mul_f32_e32 v70, v66, v74
	v_mul_f32_e32 v66, v71, v79
	v_mul_f32_e32 v67, v67, v75
	v_mul_f32_e32 v68, v68, v76
; __device__ __forceinline__ float fast_rcp(float x) { return __builtin_amdgcn_rcpf(x); }
; __device__ __forceinline__ float fast_exp2(float x) { return __builtin_amdgcn_exp2f(x); }
; __device__ __forceinline__ u32x4 pack8(f32x4 v0, f32x4 v1) { u32x4 w; w.x = cvt_pk_bf16(v0[0], v0[1]); w.y = cvt_pk_bf16(v0[2], v0[3]); w.z = cvt_pk_bf16(v1[0], v1[1]); w.w = cvt_pk_bf16(v1[2], v1[3]); return w; }
;     __device__ __forceinline__ void operator()(const f32x4 (&acc)[2][2][4][2], const Unit& u, int wr, int wc, int fr, int fq) const {
;     ...
;             for (int m = 0; m < 4; ++m) { bf16_t* rowp = O + (size_t)(row0 + ai * HALF + m * 16) * DFF + col0;
;                 const float r = rs[row0 + ai * HALF + m * 16], r2 = r * r;
;                 f32x4 h0, h1;
; #pragma unroll
;                 for (int j = 0; j < 4; ++j) {
;                     const float g0 = acc[ai][0][m][0][j], g1 = acc[ai][0][m][1][j];
;                     h0[j] = g0 * r2 * fast_rcp(1.0f + fast_exp2(g0 * (-LOG2E * r))) * acc[ai][1][m][0][j];
;                     h1[j] = g1 * r2 * fast_rcp(1.0f + fast_exp2(g1 * (-LOG2E * r))) * acc[ai][1][m][1][j]; }
;                 *(u32x4*)rowp = pack8(h0, h1); }
	v_cvt_pk_bf16_f32 v64, v68, v64
	v_cvt_pk_bf16_f32 v65, v65, v66
	v_cvt_pk_bf16_f32 v66, v72, v69
	v_cvt_pk_bf16_f32 v67, v70, v67
	global_store_dwordx4 v[80:81], v[64:67], off
	s_nop 1
	v_mov_b32_e32 v66, v207
	s_nop 0
	v_add_u32_e32 v64, 0x80, v144
	v_mad_i64_i32 v[64:65], s[40:41], v64, s52, v[146:147]
	v_lshl_add_u64 v[64:65], v[64:65], 0, v[148:149]
	v_mul_f32_e32 v67, v66, v66
	v_mul_f32_e32 v66, 0xbfb8aa3b, v66
	v_mul_f32_e32 v68, v60, v67
	v_mul_f32_e32 v69, v56, v67
	v_mul_f32_e32 v56, v56, v66
	v_mul_f32_e32 v70, v61, v67
	v_mul_f32_e32 v61, v61, v66
	v_mul_f32_e32 v71, v57, v67
	v_mul_f32_e32 v57, v57, v66
	v_mul_f32_e32 v72, v62, v67
	v_mul_f32_e32 v62, v62, v66
	v_mul_f32_e32 v73, v58, v67
	v_mul_f32_e32 v58, v58, v66
	v_mul_f32_e32 v74, v63, v67
	v_mul_f32_e32 v63, v63, v66
	v_mul_f32_e32 v67, v59, v67
	v_mul_f32_e32 v59, v59, v66
	v_mul_f32_e32 v60, v60, v66
	v_exp_f32_e32 v56, v56
	v_exp_f32_e32 v61, v61
	v_exp_f32_e32 v57, v57
	v_exp_f32_e32 v62, v62
	v_exp_f32_e32 v58, v58
	v_exp_f32_e32 v63, v63
	v_exp_f32_e32 v59, v59
	v_exp_f32_e32 v60, v60
	v_add_f32_e32 v56, 1.0, v56
	v_add_f32_e32 v61, 1.0, v61
	v_add_f32_e32 v57, 1.0, v57
	v_add_f32_e32 v62, 1.0, v62
	v_add_f32_e32 v58, 1.0, v58
	v_add_f32_e32 v63, 1.0, v63
	v_add_f32_e32 v59, 1.0, v59
	v_add_f32_e32 v60, 1.0, v60
	v_rcp_f32_e32 v56, v56
	v_rcp_f32_e32 v61, v61
	v_rcp_f32_e32 v57, v57
	v_rcp_f32_e32 v62, v62
	v_rcp_f32_e32 v58, v58
	v_rcp_f32_e32 v63, v63
	v_rcp_f32_e32 v59, v59
	v_rcp_f32_e32 v60, v60
	v_mul_f32_e32 v56, v69, v56
	v_mul_f32_e32 v61, v70, v61
	v_mul_f32_e32 v57, v71, v57
	v_mul_f32_e32 v62, v72, v62
	v_mul_f32_e32 v58, v73, v58
	v_mul_f32_e32 v63, v74, v63
	v_mul_f32_e32 v59, v67, v59
	v_mul_f32_e32 v60, v68, v60
	v_mul_f32_e32 v56, v48, v56
	v_mul_f32_e32 v48, v53, v61
	v_mul_f32_e32 v53, v49, v57
	v_mul_f32_e32 v49, v54, v62
	v_mul_f32_e32 v54, v50, v58
	v_mul_f32_e32 v50, v55, v63
	v_mul_f32_e32 v51, v51, v59
	v_mul_f32_e32 v52, v52, v60
	v_cvt_pk_bf16_f32 v48, v52, v48
	v_cvt_pk_bf16_f32 v49, v49, v50
	v_cvt_pk_bf16_f32 v50, v56, v53
	v_cvt_pk_bf16_f32 v51, v54, v51
	global_store_dwordx4 v[64:65], v[48:51], off
	s_nop 1
	v_mov_b32_e32 v50, v208
	s_nop 0
	v_add_u32_e32 v48, 0x90, v144
	v_mad_i64_i32 v[48:49], s[40:41], v48, s52, v[146:147]
	v_lshl_add_u64 v[48:49], v[48:49], 0, v[148:149]
	v_mul_f32_e32 v51, v50, v50
	v_mul_f32_e32 v50, 0xbfb8aa3b, v50
	v_mul_f32_e32 v52, v44, v51
	v_mul_f32_e32 v53, v40, v51
	v_mul_f32_e32 v40, v40, v50
	v_mul_f32_e32 v54, v45, v51
	v_mul_f32_e32 v45, v45, v50
	v_mul_f32_e32 v55, v41, v51
	v_mul_f32_e32 v41, v41, v50
	v_mul_f32_e32 v56, v46, v51
	v_mul_f32_e32 v46, v46, v50
	v_mul_f32_e32 v57, v42, v51
	v_mul_f32_e32 v42, v42, v50
	v_mul_f32_e32 v58, v47, v51
	v_mul_f32_e32 v47, v47, v50
	v_mul_f32_e32 v51, v43, v51
	v_mul_f32_e32 v43, v43, v50
	v_mul_f32_e32 v44, v44, v50
	v_exp_f32_e32 v40, v40
	v_exp_f32_e32 v45, v45
	v_exp_f32_e32 v41, v41
	v_exp_f32_e32 v46, v46
	v_exp_f32_e32 v42, v42
	v_exp_f32_e32 v47, v47
	v_exp_f32_e32 v43, v43
	v_exp_f32_e32 v44, v44
	v_add_f32_e32 v40, 1.0, v40
	v_add_f32_e32 v45, 1.0, v45
	v_add_f32_e32 v41, 1.0, v41
	v_add_f32_e32 v46, 1.0, v46
	v_add_f32_e32 v42, 1.0, v42
	v_add_f32_e32 v47, 1.0, v47
	v_add_f32_e32 v43, 1.0, v43
	v_add_f32_e32 v44, 1.0, v44
	v_rcp_f32_e32 v40, v40
	v_rcp_f32_e32 v45, v45
	v_rcp_f32_e32 v41, v41
	v_rcp_f32_e32 v46, v46
	v_rcp_f32_e32 v42, v42
	v_rcp_f32_e32 v47, v47
	v_rcp_f32_e32 v43, v43
	v_rcp_f32_e32 v44, v44
	v_mul_f32_e32 v40, v53, v40
	v_mul_f32_e32 v45, v54, v45
	v_mul_f32_e32 v41, v55, v41
	v_mul_f32_e32 v46, v56, v46
	v_mul_f32_e32 v42, v57, v42
	v_mul_f32_e32 v47, v58, v47
	v_mul_f32_e32 v43, v51, v43
	v_mul_f32_e32 v44, v52, v44
	v_mul_f32_e32 v40, v32, v40
	v_mul_f32_e32 v32, v37, v45
	v_mul_f32_e32 v37, v33, v41
	v_mul_f32_e32 v33, v38, v46
	v_mul_f32_e32 v38, v34, v42
	v_mul_f32_e32 v34, v39, v47
	v_mul_f32_e32 v35, v35, v43
	v_mul_f32_e32 v36, v36, v44
	v_cvt_pk_bf16_f32 v32, v36, v32
	v_cvt_pk_bf16_f32 v33, v33, v34
	v_cvt_pk_bf16_f32 v34, v40, v37
	v_cvt_pk_bf16_f32 v35, v38, v35
; __device__ __forceinline__ float fast_rcp(float x) { return __builtin_amdgcn_rcpf(x); }
; __device__ __forceinline__ float fast_exp2(float x) { return __builtin_amdgcn_exp2f(x); }
; #define PG8_WAIT_V(n) asm volatile("s_waitcnt vmcnt(" #n ")" ::: "memory")
; #define PG8_BAR __builtin_amdgcn_s_barrier()
; __device__ __forceinline__ u32x4 pack8(f32x4 v0, f32x4 v1) { u32x4 w; w.x = cvt_pk_bf16(v0[0], v0[1]); w.y = cvt_pk_bf16(v0[2], v0[3]); w.z = cvt_pk_bf16(v1[0], v1[1]); w.w = cvt_pk_bf16(v1[2], v1[3]); return w; }
; template <class Epi>
; __device__ __forceinline__ void gemm_phase(LAS unsigned char* lds, const Gemm g, const StaticOrder& S, const Epi& E) {
;     ...
;     PG8_WAIT_V(0);
;     if (wr == 0) PG8_BAR;
;     PG8_BAR;
;     __device__ __forceinline__ void operator()(const f32x4 (&acc)[2][2][4][2], const Unit& u, int wr, int wc, int fr, int fq) const {
;     ...
;             for (int m = 0; m < 4; ++m) { bf16_t* rowp = O + (size_t)(row0 + ai * HALF + m * 16) * DFF + col0;
;                 const float r = rs[row0 + ai * HALF + m * 16], r2 = r * r;
;                 f32x4 h0, h1;
; #pragma unroll
;                 for (int j = 0; j < 4; ++j) {
;                     const float g0 = acc[ai][0][m][0][j], g1 = acc[ai][0][m][1][j];
;                     h0[j] = g0 * r2 * fast_rcp(1.0f + fast_exp2(g0 * (-LOG2E * r))) * acc[ai][1][m][0][j];
;                     h1[j] = g1 * r2 * fast_rcp(1.0f + fast_exp2(g1 * (-LOG2E * r))) * acc[ai][1][m][1][j]; }
;                 *(u32x4*)rowp = pack8(h0, h1); }
	global_store_dwordx4 v[48:49], v[32:35], off
	s_nop 1
	v_mov_b32_e32 v34, v209
	s_nop 0
	v_add_u32_e32 v32, 0xa0, v144
	v_mad_i64_i32 v[32:33], s[40:41], v32, s52, v[146:147]
	v_lshl_add_u64 v[32:33], v[32:33], 0, v[148:149]
	s_mov_b64 s[40:41], s[34:35]
	v_mul_f32_e32 v35, v34, v34
	v_mul_f32_e32 v34, 0xbfb8aa3b, v34
	v_mul_f32_e32 v36, v28, v35
	v_mul_f32_e32 v37, v24, v35
	v_mul_f32_e32 v24, v24, v34
	v_mul_f32_e32 v38, v29, v35
	v_mul_f32_e32 v29, v29, v34
	v_mul_f32_e32 v39, v25, v35
	v_mul_f32_e32 v25, v25, v34
	v_mul_f32_e32 v40, v30, v35
	v_mul_f32_e32 v30, v30, v34
	v_mul_f32_e32 v41, v26, v35
	v_mul_f32_e32 v26, v26, v34
	v_mul_f32_e32 v42, v31, v35
	v_mul_f32_e32 v31, v31, v34
	v_mul_f32_e32 v35, v27, v35
	v_mul_f32_e32 v27, v27, v34
	v_mul_f32_e32 v28, v28, v34
	v_exp_f32_e32 v24, v24
	v_exp_f32_e32 v29, v29
	v_exp_f32_e32 v25, v25
	v_exp_f32_e32 v30, v30
	v_exp_f32_e32 v26, v26
	v_exp_f32_e32 v31, v31
	v_exp_f32_e32 v27, v27
	v_exp_f32_e32 v28, v28
	v_add_f32_e32 v24, 1.0, v24
	v_add_f32_e32 v29, 1.0, v29
	v_add_f32_e32 v25, 1.0, v25
	v_add_f32_e32 v30, 1.0, v30
	v_add_f32_e32 v26, 1.0, v26
	v_add_f32_e32 v31, 1.0, v31
	v_add_f32_e32 v27, 1.0, v27
	v_add_f32_e32 v28, 1.0, v28
	v_rcp_f32_e32 v24, v24
	v_rcp_f32_e32 v29, v29
	v_rcp_f32_e32 v25, v25
	v_rcp_f32_e32 v30, v30
	v_rcp_f32_e32 v26, v26
	v_rcp_f32_e32 v31, v31
	v_rcp_f32_e32 v27, v27
	v_rcp_f32_e32 v28, v28
	v_mul_f32_e32 v24, v37, v24
	v_mul_f32_e32 v29, v38, v29
	v_mul_f32_e32 v25, v39, v25
	v_mul_f32_e32 v30, v40, v30
	v_mul_f32_e32 v26, v41, v26
	v_mul_f32_e32 v31, v42, v31
	v_mul_f32_e32 v27, v35, v27
	v_mul_f32_e32 v28, v36, v28
	v_mul_f32_e32 v24, v16, v24
	v_mul_f32_e32 v16, v21, v29
	v_mul_f32_e32 v21, v17, v25
	v_mul_f32_e32 v17, v22, v30
	v_mul_f32_e32 v22, v18, v26
	v_mul_f32_e32 v18, v23, v31
	v_mul_f32_e32 v19, v19, v27
	v_mul_f32_e32 v20, v20, v28
	v_cvt_pk_bf16_f32 v16, v20, v16
	v_cvt_pk_bf16_f32 v17, v17, v18
	v_cvt_pk_bf16_f32 v18, v24, v21
	v_cvt_pk_bf16_f32 v19, v22, v19
	global_store_dwordx4 v[32:33], v[16:19], off
	s_nop 1
	v_mov_b32_e32 v18, v210
	s_nop 0
	v_add_u32_e32 v16, 0xb0, v144
	v_mad_i64_i32 v[16:17], s[6:7], v16, s52, v[146:147]
	v_lshl_add_u64 v[16:17], v[16:17], 0, v[148:149]
	v_mul_f32_e32 v19, v18, v18
	v_mul_f32_e32 v18, 0xbfb8aa3b, v18
	v_mul_f32_e32 v20, v12, v19
	v_mul_f32_e32 v21, v8, v19
	v_mul_f32_e32 v8, v8, v18
	v_mul_f32_e32 v22, v13, v19
	v_mul_f32_e32 v13, v13, v18
	v_mul_f32_e32 v23, v9, v19
	v_mul_f32_e32 v9, v9, v18
	v_mul_f32_e32 v24, v14, v19
	v_mul_f32_e32 v14, v14, v18
	v_mul_f32_e32 v25, v10, v19
	v_mul_f32_e32 v10, v10, v18
	v_mul_f32_e32 v26, v15, v19
	v_mul_f32_e32 v15, v15, v18
	v_mul_f32_e32 v19, v11, v19
	v_mul_f32_e32 v11, v11, v18
	v_mul_f32_e32 v12, v12, v18
	v_exp_f32_e32 v8, v8
	v_exp_f32_e32 v13, v13
	v_exp_f32_e32 v9, v9
	v_exp_f32_e32 v14, v14
	v_exp_f32_e32 v10, v10
	v_exp_f32_e32 v15, v15
	v_exp_f32_e32 v11, v11
	v_exp_f32_e32 v12, v12
	v_add_f32_e32 v8, 1.0, v8
	v_add_f32_e32 v13, 1.0, v13
	v_add_f32_e32 v9, 1.0, v9
	v_add_f32_e32 v14, 1.0, v14
	v_add_f32_e32 v10, 1.0, v10
	v_add_f32_e32 v15, 1.0, v15
	v_add_f32_e32 v11, 1.0, v11
	v_add_f32_e32 v12, 1.0, v12
	v_rcp_f32_e32 v8, v8
	v_rcp_f32_e32 v13, v13
	v_rcp_f32_e32 v9, v9
	v_rcp_f32_e32 v14, v14
	v_rcp_f32_e32 v10, v10
	v_rcp_f32_e32 v15, v15
	v_rcp_f32_e32 v11, v11
	v_rcp_f32_e32 v12, v12
	v_mul_f32_e32 v8, v21, v8
	v_mul_f32_e32 v13, v22, v13
	v_mul_f32_e32 v9, v23, v9
	v_mul_f32_e32 v14, v24, v14
	v_mul_f32_e32 v10, v25, v10
	v_mul_f32_e32 v15, v26, v15
	v_mul_f32_e32 v11, v19, v11
	v_mul_f32_e32 v12, v20, v12
	v_mul_f32_e32 v8, v0, v8
	v_mul_f32_e32 v0, v5, v13
	v_mul_f32_e32 v5, v1, v9
	v_mul_f32_e32 v1, v6, v14
	v_mul_f32_e32 v6, v2, v10
	v_mul_f32_e32 v2, v7, v15
	v_mul_f32_e32 v3, v3, v11
	v_mul_f32_e32 v4, v4, v12
	v_cvt_pk_bf16_f32 v0, v4, v0
	v_cvt_pk_bf16_f32 v1, v1, v2
	v_cvt_pk_bf16_f32 v2, v8, v5
	v_cvt_pk_bf16_f32 v3, v6, v3
	global_store_dwordx4 v[16:17], v[0:3], off
	s_cbranch_vccz .LBB0_793
	s_waitcnt vmcnt(0)
	s_cmpk_gt_u32 s10, 0xff
	s_cbranch_scc1 .LBB0_800
	s_barrier

; #define PG8_STAGE(bufoff, gbase, voff) do { _Pragma("unroll") for (int _i = 0; _i < 2; ++_i) \
;         __builtin_amdgcn_global_load_lds((const unsigned*)((const char*)(gbase) + (voff)[_i]), (LAS unsigned*)(lds + (bufoff) + ldsw + _i * 8192), 16, 0, 0); } while (0)
; #define PG8_LDA(dst, b, h) do { _Pragma("unroll") for (int m = 0; m < 4; ++m) _Pragma("unroll") for (int k = 0; k < 2; ++k) dst[m][k] = *(const LAS bf16x8*)(lds + PG8_SA(b, h) + aoff + m * 2048 + k * 1024); } while (0)
; #define PG8_LDB(dst, b, h) do { _Pragma("unroll") for (int n = 0; n < 2; ++n) _Pragma("unroll") for (int k = 0; k < 2; ++k) dst[n][k] = *(const LAS bf16x8*)(lds + PG8_SB(b, h) + boff + n * 2048 + k * 1024); } while (0)
; #define PG8_MMA(ai, bj, At, Bt) do { __builtin_amdgcn_s_setprio(1); _Pragma("unroll") for (int m = 0; m < 4; ++m) _Pragma("unroll") for (int n = 0; n < 2; ++n) _Pragma("unroll") for (int k = 0; k < 2; ++k) \
;         acc[ai][bj][m][n] = __builtin_amdgcn_mfma_f32_16x16x32_bf16(Bt[n][k], At[m][k], acc[ai][bj][m][n], 0, 0, 0); __builtin_amdgcn_s_setprio(0); } while (0)
; #define PG8_WAIT_V(n) asm volatile("s_waitcnt vmcnt(" #n ")" ::: "memory")
; #define PG8_WAIT_L(n) asm volatile("s_waitcnt lgkmcnt(" #n ")" ::: "memory")
; #define PG8_BAR __builtin_amdgcn_s_barrier()
; #define PG8_SCHED __builtin_amdgcn_sched_barrier(0)
; template <class Epi>
; __device__ __forceinline__ void gemm_phase(LAS unsigned char* lds, const Gemm g, const StaticOrder& S, const Epi& E) {
;     ...
;             PG8_LDB(B0, 0, 0); PG8_SCHED; PG8_LDA(At, 0, 0); PG8_STAGE(PG8_SA(1, 1), a1 + hstep, voffA);
;             PG8_WAIT_L(8); PG8_BAR; PG8_WAIT_L(0); PG8_MMA(0, 0, At, B0); PG8_BAR; PG8_SCHED;
;             PG8_LDB(B1, 0, 1); PG8_STAGE(PG8_SB(0, 0), b2, voffB);
;             PG8_BAR; PG8_WAIT_L(0); PG8_MMA(0, 1, At, B1); PG8_BAR;
;             PG8_LDA(At, 0, 1); PG8_STAGE(PG8_SA(0, 0), a2, voffA);
;             PG8_BAR; PG8_WAIT_L(0); PG8_MMA(1, 0, At, B0); PG8_BAR; PG8_SCHED;
;             PG8_STAGE(PG8_SB(0, 1), b2 + hstep, voffB);
;             PG8_WAIT_V(6); PG8_BAR; PG8_MMA(1, 1, At, B1); PG8_BAR;
.LBB0_864:
	ds_read_b128 v[148:151], v145
	ds_read_b128 v[152:155], v145 offset:1024
	ds_read_b128 v[160:163], v145 offset:2048
	ds_read_b128 v[164:167], v145 offset:3072
	s_add_u32 s44, s42, 0x100
	s_addc_u32 s45, s43, 0
	s_cmpk_eq_i32 s67, 0x54
	s_cselect_b32 s49, s41, s45
	s_cselect_b32 s48, s40, s44
	s_cselect_b32 s47, s7, s66
	s_cselect_b32 s46, s6, s65
	s_add_i32 m0, s28, 0xc000
	ds_read_b128 v[168:171], v146
	ds_read_b128 v[172:175], v146 offset:1024
	ds_read_b128 v[176:179], v146 offset:2048
	ds_read_b128 v[180:183], v146 offset:3072
	ds_read_b128 v[184:187], v146 offset:4096
	ds_read_b128 v[188:191], v146 offset:5120
	ds_read_b128 v[192:195], v146 offset:6144
	ds_read_b128 v[196:199], v146 offset:7168
	global_load_lds_dwordx4 v136, s[42:43]
	s_add_i32 m0, s28, 0xe000
	s_nop 0
	global_load_lds_dwordx4 v138, s[42:43]
	s_waitcnt lgkmcnt(8)
	s_barrier
	s_waitcnt lgkmcnt(0)
	s_setprio 1
	s_waitcnt lgkmcnt(0)
	v_mfma_f32_16x16x32_bf16 v[124:127], v[148:151], v[168:171], v[124:127]
	v_mfma_f32_16x16x32_bf16 v[120:123], v[160:163], v[168:171], v[120:123]
	v_mfma_f32_16x16x32_bf16 v[112:115], v[148:151], v[176:179], v[112:115]
	v_mfma_f32_16x16x32_bf16 v[104:107], v[160:163], v[176:179], v[104:107]
	v_mfma_f32_16x16x32_bf16 v[96:99], v[148:151], v[184:187], v[96:99]
	v_mfma_f32_16x16x32_bf16 v[88:91], v[160:163], v[184:187], v[88:91]
	v_mfma_f32_16x16x32_bf16 v[80:83], v[148:151], v[192:195], v[80:83]
	v_mfma_f32_16x16x32_bf16 v[72:75], v[160:163], v[192:195], v[72:75]
	v_mfma_f32_16x16x32_bf16 v[124:127], v[152:155], v[172:175], v[124:127]
	v_mfma_f32_16x16x32_bf16 v[120:123], v[164:167], v[172:175], v[120:123]
	v_mfma_f32_16x16x32_bf16 v[112:115], v[152:155], v[180:183], v[112:115]
	v_mfma_f32_16x16x32_bf16 v[104:107], v[164:167], v[180:183], v[104:107]
	v_mfma_f32_16x16x32_bf16 v[96:99], v[152:155], v[188:191], v[96:99]
	v_mfma_f32_16x16x32_bf16 v[88:91], v[164:167], v[188:191], v[88:91]
	v_mfma_f32_16x16x32_bf16 v[80:83], v[152:155], v[196:199], v[80:83]
	v_mfma_f32_16x16x32_bf16 v[72:75], v[164:167], v[196:199], v[72:75]
	s_setprio 0
	s_barrier
	s_add_i32 s42, s55, s23
	s_add_u32 s98, s46, s2
	s_addc_u32 s99, s47, s3
	s_mov_b32 m0, s42
	ds_read_b128 v[200:203], v147
	ds_read_b128 v[204:207], v147 offset:1024
	ds_read_b128 v[208:211], v147 offset:2048
	ds_read_b128 v[212:215], v147 offset:3072
	global_load_lds_dwordx4 v132, s[46:47]
	s_add_i32 m0, s42, 0x2000
	s_nop 0
	global_load_lds_dwordx4 v128, s[46:47]
	s_barrier
	s_waitcnt lgkmcnt(0)
	s_setprio 1
	s_waitcnt lgkmcnt(0)
	v_mfma_f32_16x16x32_bf16 v[116:119], v[200:203], v[168:171], v[116:119]
	v_mfma_f32_16x16x32_bf16 v[108:111], v[208:211], v[168:171], v[108:111]
	v_mfma_f32_16x16x32_bf16 v[100:103], v[200:203], v[176:179], v[100:103]
	v_mfma_f32_16x16x32_bf16 v[92:95], v[208:211], v[176:179], v[92:95]
	v_mfma_f32_16x16x32_bf16 v[84:87], v[200:203], v[184:187], v[84:87]
	v_mfma_f32_16x16x32_bf16 v[76:79], v[208:211], v[184:187], v[76:79]
	v_mfma_f32_16x16x32_bf16 v[68:71], v[200:203], v[192:195], v[68:71]
	v_mfma_f32_16x16x32_bf16 v[64:67], v[208:211], v[192:195], v[64:67]
	v_mfma_f32_16x16x32_bf16 v[116:119], v[204:207], v[172:175], v[116:119]
	v_mfma_f32_16x16x32_bf16 v[108:111], v[212:215], v[172:175], v[108:111]
	v_mfma_f32_16x16x32_bf16 v[100:103], v[204:207], v[180:183], v[100:103]
	v_mfma_f32_16x16x32_bf16 v[92:95], v[212:215], v[180:183], v[92:95]
	v_mfma_f32_16x16x32_bf16 v[84:87], v[204:207], v[188:191], v[84:87]
	v_mfma_f32_16x16x32_bf16 v[76:79], v[212:215], v[188:191], v[76:79]
	v_mfma_f32_16x16x32_bf16 v[68:71], v[204:207], v[196:199], v[68:71]
	v_mfma_f32_16x16x32_bf16 v[64:67], v[212:215], v[196:199], v[64:67]
	s_setprio 0
	s_mov_b32 m0, s28
	s_add_u32 s100, s48, s2
	s_addc_u32 s101, s49, s3
	s_barrier
	ds_read_b128 v[168:171], v146 offset:16384
	ds_read_b128 v[172:175], v146 offset:17408
	ds_read_b128 v[176:179], v146 offset:18432
	ds_read_b128 v[180:183], v146 offset:19456
	ds_read_b128 v[184:187], v146 offset:20480
	ds_read_b128 v[188:191], v146 offset:21504
	ds_read_b128 v[192:195], v146 offset:22528
	ds_read_b128 v[196:199], v146 offset:23552
	global_load_lds_dwordx4 v134, s[48:49]
	s_mov_b32 m0, s29
	s_nop 0
	global_load_lds_dwordx4 v130, s[48:49]
	s_barrier
	s_waitcnt lgkmcnt(0)
	s_setprio 1
	s_waitcnt lgkmcnt(0)
	v_mfma_f32_16x16x32_bf16 v[60:63], v[148:151], v[168:171], v[60:63]
	v_mfma_f32_16x16x32_bf16 v[56:59], v[160:163], v[168:171], v[56:59]
	v_mfma_f32_16x16x32_bf16 v[52:55], v[148:151], v[176:179], v[52:55]
	v_mfma_f32_16x16x32_bf16 v[44:47], v[160:163], v[176:179], v[44:47]
	v_mfma_f32_16x16x32_bf16 v[36:39], v[148:151], v[184:187], v[36:39]
	v_mfma_f32_16x16x32_bf16 v[28:31], v[160:163], v[184:187], v[28:31]
	v_mfma_f32_16x16x32_bf16 v[20:23], v[148:151], v[192:195], v[20:23]
	v_mfma_f32_16x16x32_bf16 v[12:15], v[160:163], v[192:195], v[12:15]
	v_mfma_f32_16x16x32_bf16 v[60:63], v[152:155], v[172:175], v[60:63]
	v_mfma_f32_16x16x32_bf16 v[56:59], v[164:167], v[172:175], v[56:59]
	v_mfma_f32_16x16x32_bf16 v[52:55], v[152:155], v[180:183], v[52:55]
	v_mfma_f32_16x16x32_bf16 v[44:47], v[164:167], v[180:183], v[44:47]
	v_mfma_f32_16x16x32_bf16 v[36:39], v[152:155], v[188:191], v[36:39]
	v_mfma_f32_16x16x32_bf16 v[28:31], v[164:167], v[188:191], v[28:31]
	v_mfma_f32_16x16x32_bf16 v[20:23], v[152:155], v[196:199], v[20:23]
	v_mfma_f32_16x16x32_bf16 v[12:15], v[164:167], v[196:199], v[12:15]
	s_setprio 0
	s_barrier
	s_add_u32 s42, s46, 0x160000
	s_addc_u32 s43, s47, 0
	s_add_i32 s68, s56, s23
	s_mov_b32 m0, s68
	s_nop 0
	global_load_lds_dwordx4 v132, s[42:43]
	s_add_i32 m0, s68, 0x2000
	s_nop 0
	global_load_lds_dwordx4 v128, s[42:43]
	s_waitcnt vmcnt(6)
	s_barrier
; #define PG8_STAGE(bufoff, gbase, voff) do { _Pragma("unroll") for (int _i = 0; _i < 2; ++_i) \
;         __builtin_amdgcn_global_load_lds((const unsigned*)((const char*)(gbase) + (voff)[_i]), (LAS unsigned*)(lds + (bufoff) + ldsw + _i * 8192), 16, 0, 0); } while (0)
; #define PG8_LDA(dst, b, h) do { _Pragma("unroll") for (int m = 0; m < 4; ++m) _Pragma("unroll") for (int k = 0; k < 2; ++k) dst[m][k] = *(const LAS bf16x8*)(lds + PG8_SA(b, h) + aoff + m * 2048 + k * 1024); } while (0)
; #define PG8_LDB(dst, b, h) do { _Pragma("unroll") for (int n = 0; n < 2; ++n) _Pragma("unroll") for (int k = 0; k < 2; ++k) dst[n][k] = *(const LAS bf16x8*)(lds + PG8_SB(b, h) + boff + n * 2048 + k * 1024); } while (0)
; #define PG8_MMA(ai, bj, At, Bt) do { __builtin_amdgcn_s_setprio(1); _Pragma("unroll") for (int m = 0; m < 4; ++m) _Pragma("unroll") for (int n = 0; n < 2; ++n) _Pragma("unroll") for (int k = 0; k < 2; ++k) \
;         acc[ai][bj][m][n] = __builtin_amdgcn_mfma_f32_16x16x32_bf16(Bt[n][k], At[m][k], acc[ai][bj][m][n], 0, 0, 0); __builtin_amdgcn_s_setprio(0); } while (0)
; #define PG8_WAIT_V(n) asm volatile("s_waitcnt vmcnt(" #n ")" ::: "memory")
; #define PG8_WAIT_L(n) asm volatile("s_waitcnt lgkmcnt(" #n ")" ::: "memory")
; #define PG8_BAR __builtin_amdgcn_s_barrier()
; #define PG8_SCHED __builtin_amdgcn_sched_barrier(0)
; template <class Epi>
; __device__ __forceinline__ void gemm_phase(LAS unsigned char* lds, const Gemm g, const StaticOrder& S, const Epi& E) {
;     ...
;             PG8_WAIT_V(6); PG8_BAR; PG8_MMA(1, 1, At, B1); PG8_BAR;
;             PG8_LDB(B0, 1, 0); PG8_SCHED; PG8_LDA(At, 1, 0); PG8_STAGE(PG8_SA(0, 1), a2 + hstep, voffA);
;             PG8_WAIT_L(8); PG8_BAR; PG8_WAIT_L(0); PG8_MMA(0, 0, At, B0); PG8_BAR; PG8_SCHED;
;             PG8_LDB(B1, 1, 1); PG8_STAGE(PG8_SB(1, 0), b3, voffB);
;             PG8_BAR; PG8_WAIT_L(0); PG8_MMA(0, 1, At, B1); PG8_BAR;
;             PG8_LDA(At, 1, 1); PG8_STAGE(PG8_SA(1, 0), a3, voffA);
;             PG8_BAR; PG8_WAIT_L(0); PG8_MMA(1, 0, At, B0); PG8_BAR; PG8_SCHED;
;             PG8_STAGE(PG8_SB(1, 1), b3 + hstep, voffB);
	s_setprio 1
	v_mfma_f32_16x16x32_bf16 v[48:51], v[200:203], v[168:171], v[48:51]
	v_mfma_f32_16x16x32_bf16 v[40:43], v[208:211], v[168:171], v[40:43]
	v_mfma_f32_16x16x32_bf16 v[32:35], v[200:203], v[176:179], v[32:35]
	v_mfma_f32_16x16x32_bf16 v[24:27], v[208:211], v[176:179], v[24:27]
	v_mfma_f32_16x16x32_bf16 v[16:19], v[200:203], v[184:187], v[16:19]
	v_mfma_f32_16x16x32_bf16 v[8:11], v[208:211], v[184:187], v[8:11]
	v_mfma_f32_16x16x32_bf16 v[4:7], v[200:203], v[192:195], v[4:7]
	v_mfma_f32_16x16x32_bf16 v[0:3], v[208:211], v[192:195], v[0:3]
	v_mfma_f32_16x16x32_bf16 v[48:51], v[204:207], v[172:175], v[48:51]
	v_mfma_f32_16x16x32_bf16 v[40:43], v[212:215], v[172:175], v[40:43]
	v_mfma_f32_16x16x32_bf16 v[32:35], v[204:207], v[180:183], v[32:35]
	v_mfma_f32_16x16x32_bf16 v[24:27], v[212:215], v[180:183], v[24:27]
	v_mfma_f32_16x16x32_bf16 v[16:19], v[204:207], v[188:191], v[16:19]
	v_mfma_f32_16x16x32_bf16 v[8:11], v[212:215], v[188:191], v[8:11]
	v_mfma_f32_16x16x32_bf16 v[4:7], v[204:207], v[196:199], v[4:7]
	v_mfma_f32_16x16x32_bf16 v[0:3], v[212:215], v[196:199], v[0:3]
	s_setprio 0
	s_add_i32 s68, 0, 0x18000
	v_add_u32_e32 v164, s68, v143
	s_barrier
	ds_read_b128 v[148:151], v164
	ds_read_b128 v[152:155], v164 offset:1024
	ds_read_b128 v[160:163], v164 offset:2048
	ds_read_b128 v[164:167], v164 offset:3072
	s_add_u32 s42, s48, 0x160000
	s_addc_u32 s43, s49, 0
	s_mov_b32 m0, s33
	ds_read_b128 v[168:171], v146 offset:32768
	ds_read_b128 v[172:175], v146 offset:33792
	ds_read_b128 v[176:179], v146 offset:34816
	ds_read_b128 v[180:183], v146 offset:35840
	ds_read_b128 v[184:187], v146 offset:36864
	ds_read_b128 v[188:191], v146 offset:37888
	ds_read_b128 v[192:195], v146 offset:38912
	ds_read_b128 v[196:199], v146 offset:39936
	global_load_lds_dwordx4 v134, s[42:43]
	s_mov_b32 m0, s50
	s_nop 0
	global_load_lds_dwordx4 v130, s[42:43]
	s_waitcnt lgkmcnt(8)
	s_barrier
	s_waitcnt lgkmcnt(0)
	s_setprio 1
	s_waitcnt lgkmcnt(0)
	v_mfma_f32_16x16x32_bf16 v[124:127], v[148:151], v[168:171], v[124:127]
	v_mfma_f32_16x16x32_bf16 v[120:123], v[160:163], v[168:171], v[120:123]
	v_mfma_f32_16x16x32_bf16 v[112:115], v[148:151], v[176:179], v[112:115]
	v_mfma_f32_16x16x32_bf16 v[104:107], v[160:163], v[176:179], v[104:107]
	v_mfma_f32_16x16x32_bf16 v[96:99], v[148:151], v[184:187], v[96:99]
	v_mfma_f32_16x16x32_bf16 v[88:91], v[160:163], v[184:187], v[88:91]
	v_mfma_f32_16x16x32_bf16 v[80:83], v[148:151], v[192:195], v[80:83]
	v_mfma_f32_16x16x32_bf16 v[72:75], v[160:163], v[192:195], v[72:75]
	v_mfma_f32_16x16x32_bf16 v[124:127], v[152:155], v[172:175], v[124:127]
	v_mfma_f32_16x16x32_bf16 v[120:123], v[164:167], v[172:175], v[120:123]
	v_mfma_f32_16x16x32_bf16 v[112:115], v[152:155], v[180:183], v[112:115]
	v_mfma_f32_16x16x32_bf16 v[104:107], v[164:167], v[180:183], v[104:107]
	v_mfma_f32_16x16x32_bf16 v[96:99], v[152:155], v[188:191], v[96:99]
	v_mfma_f32_16x16x32_bf16 v[88:91], v[164:167], v[188:191], v[88:91]
	v_mfma_f32_16x16x32_bf16 v[80:83], v[152:155], v[196:199], v[80:83]
	v_mfma_f32_16x16x32_bf16 v[72:75], v[164:167], v[196:199], v[72:75]
	s_setprio 0
	s_barrier
	s_add_i32 s48, 0, 0x1c000
	s_add_i32 s42, s68, s23
	v_add_u32_e32 v212, s48, v143
	s_mov_b32 m0, s42
	ds_read_b128 v[200:203], v212
	ds_read_b128 v[204:207], v212 offset:1024
	ds_read_b128 v[208:211], v212 offset:2048
	ds_read_b128 v[212:215], v212 offset:3072
	global_load_lds_dwordx4 v132, s[98:99]
	s_add_i32 m0, s42, 0x2000
	s_nop 0
	global_load_lds_dwordx4 v128, s[98:99]
	s_barrier
	s_waitcnt lgkmcnt(0)
	s_setprio 1
	s_waitcnt lgkmcnt(0)
	v_mfma_f32_16x16x32_bf16 v[116:119], v[200:203], v[168:171], v[116:119]
	v_mfma_f32_16x16x32_bf16 v[108:111], v[208:211], v[168:171], v[108:111]
	v_mfma_f32_16x16x32_bf16 v[100:103], v[200:203], v[176:179], v[100:103]
	v_mfma_f32_16x16x32_bf16 v[92:95], v[208:211], v[176:179], v[92:95]
	v_mfma_f32_16x16x32_bf16 v[84:87], v[200:203], v[184:187], v[84:87]
	v_mfma_f32_16x16x32_bf16 v[76:79], v[208:211], v[184:187], v[76:79]
	v_mfma_f32_16x16x32_bf16 v[68:71], v[200:203], v[192:195], v[68:71]
	v_mfma_f32_16x16x32_bf16 v[64:67], v[208:211], v[192:195], v[64:67]
	v_mfma_f32_16x16x32_bf16 v[116:119], v[204:207], v[172:175], v[116:119]
	v_mfma_f32_16x16x32_bf16 v[108:111], v[212:215], v[172:175], v[108:111]
	v_mfma_f32_16x16x32_bf16 v[100:103], v[204:207], v[180:183], v[100:103]
	v_mfma_f32_16x16x32_bf16 v[92:95], v[212:215], v[180:183], v[92:95]
	v_mfma_f32_16x16x32_bf16 v[84:87], v[204:207], v[188:191], v[84:87]
	v_mfma_f32_16x16x32_bf16 v[76:79], v[212:215], v[188:191], v[76:79]
	v_mfma_f32_16x16x32_bf16 v[68:71], v[204:207], v[196:199], v[68:71]
	v_mfma_f32_16x16x32_bf16 v[64:67], v[212:215], v[196:199], v[64:67]
	s_setprio 0
	s_mov_b32 m0, s52
	s_barrier
	ds_read_b128 v[168:171], v146 offset:49152
	ds_read_b128 v[172:175], v146 offset:50176
	ds_read_b128 v[176:179], v146 offset:51200
	ds_read_b128 v[180:183], v146 offset:52224
	ds_read_b128 v[184:187], v146 offset:53248
	ds_read_b128 v[188:191], v146 offset:54272
	ds_read_b128 v[192:195], v146 offset:55296
	ds_read_b128 v[196:199], v146 offset:56320
	global_load_lds_dwordx4 v134, s[100:101]
	s_mov_b32 m0, s53
	s_nop 0
	global_load_lds_dwordx4 v130, s[100:101]
	s_barrier
; #define PG8_STAGE(bufoff, gbase, voff) do { _Pragma("unroll") for (int _i = 0; _i < 2; ++_i) \
;         __builtin_amdgcn_global_load_lds((const unsigned*)((const char*)(gbase) + (voff)[_i]), (LAS unsigned*)(lds + (bufoff) + ldsw + _i * 8192), 16, 0, 0); } while (0)
; #define PG8_LDA(dst, b, h) do { _Pragma("unroll") for (int m = 0; m < 4; ++m) _Pragma("unroll") for (int k = 0; k < 2; ++k) dst[m][k] = *(const LAS bf16x8*)(lds + PG8_SA(b, h) + aoff + m * 2048 + k * 1024); } while (0)
; #define PG8_MMA(ai, bj, At, Bt) do { __builtin_amdgcn_s_setprio(1); _Pragma("unroll") for (int m = 0; m < 4; ++m) _Pragma("unroll") for (int n = 0; n < 2; ++n) _Pragma("unroll") for (int k = 0; k < 2; ++k) \
;         acc[ai][bj][m][n] = __builtin_amdgcn_mfma_f32_16x16x32_bf16(Bt[n][k], At[m][k], acc[ai][bj][m][n], 0, 0, 0); __builtin_amdgcn_s_setprio(0); } while (0)
; #define PG8_WAIT_V(n) asm volatile("s_waitcnt vmcnt(" #n ")" ::: "memory")
; #define PG8_WAIT_L(n) asm volatile("s_waitcnt lgkmcnt(" #n ")" ::: "memory")
; #define PG8_BAR __builtin_amdgcn_s_barrier()
; #define PG8_SCHED __builtin_amdgcn_sched_barrier(0)
; template <class Epi>
; __device__ __forceinline__ void gemm_phase(LAS unsigned char* lds, const Gemm g, const StaticOrder& S, const Epi& E) {
;     ...
;             PG8_BAR; PG8_WAIT_L(0); PG8_MMA(0, 1, At, B1); PG8_BAR;
;             PG8_LDA(At, 1, 1); PG8_STAGE(PG8_SA(1, 0), a3, voffA);
;             PG8_BAR; PG8_WAIT_L(0); PG8_MMA(1, 0, At, B0); PG8_BAR; PG8_SCHED;
;             PG8_STAGE(PG8_SB(1, 1), b3 + hstep, voffB);
;             PG8_WAIT_V(6); PG8_BAR; PG8_MMA(1, 1, At, B1); PG8_BAR;
	s_waitcnt lgkmcnt(0)
	s_setprio 1
	s_waitcnt lgkmcnt(0)
	v_mfma_f32_16x16x32_bf16 v[60:63], v[148:151], v[168:171], v[60:63]
	v_mfma_f32_16x16x32_bf16 v[56:59], v[160:163], v[168:171], v[56:59]
	v_mfma_f32_16x16x32_bf16 v[52:55], v[148:151], v[176:179], v[52:55]
	v_mfma_f32_16x16x32_bf16 v[44:47], v[160:163], v[176:179], v[44:47]
	v_mfma_f32_16x16x32_bf16 v[36:39], v[148:151], v[184:187], v[36:39]
	v_mfma_f32_16x16x32_bf16 v[28:31], v[160:163], v[184:187], v[28:31]
	v_mfma_f32_16x16x32_bf16 v[20:23], v[148:151], v[192:195], v[20:23]
	v_mfma_f32_16x16x32_bf16 v[12:15], v[160:163], v[192:195], v[12:15]
	v_mfma_f32_16x16x32_bf16 v[60:63], v[152:155], v[172:175], v[60:63]
	v_mfma_f32_16x16x32_bf16 v[56:59], v[164:167], v[172:175], v[56:59]
	v_mfma_f32_16x16x32_bf16 v[52:55], v[152:155], v[180:183], v[52:55]
	v_mfma_f32_16x16x32_bf16 v[44:47], v[164:167], v[180:183], v[44:47]
	v_mfma_f32_16x16x32_bf16 v[36:39], v[152:155], v[188:191], v[36:39]
	v_mfma_f32_16x16x32_bf16 v[28:31], v[164:167], v[188:191], v[28:31]
	v_mfma_f32_16x16x32_bf16 v[20:23], v[152:155], v[196:199], v[20:23]
	v_mfma_f32_16x16x32_bf16 v[12:15], v[164:167], v[196:199], v[12:15]
	s_setprio 0
	s_barrier
	s_add_u32 s42, s46, 0x160080
	s_addc_u32 s43, s47, 0
	s_add_i32 s46, s48, s23
	s_mov_b32 m0, s46
	s_nop 0
	global_load_lds_dwordx4 v132, s[42:43]
	s_add_i32 m0, s46, 0x2000
	s_nop 0
	global_load_lds_dwordx4 v128, s[42:43]
	s_waitcnt vmcnt(6)
	s_barrier
	s_setprio 1
	v_mfma_f32_16x16x32_bf16 v[48:51], v[200:203], v[168:171], v[48:51]
	v_mfma_f32_16x16x32_bf16 v[40:43], v[208:211], v[168:171], v[40:43]
	v_mfma_f32_16x16x32_bf16 v[32:35], v[200:203], v[176:179], v[32:35]
	v_mfma_f32_16x16x32_bf16 v[24:27], v[208:211], v[176:179], v[24:27]
	v_mfma_f32_16x16x32_bf16 v[16:19], v[200:203], v[184:187], v[16:19]
	v_mfma_f32_16x16x32_bf16 v[8:11], v[208:211], v[184:187], v[8:11]
	v_mfma_f32_16x16x32_bf16 v[4:7], v[200:203], v[192:195], v[4:7]
	v_mfma_f32_16x16x32_bf16 v[0:3], v[208:211], v[192:195], v[0:3]
	v_mfma_f32_16x16x32_bf16 v[48:51], v[204:207], v[172:175], v[48:51]
	v_mfma_f32_16x16x32_bf16 v[40:43], v[212:215], v[172:175], v[40:43]
	v_mfma_f32_16x16x32_bf16 v[32:35], v[204:207], v[180:183], v[32:35]
	v_mfma_f32_16x16x32_bf16 v[24:27], v[212:215], v[180:183], v[24:27]
	v_mfma_f32_16x16x32_bf16 v[16:19], v[204:207], v[188:191], v[16:19]
	v_mfma_f32_16x16x32_bf16 v[8:11], v[212:215], v[188:191], v[8:11]
	v_mfma_f32_16x16x32_bf16 v[4:7], v[204:207], v[196:199], v[4:7]
	v_mfma_f32_16x16x32_bf16 v[0:3], v[212:215], v[196:199], v[0:3]
	s_setprio 0
	s_add_i32 s67, s67, 2
	s_add_u32 s65, s65, 0x100
	s_addc_u32 s66, s66, 0
	s_cmpk_gt_u32 s67, 0x55
	s_mov_b64 s[42:43], s[44:45]
	s_barrier
	s_cbranch_scc0 .LBB0_864
; __device__ __forceinline__ unsigned cvt_pk_bf16(float lo, float hi) { unsigned r; asm volatile("v_cvt_pk_bf16_f32 %0, %1, %2" : "=v"(r) : "v"(lo), "v"(hi)); return r; }
; #define PG8_WAIT_V(n) asm volatile("s_waitcnt vmcnt(" #n ")" ::: "memory")
; #define PG8_BAR __builtin_amdgcn_s_barrier()
; template <class Epi>
; __device__ __forceinline__ void gemm_phase(LAS unsigned char* lds, const Gemm g, const StaticOrder& S, const Epi& E) {
;     ...
;         E(acc, cur, wr, wc, fr, fq);
;         if (!has_next) break;
; #pragma unroll
;         for (int a = 0; a < 2; ++a)
; #pragma unroll
;             for (int b = 0; b < 2; ++b)
; #pragma unroll
;                 for (int m = 0; m < 4; ++m)
; #pragma unroll
;                     for (int n = 0; n < 2; ++n) acc[a][b][m][n] = (f32x4){0.f, 0.f, 0.f, 0.f};
;         cur = nxt; cA = nA; cB = nB; ++ui;
;     }
;     PG8_WAIT_V(0);
;     if (wr == 0) PG8_BAR;
;     PG8_BAR;
; __device__ __forceinline__ u32x4 pack8(f32x4 v0, f32x4 v1) { u32x4 w; w.x = cvt_pk_bf16(v0[0], v0[1]); w.y = cvt_pk_bf16(v0[2], v0[3]); w.z = cvt_pk_bf16(v1[0], v1[1]); w.w = cvt_pk_bf16(v1[2], v1[3]); return w; }
;     __device__ __forceinline__ void operator()(const f32x4 (&acc)[2][2][4][2], const Unit& u, int wr, int wc, int fr, int fq) const {
;         const int row0 = u.pm * BM + wr * 64 + fr, col0 = u.pn * BM + wc * 32 + 8 * fq;
; #pragma unroll
;         for (int ai = 0; ai < 2; ++ai)
; #pragma unroll
;             for (int m = 0; m < 4; ++m) { bf16_t* rowp = O + (size_t)(row0 + ai * HALF + m * 16) * ldc + col0;
; #pragma unroll
;                 for (int bj = 0; bj < 2; ++bj) *(u32x4*)(rowp + bj * HALF) = pack8(acc[ai][bj][m][0], acc[ai][bj][m][1]); }
	v_lshl_add_u32 v148, s63, 8, v142
	v_lshl_or_b32 v140, s64, 8, v144
	v_ashrrev_i32_e32 v149, 31, v148
	v_ashrrev_i32_e32 v141, 31, v140
	v_lshlrev_b64 v[150:151], 12, v[148:149]
	v_lshl_add_u64 v[150:151], s[24:25], 0, v[150:151]
	v_lshlrev_b64 v[152:153], 1, v[140:141]
	v_lshl_add_u64 v[140:141], v[150:151], 0, v[152:153]
	v_cvt_pk_bf16_f32 v124, v124, v125
	v_cvt_pk_bf16_f32 v125, v126, v127
	v_cvt_pk_bf16_f32 v126, v120, v121
	v_cvt_pk_bf16_f32 v127, v122, v123
	global_store_dwordx4 v[140:141], v[124:127], off
	v_cvt_pk_bf16_f32 v116, v116, v117
	v_cvt_pk_bf16_f32 v117, v118, v119
	v_cvt_pk_bf16_f32 v118, v108, v109
	v_or_b32_e32 v108, 16, v148
	v_ashrrev_i32_e32 v109, 31, v108
	v_lshlrev_b64 v[108:109], 12, v[108:109]
	v_lshl_add_u64 v[108:109], s[24:25], 0, v[108:109]
	v_cvt_pk_bf16_f32 v119, v110, v111
	global_store_dwordx4 v[140:141], v[116:119], off offset:256
	s_mov_b32 s64, s61
	s_mov_b32 s63, s62
	v_lshl_add_u64 v[116:117], v[108:109], 0, v[152:153]
	v_cvt_pk_bf16_f32 v108, v112, v113
	v_cvt_pk_bf16_f32 v109, v114, v115
	v_cvt_pk_bf16_f32 v110, v104, v105
	v_cvt_pk_bf16_f32 v111, v106, v107
	global_store_dwordx4 v[116:117], v[108:111], off
	v_cvt_pk_bf16_f32 v100, v100, v101
	v_cvt_pk_bf16_f32 v101, v102, v103
	v_cvt_pk_bf16_f32 v102, v92, v93
	v_or_b32_e32 v92, 32, v148
	v_ashrrev_i32_e32 v93, 31, v92
	v_lshlrev_b64 v[92:93], 12, v[92:93]
	v_lshl_add_u64 v[92:93], s[24:25], 0, v[92:93]
	v_cvt_pk_bf16_f32 v103, v94, v95
	global_store_dwordx4 v[116:117], v[100:103], off offset:256
	s_mov_b64 s[44:45], s[6:7]
	s_mov_b64 s[42:43], s[40:41]
	v_lshl_add_u64 v[100:101], v[92:93], 0, v[152:153]
	v_cvt_pk_bf16_f32 v92, v96, v97
	v_cvt_pk_bf16_f32 v93, v98, v99
	v_cvt_pk_bf16_f32 v94, v88, v89
	v_cvt_pk_bf16_f32 v95, v90, v91
	global_store_dwordx4 v[100:101], v[92:95], off
	v_cvt_pk_bf16_f32 v84, v84, v85
	v_cvt_pk_bf16_f32 v85, v86, v87
	v_cvt_pk_bf16_f32 v86, v76, v77
	v_or_b32_e32 v76, 48, v148
	v_ashrrev_i32_e32 v77, 31, v76
	v_lshlrev_b64 v[76:77], 12, v[76:77]
	v_lshl_add_u64 v[76:77], s[24:25], 0, v[76:77]
	v_cvt_pk_bf16_f32 v87, v78, v79
	global_store_dwordx4 v[100:101], v[84:87], off offset:256
	s_nop 1
	v_lshl_add_u64 v[84:85], v[76:77], 0, v[152:153]
	v_cvt_pk_bf16_f32 v76, v80, v81
	v_cvt_pk_bf16_f32 v77, v82, v83
	v_cvt_pk_bf16_f32 v78, v72, v73
	v_cvt_pk_bf16_f32 v79, v74, v75
	global_store_dwordx4 v[84:85], v[76:79], off
	v_cvt_pk_bf16_f32 v68, v68, v69
	v_cvt_pk_bf16_f32 v69, v70, v71
	v_cvt_pk_bf16_f32 v70, v64, v65
	v_cvt_pk_bf16_f32 v71, v66, v67
	global_store_dwordx4 v[84:85], v[68:71], off offset:256
	v_cvt_pk_bf16_f32 v60, v60, v61
	v_cvt_pk_bf16_f32 v61, v62, v63
	v_cvt_pk_bf16_f32 v62, v56, v57
	v_add_co_u32_e32 v56, vcc, s57, v140
	v_lshl_add_u64 v[64:65], v[140:141], 0, s[8:9]
	s_nop 0
	v_addc_co_u32_e32 v57, vcc, 0, v141, vcc
	v_cvt_pk_bf16_f32 v63, v58, v59
	global_store_dwordx4 v[56:57], v[60:63], off
	v_cvt_pk_bf16_f32 v48, v48, v49
	v_cvt_pk_bf16_f32 v49, v50, v51
	v_cvt_pk_bf16_f32 v50, v40, v41
	v_cvt_pk_bf16_f32 v51, v42, v43
	global_store_dwordx4 v[64:65], v[48:51], off offset:256
	v_cvt_pk_bf16_f32 v40, v52, v53
	v_cvt_pk_bf16_f32 v41, v54, v55
	v_cvt_pk_bf16_f32 v42, v44, v45
	v_add_co_u32_e32 v44, vcc, s58, v140
	s_nop 0
	v_lshl_add_u64 v[48:49], v[140:141], 0, s[30:31]
	v_addc_co_u32_e32 v45, vcc, 0, v141, vcc
	v_cvt_pk_bf16_f32 v43, v46, v47
	global_store_dwordx4 v[44:45], v[40:43], off
	v_cvt_pk_bf16_f32 v32, v32, v33
	v_cvt_pk_bf16_f32 v33, v34, v35
	v_cvt_pk_bf16_f32 v34, v24, v25
	v_cvt_pk_bf16_f32 v35, v26, v27
	global_store_dwordx4 v[48:49], v[32:35], off offset:256
	v_cvt_pk_bf16_f32 v24, v36, v37
	v_cvt_pk_bf16_f32 v25, v38, v39
	v_cvt_pk_bf16_f32 v26, v28, v29
	v_add_co_u32_e32 v28, vcc, s59, v140
	s_nop 0
	v_lshl_add_u64 v[32:33], v[140:141], 0, s[34:35]
	v_addc_co_u32_e32 v29, vcc, 0, v141, vcc
	v_cvt_pk_bf16_f32 v27, v30, v31
	global_store_dwordx4 v[28:29], v[24:27], off
	v_cvt_pk_bf16_f32 v16, v16, v17
	v_cvt_pk_bf16_f32 v17, v18, v19
	v_cvt_pk_bf16_f32 v18, v8, v9
	v_cvt_pk_bf16_f32 v19, v10, v11
	global_store_dwordx4 v[32:33], v[16:19], off offset:256
	v_cvt_pk_bf16_f32 v8, v20, v21
	v_cvt_pk_bf16_f32 v9, v22, v23
	v_cvt_pk_bf16_f32 v10, v12, v13
	v_add_co_u32_e32 v12, vcc, s60, v140
	s_nop 0
	v_lshl_add_u64 v[16:17], v[140:141], 0, s[36:37]
	v_addc_co_u32_e32 v13, vcc, 0, v141, vcc
	s_and_b64 vcc, exec, s[38:39]
	v_cvt_pk_bf16_f32 v11, v14, v15
	global_store_dwordx4 v[12:13], v[8:11], off
	v_cvt_pk_bf16_f32 v4, v4, v5
	v_cvt_pk_bf16_f32 v5, v6, v7
	v_cvt_pk_bf16_f32 v6, v0, v1
	v_cvt_pk_bf16_f32 v7, v2, v3
	global_store_dwordx4 v[16:17], v[4:7], off offset:256
	s_cbranch_vccz .LBB0_857
	s_waitcnt vmcnt(0)
	s_cmpk_gt_u32 s10, 0xff
	v_readlane_b32 s62, v232, 20
	v_readlane_b32 s61, v232, 21
	s_cbranch_scc1 .LBB0_868
	s_barrier

; #define PG8_STAGE(bufoff, gbase, voff) do { _Pragma("unroll") for (int _i = 0; _i < 2; ++_i) \
;         __builtin_amdgcn_global_load_lds((const unsigned*)((const char*)(gbase) + (voff)[_i]), (LAS unsigned*)(lds + (bufoff) + ldsw + _i * 8192), 16, 0, 0); } while (0)
; #define PG8_LDA(dst, b, h) do { _Pragma("unroll") for (int m = 0; m < 4; ++m) _Pragma("unroll") for (int k = 0; k < 2; ++k) dst[m][k] = *(const LAS bf16x8*)(lds + PG8_SA(b, h) + aoff + m * 2048 + k * 1024); } while (0)
; #define PG8_LDB(dst, b, h) do { _Pragma("unroll") for (int n = 0; n < 2; ++n) _Pragma("unroll") for (int k = 0; k < 2; ++k) dst[n][k] = *(const LAS bf16x8*)(lds + PG8_SB(b, h) + boff + n * 2048 + k * 1024); } while (0)
; #define PG8_MMA(ai, bj, At, Bt) do { __builtin_amdgcn_s_setprio(1); _Pragma("unroll") for (int m = 0; m < 4; ++m) _Pragma("unroll") for (int n = 0; n < 2; ++n) _Pragma("unroll") for (int k = 0; k < 2; ++k) \
;         acc[ai][bj][m][n] = __builtin_amdgcn_mfma_f32_16x16x32_bf16(Bt[n][k], At[m][k], acc[ai][bj][m][n], 0, 0, 0); __builtin_amdgcn_s_setprio(0); } while (0)
; #define PG8_WAIT_V(n) asm volatile("s_waitcnt vmcnt(" #n ")" ::: "memory")
; #define PG8_WAIT_L(n) asm volatile("s_waitcnt lgkmcnt(" #n ")" ::: "memory")
; #define PG8_BAR __builtin_amdgcn_s_barrier()
; #define PG8_SCHED __builtin_amdgcn_sched_barrier(0)
; template <class Epi>
; __device__ __forceinline__ void gemm_phase(LAS unsigned char* lds, const Gemm g, const StaticOrder& S, const Epi& E) {
;     ...
;             PG8_LDB(B0, 0, 0); PG8_SCHED; PG8_LDA(At, 0, 0); PG8_STAGE(PG8_SA(1, 1), a1 + hstep, voffA);
;             PG8_WAIT_L(8); PG8_BAR; PG8_WAIT_L(0); PG8_MMA(0, 0, At, B0); PG8_BAR; PG8_SCHED;
;             PG8_LDB(B1, 0, 1); PG8_STAGE(PG8_SB(0, 0), b2, voffB);
;             PG8_BAR; PG8_WAIT_L(0); PG8_MMA(0, 1, At, B1); PG8_BAR;
;             PG8_LDA(At, 0, 1); PG8_STAGE(PG8_SA(0, 0), a2, voffA);
;             PG8_BAR; PG8_WAIT_L(0); PG8_MMA(1, 0, At, B0); PG8_BAR; PG8_SCHED;
;             PG8_STAGE(PG8_SB(0, 1), b2 + hstep, voffB);
;             PG8_WAIT_V(6); PG8_BAR; PG8_MMA(1, 1, At, B1); PG8_BAR;
.LBB0_999:
	ds_read_b128 v[140:143], v151
	ds_read_b128 v[144:147], v151 offset:1024
	ds_read_b128 v[154:157], v151 offset:2048
	ds_read_b128 v[160:163], v151 offset:3072
	s_add_u32 s48, s46, 0xfff80080
	s_addc_u32 s49, s47, -1
	s_cmp_eq_u32 s63, 28
	s_cselect_b32 s51, s37, s49
	s_cselect_b32 s50, s59, s48
	s_cselect_b32 s49, s35, s62
	s_cselect_b32 s48, s60, s61
	s_add_i32 m0, s28, 0xc000
	ds_read_b128 v[164:167], v152
	ds_read_b128 v[168:171], v152 offset:1024
	ds_read_b128 v[172:175], v152 offset:2048
	ds_read_b128 v[176:179], v152 offset:3072
	ds_read_b128 v[180:183], v152 offset:4096
	ds_read_b128 v[184:187], v152 offset:5120
	ds_read_b128 v[188:191], v152 offset:6144
	ds_read_b128 v[192:195], v152 offset:7168
	global_load_lds_dwordx4 v136, s[46:47]
	s_add_i32 m0, s28, 0xe000
	s_nop 0
	global_load_lds_dwordx4 v138, s[46:47]
	s_waitcnt lgkmcnt(8)
	s_barrier
	s_waitcnt lgkmcnt(0)
	s_setprio 1
	s_waitcnt lgkmcnt(0)
	v_mfma_f32_16x16x32_bf16 v[124:127], v[140:143], v[164:167], v[124:127]
	v_mfma_f32_16x16x32_bf16 v[120:123], v[154:157], v[164:167], v[120:123]
	v_mfma_f32_16x16x32_bf16 v[108:111], v[140:143], v[172:175], v[108:111]
	v_mfma_f32_16x16x32_bf16 v[104:107], v[154:157], v[172:175], v[104:107]
	v_mfma_f32_16x16x32_bf16 v[92:95], v[140:143], v[180:183], v[92:95]
	v_mfma_f32_16x16x32_bf16 v[88:91], v[154:157], v[180:183], v[88:91]
	v_mfma_f32_16x16x32_bf16 v[76:79], v[140:143], v[188:191], v[76:79]
	v_mfma_f32_16x16x32_bf16 v[72:75], v[154:157], v[188:191], v[72:75]
	v_mfma_f32_16x16x32_bf16 v[124:127], v[144:147], v[168:171], v[124:127]
	v_mfma_f32_16x16x32_bf16 v[120:123], v[160:163], v[168:171], v[120:123]
	v_mfma_f32_16x16x32_bf16 v[108:111], v[144:147], v[176:179], v[108:111]
	v_mfma_f32_16x16x32_bf16 v[104:107], v[160:163], v[176:179], v[104:107]
	v_mfma_f32_16x16x32_bf16 v[92:95], v[144:147], v[184:187], v[92:95]
	v_mfma_f32_16x16x32_bf16 v[88:91], v[160:163], v[184:187], v[88:91]
	v_mfma_f32_16x16x32_bf16 v[76:79], v[144:147], v[192:195], v[76:79]
	v_mfma_f32_16x16x32_bf16 v[72:75], v[160:163], v[192:195], v[72:75]
	s_setprio 0
	s_barrier
	s_add_i32 s64, s56, s23
	s_add_u32 s98, s48, s4
	s_addc_u32 s99, s49, s5
	s_mov_b32 m0, s64
	ds_read_b128 v[196:199], v153
	ds_read_b128 v[200:203], v153 offset:1024
	ds_read_b128 v[204:207], v153 offset:2048
	ds_read_b128 v[208:211], v153 offset:3072
	global_load_lds_dwordx4 v132, s[48:49]
	s_add_i32 m0, s64, 0x2000
	s_nop 0
	global_load_lds_dwordx4 v128, s[48:49]
	s_barrier
	s_waitcnt lgkmcnt(0)
	s_setprio 1
	s_waitcnt lgkmcnt(0)
	v_mfma_f32_16x16x32_bf16 v[116:119], v[196:199], v[164:167], v[116:119]
	v_mfma_f32_16x16x32_bf16 v[112:115], v[204:207], v[164:167], v[112:115]
	v_mfma_f32_16x16x32_bf16 v[100:103], v[196:199], v[172:175], v[100:103]
	v_mfma_f32_16x16x32_bf16 v[96:99], v[204:207], v[172:175], v[96:99]
	v_mfma_f32_16x16x32_bf16 v[84:87], v[196:199], v[180:183], v[84:87]
	v_mfma_f32_16x16x32_bf16 v[80:83], v[204:207], v[180:183], v[80:83]
	v_mfma_f32_16x16x32_bf16 v[68:71], v[196:199], v[188:191], v[68:71]
	v_mfma_f32_16x16x32_bf16 v[64:67], v[204:207], v[188:191], v[64:67]
	v_mfma_f32_16x16x32_bf16 v[116:119], v[200:203], v[168:171], v[116:119]
	v_mfma_f32_16x16x32_bf16 v[112:115], v[208:211], v[168:171], v[112:115]
	v_mfma_f32_16x16x32_bf16 v[100:103], v[200:203], v[176:179], v[100:103]
	v_mfma_f32_16x16x32_bf16 v[96:99], v[208:211], v[176:179], v[96:99]
	v_mfma_f32_16x16x32_bf16 v[84:87], v[200:203], v[184:187], v[84:87]
	v_mfma_f32_16x16x32_bf16 v[80:83], v[208:211], v[184:187], v[80:83]
	v_mfma_f32_16x16x32_bf16 v[68:71], v[200:203], v[192:195], v[68:71]
	v_mfma_f32_16x16x32_bf16 v[64:67], v[208:211], v[192:195], v[64:67]
	s_setprio 0
	s_mov_b32 m0, s28
	s_add_u32 s100, s50, s4
	s_addc_u32 s101, s51, s5
	s_barrier
	ds_read_b128 v[164:167], v152 offset:16384
	ds_read_b128 v[168:171], v152 offset:17408
	ds_read_b128 v[172:175], v152 offset:18432
	ds_read_b128 v[176:179], v152 offset:19456
	ds_read_b128 v[180:183], v152 offset:20480
	ds_read_b128 v[184:187], v152 offset:21504
	ds_read_b128 v[188:191], v152 offset:22528
	ds_read_b128 v[192:195], v152 offset:23552
	global_load_lds_dwordx4 v134, s[50:51]
	s_mov_b32 m0, s29
	s_nop 0
	global_load_lds_dwordx4 v130, s[50:51]
	s_barrier
	s_waitcnt lgkmcnt(0)
	s_setprio 1
	s_waitcnt lgkmcnt(0)
	v_mfma_f32_16x16x32_bf16 v[60:63], v[140:143], v[164:167], v[60:63]
	v_mfma_f32_16x16x32_bf16 v[56:59], v[154:157], v[164:167], v[56:59]
	v_mfma_f32_16x16x32_bf16 v[44:47], v[140:143], v[172:175], v[44:47]
	v_mfma_f32_16x16x32_bf16 v[40:43], v[154:157], v[172:175], v[40:43]
	v_mfma_f32_16x16x32_bf16 v[28:31], v[140:143], v[180:183], v[28:31]
	v_mfma_f32_16x16x32_bf16 v[24:27], v[154:157], v[180:183], v[24:27]
	v_mfma_f32_16x16x32_bf16 v[12:15], v[140:143], v[188:191], v[12:15]
	v_mfma_f32_16x16x32_bf16 v[8:11], v[154:157], v[188:191], v[8:11]
	v_mfma_f32_16x16x32_bf16 v[60:63], v[144:147], v[168:171], v[60:63]
	v_mfma_f32_16x16x32_bf16 v[56:59], v[160:163], v[168:171], v[56:59]
	v_mfma_f32_16x16x32_bf16 v[44:47], v[144:147], v[176:179], v[44:47]
	v_mfma_f32_16x16x32_bf16 v[40:43], v[160:163], v[176:179], v[40:43]
	v_mfma_f32_16x16x32_bf16 v[28:31], v[144:147], v[184:187], v[28:31]
	v_mfma_f32_16x16x32_bf16 v[24:27], v[160:163], v[184:187], v[24:27]
	v_mfma_f32_16x16x32_bf16 v[12:15], v[144:147], v[192:195], v[12:15]
	v_mfma_f32_16x16x32_bf16 v[8:11], v[160:163], v[192:195], v[8:11]
	s_setprio 0
	s_barrier
	s_add_u32 s64, s48, 0x80000
	s_addc_u32 s65, s49, 0
	s_add_i32 s66, s57, s23
	s_mov_b32 m0, s66
	s_nop 0
	global_load_lds_dwordx4 v132, s[64:65]
	s_add_i32 m0, s66, 0x2000
	s_nop 0
	global_load_lds_dwordx4 v128, s[64:65]
	s_waitcnt vmcnt(6)
	s_barrier
; #define PG8_STAGE(bufoff, gbase, voff) do { _Pragma("unroll") for (int _i = 0; _i < 2; ++_i) \
;         __builtin_amdgcn_global_load_lds((const unsigned*)((const char*)(gbase) + (voff)[_i]), (LAS unsigned*)(lds + (bufoff) + ldsw + _i * 8192), 16, 0, 0); } while (0)
; #define PG8_LDA(dst, b, h) do { _Pragma("unroll") for (int m = 0; m < 4; ++m) _Pragma("unroll") for (int k = 0; k < 2; ++k) dst[m][k] = *(const LAS bf16x8*)(lds + PG8_SA(b, h) + aoff + m * 2048 + k * 1024); } while (0)
; #define PG8_LDB(dst, b, h) do { _Pragma("unroll") for (int n = 0; n < 2; ++n) _Pragma("unroll") for (int k = 0; k < 2; ++k) dst[n][k] = *(const LAS bf16x8*)(lds + PG8_SB(b, h) + boff + n * 2048 + k * 1024); } while (0)
; #define PG8_MMA(ai, bj, At, Bt) do { __builtin_amdgcn_s_setprio(1); _Pragma("unroll") for (int m = 0; m < 4; ++m) _Pragma("unroll") for (int n = 0; n < 2; ++n) _Pragma("unroll") for (int k = 0; k < 2; ++k) \
;         acc[ai][bj][m][n] = __builtin_amdgcn_mfma_f32_16x16x32_bf16(Bt[n][k], At[m][k], acc[ai][bj][m][n], 0, 0, 0); __builtin_amdgcn_s_setprio(0); } while (0)
; #define PG8_WAIT_V(n) asm volatile("s_waitcnt vmcnt(" #n ")" ::: "memory")
; #define PG8_WAIT_L(n) asm volatile("s_waitcnt lgkmcnt(" #n ")" ::: "memory")
; #define PG8_BAR __builtin_amdgcn_s_barrier()
; #define PG8_SCHED __builtin_amdgcn_sched_barrier(0)
; template <class Epi>
; __device__ __forceinline__ void gemm_phase(LAS unsigned char* lds, const Gemm g, const StaticOrder& S, const Epi& E) {
;     ...
;             PG8_WAIT_V(6); PG8_BAR; PG8_MMA(1, 1, At, B1); PG8_BAR;
;             PG8_LDB(B0, 1, 0); PG8_SCHED; PG8_LDA(At, 1, 0); PG8_STAGE(PG8_SA(0, 1), a2 + hstep, voffA);
;             PG8_WAIT_L(8); PG8_BAR; PG8_WAIT_L(0); PG8_MMA(0, 0, At, B0); PG8_BAR; PG8_SCHED;
;             PG8_LDB(B1, 1, 1); PG8_STAGE(PG8_SB(1, 0), b3, voffB);
;             PG8_BAR; PG8_WAIT_L(0); PG8_MMA(0, 1, At, B1); PG8_BAR;
;             PG8_LDA(At, 1, 1); PG8_STAGE(PG8_SA(1, 0), a3, voffA);
	s_setprio 1
	v_mfma_f32_16x16x32_bf16 v[52:55], v[196:199], v[164:167], v[52:55]
	v_mfma_f32_16x16x32_bf16 v[48:51], v[204:207], v[164:167], v[48:51]
	v_mfma_f32_16x16x32_bf16 v[36:39], v[196:199], v[172:175], v[36:39]
	v_mfma_f32_16x16x32_bf16 v[32:35], v[204:207], v[172:175], v[32:35]
	v_mfma_f32_16x16x32_bf16 v[20:23], v[196:199], v[180:183], v[20:23]
	v_mfma_f32_16x16x32_bf16 v[16:19], v[204:207], v[180:183], v[16:19]
	v_mfma_f32_16x16x32_bf16 v[4:7], v[196:199], v[188:191], v[4:7]
	v_mfma_f32_16x16x32_bf16 v[0:3], v[204:207], v[188:191], v[0:3]
	v_mfma_f32_16x16x32_bf16 v[52:55], v[200:203], v[168:171], v[52:55]
	v_mfma_f32_16x16x32_bf16 v[48:51], v[208:211], v[168:171], v[48:51]
	v_mfma_f32_16x16x32_bf16 v[36:39], v[200:203], v[176:179], v[36:39]
	v_mfma_f32_16x16x32_bf16 v[32:35], v[208:211], v[176:179], v[32:35]
	v_mfma_f32_16x16x32_bf16 v[20:23], v[200:203], v[184:187], v[20:23]
	v_mfma_f32_16x16x32_bf16 v[16:19], v[208:211], v[184:187], v[16:19]
	v_mfma_f32_16x16x32_bf16 v[4:7], v[200:203], v[192:195], v[4:7]
	v_mfma_f32_16x16x32_bf16 v[0:3], v[208:211], v[192:195], v[0:3]
	s_setprio 0
	s_add_i32 s64, 0, 0x18000
	v_add_u32_e32 v160, s64, v149
	s_barrier
	ds_read_b128 v[140:143], v160
	ds_read_b128 v[144:147], v160 offset:1024
	ds_read_b128 v[154:157], v160 offset:2048
	ds_read_b128 v[160:163], v160 offset:3072
	s_add_u32 s50, s50, 0x80000
	s_addc_u32 s51, s51, 0
	s_mov_b32 m0, s33
	ds_read_b128 v[164:167], v152 offset:32768
	ds_read_b128 v[168:171], v152 offset:33792
	ds_read_b128 v[172:175], v152 offset:34816
	ds_read_b128 v[176:179], v152 offset:35840
	ds_read_b128 v[180:183], v152 offset:36864
	ds_read_b128 v[184:187], v152 offset:37888
	ds_read_b128 v[188:191], v152 offset:38912
	ds_read_b128 v[192:195], v152 offset:39936
	global_load_lds_dwordx4 v134, s[50:51]
	s_mov_b32 m0, s45
	s_nop 0
	global_load_lds_dwordx4 v130, s[50:51]
	s_waitcnt lgkmcnt(8)
	s_barrier
	s_waitcnt lgkmcnt(0)
	s_setprio 1
	s_waitcnt lgkmcnt(0)
	v_mfma_f32_16x16x32_bf16 v[124:127], v[140:143], v[164:167], v[124:127]
	v_mfma_f32_16x16x32_bf16 v[120:123], v[154:157], v[164:167], v[120:123]
	v_mfma_f32_16x16x32_bf16 v[108:111], v[140:143], v[172:175], v[108:111]
	v_mfma_f32_16x16x32_bf16 v[104:107], v[154:157], v[172:175], v[104:107]
	v_mfma_f32_16x16x32_bf16 v[92:95], v[140:143], v[180:183], v[92:95]
	v_mfma_f32_16x16x32_bf16 v[88:91], v[154:157], v[180:183], v[88:91]
	v_mfma_f32_16x16x32_bf16 v[76:79], v[140:143], v[188:191], v[76:79]
	v_mfma_f32_16x16x32_bf16 v[72:75], v[154:157], v[188:191], v[72:75]
	v_mfma_f32_16x16x32_bf16 v[124:127], v[144:147], v[168:171], v[124:127]
	v_mfma_f32_16x16x32_bf16 v[120:123], v[160:163], v[168:171], v[120:123]
	v_mfma_f32_16x16x32_bf16 v[108:111], v[144:147], v[176:179], v[108:111]
	v_mfma_f32_16x16x32_bf16 v[104:107], v[160:163], v[176:179], v[104:107]
	v_mfma_f32_16x16x32_bf16 v[92:95], v[144:147], v[184:187], v[92:95]
	v_mfma_f32_16x16x32_bf16 v[88:91], v[160:163], v[184:187], v[88:91]
	v_mfma_f32_16x16x32_bf16 v[76:79], v[144:147], v[192:195], v[76:79]
	v_mfma_f32_16x16x32_bf16 v[72:75], v[160:163], v[192:195], v[72:75]
	s_setprio 0
	s_barrier
	s_add_i32 s50, 0, 0x1c000
	s_add_i32 s51, s64, s23
	v_add_u32_e32 v208, s50, v149
	s_mov_b32 m0, s51
	ds_read_b128 v[196:199], v208
	ds_read_b128 v[200:203], v208 offset:1024
	ds_read_b128 v[204:207], v208 offset:2048
	ds_read_b128 v[208:211], v208 offset:3072
	global_load_lds_dwordx4 v132, s[98:99]
	s_add_i32 m0, s51, 0x2000
	s_nop 0
	global_load_lds_dwordx4 v128, s[98:99]
	s_barrier
	s_waitcnt lgkmcnt(0)
	s_setprio 1
	s_waitcnt lgkmcnt(0)
	v_mfma_f32_16x16x32_bf16 v[116:119], v[196:199], v[164:167], v[116:119]
	v_mfma_f32_16x16x32_bf16 v[112:115], v[204:207], v[164:167], v[112:115]
	v_mfma_f32_16x16x32_bf16 v[100:103], v[196:199], v[172:175], v[100:103]
	v_mfma_f32_16x16x32_bf16 v[96:99], v[204:207], v[172:175], v[96:99]
	v_mfma_f32_16x16x32_bf16 v[84:87], v[196:199], v[180:183], v[84:87]
	v_mfma_f32_16x16x32_bf16 v[80:83], v[204:207], v[180:183], v[80:83]
	v_mfma_f32_16x16x32_bf16 v[68:71], v[196:199], v[188:191], v[68:71]
	v_mfma_f32_16x16x32_bf16 v[64:67], v[204:207], v[188:191], v[64:67]
	v_mfma_f32_16x16x32_bf16 v[116:119], v[200:203], v[168:171], v[116:119]
	v_mfma_f32_16x16x32_bf16 v[112:115], v[208:211], v[168:171], v[112:115]
	v_mfma_f32_16x16x32_bf16 v[100:103], v[200:203], v[176:179], v[100:103]
	v_mfma_f32_16x16x32_bf16 v[96:99], v[208:211], v[176:179], v[96:99]
	v_mfma_f32_16x16x32_bf16 v[84:87], v[200:203], v[184:187], v[84:87]
	v_mfma_f32_16x16x32_bf16 v[80:83], v[208:211], v[184:187], v[80:83]
	v_mfma_f32_16x16x32_bf16 v[68:71], v[200:203], v[192:195], v[68:71]
	v_mfma_f32_16x16x32_bf16 v[64:67], v[208:211], v[192:195], v[64:67]
	s_setprio 0
	s_mov_b32 m0, s53
	s_barrier
	ds_read_b128 v[164:167], v152 offset:49152
	ds_read_b128 v[168:171], v152 offset:50176
	ds_read_b128 v[172:175], v152 offset:51200
	ds_read_b128 v[176:179], v152 offset:52224
	ds_read_b128 v[180:183], v152 offset:53248
	ds_read_b128 v[184:187], v152 offset:54272
	ds_read_b128 v[188:191], v152 offset:55296
	ds_read_b128 v[192:195], v152 offset:56320
	global_load_lds_dwordx4 v134, s[100:101]
	s_mov_b32 m0, s54
	s_nop 0
	global_load_lds_dwordx4 v130, s[100:101]
	s_barrier
; __device__ __forceinline__ float bf_lo(unsigned w) { return __uint_as_float(w << 16); }
; __device__ __forceinline__ float bf_hi(unsigned w) { return __uint_as_float(w & 0xffff0000u); }
; __device__ __forceinline__ float fast_rcp(float x) { return __builtin_amdgcn_rcpf(x); }
; __device__ __forceinline__ float fast_exp2(float x) { return __builtin_amdgcn_exp2f(x); }
; #define PG8_STAGE(bufoff, gbase, voff) do { _Pragma("unroll") for (int _i = 0; _i < 2; ++_i) \
;         __builtin_amdgcn_global_load_lds((const unsigned*)((const char*)(gbase) + (voff)[_i]), (LAS unsigned*)(lds + (bufoff) + ldsw + _i * 8192), 16, 0, 0); } while (0)
; #define PG8_MMA(ai, bj, At, Bt) do { __builtin_amdgcn_s_setprio(1); _Pragma("unroll") for (int m = 0; m < 4; ++m) _Pragma("unroll") for (int n = 0; n < 2; ++n) _Pragma("unroll") for (int k = 0; k < 2; ++k) \
;         acc[ai][bj][m][n] = __builtin_amdgcn_mfma_f32_16x16x32_bf16(Bt[n][k], At[m][k], acc[ai][bj][m][n], 0, 0, 0); __builtin_amdgcn_s_setprio(0); } while (0)
; #define PG8_BAR __builtin_amdgcn_s_barrier()
; template <class Epi>
; __device__ __forceinline__ void gemm_phase(LAS unsigned char* lds, const Gemm g, const StaticOrder& S, const Epi& E) {
;     ...
;             PG8_BAR; PG8_WAIT_L(0); PG8_MMA(1, 0, At, B0); PG8_BAR; PG8_SCHED;
;             PG8_STAGE(PG8_SB(1, 1), b3 + hstep, voffB);
;             PG8_WAIT_V(6); PG8_BAR; PG8_MMA(1, 1, At, B1); PG8_BAR;
;     __device__ __forceinline__ void operator()(const f32x4 (&acc)[2][2][4][2], const Unit& u, int wr, int wc, int fr, int fq) const {
;     ...
;             for (int m = 0; m < 4; ++m) { const size_t ro = (size_t)(row0 + ai * HALF + m * 16) * DM + col0; const float nr = -LOG2E * rs[row0 + ai * HALF + m * 16];
; #pragma unroll
;                 for (int bj = 0; bj < 2; ++bj) {
;                     const u32x4 pw = *(const u32x4*)(PP + ro + bj * HALF);
;                     const float pv[8] = {bf_lo(pw.x), bf_hi(pw.x), bf_lo(pw.y), bf_hi(pw.y), bf_lo(pw.z), bf_hi(pw.z), bf_lo(pw.w), bf_hi(pw.w)};
;                     f32x4 t0, t1;
; #pragma unroll
;                     for (int j = 0; j < 4; ++j) {
;                         t0[j] = fast_rcp(1.0f + fast_exp2(acc[ai][bj][m][0][j] * nr)) * pv[j];
;                         t1[j] = fast_rcp(1.0f + fast_exp2(acc[ai][bj][m][1][j] * nr)) * pv[4 + j]; }
;                     *(u32x4*)(O + ro + bj * HALF) = pack8(t0, t1); } }
	s_waitcnt lgkmcnt(0)
	s_setprio 1
	s_waitcnt lgkmcnt(0)
	v_mfma_f32_16x16x32_bf16 v[60:63], v[140:143], v[164:167], v[60:63]
	v_mfma_f32_16x16x32_bf16 v[56:59], v[154:157], v[164:167], v[56:59]
	v_mfma_f32_16x16x32_bf16 v[44:47], v[140:143], v[172:175], v[44:47]
	v_mfma_f32_16x16x32_bf16 v[40:43], v[154:157], v[172:175], v[40:43]
	v_mfma_f32_16x16x32_bf16 v[28:31], v[140:143], v[180:183], v[28:31]
	v_mfma_f32_16x16x32_bf16 v[24:27], v[154:157], v[180:183], v[24:27]
	v_mfma_f32_16x16x32_bf16 v[12:15], v[140:143], v[188:191], v[12:15]
	v_mfma_f32_16x16x32_bf16 v[8:11], v[154:157], v[188:191], v[8:11]
	v_mfma_f32_16x16x32_bf16 v[60:63], v[144:147], v[168:171], v[60:63]
	v_mfma_f32_16x16x32_bf16 v[56:59], v[160:163], v[168:171], v[56:59]
	v_mfma_f32_16x16x32_bf16 v[44:47], v[144:147], v[176:179], v[44:47]
	v_mfma_f32_16x16x32_bf16 v[40:43], v[160:163], v[176:179], v[40:43]
	v_mfma_f32_16x16x32_bf16 v[28:31], v[144:147], v[184:187], v[28:31]
	v_mfma_f32_16x16x32_bf16 v[24:27], v[160:163], v[184:187], v[24:27]
	v_mfma_f32_16x16x32_bf16 v[12:15], v[144:147], v[192:195], v[12:15]
	v_mfma_f32_16x16x32_bf16 v[8:11], v[160:163], v[192:195], v[8:11]
	s_setprio 0
	s_barrier
	s_add_u32 s48, s48, 0x80080
	s_addc_u32 s49, s49, 0
	s_add_i32 s50, s50, s23
	s_mov_b32 m0, s50
	s_nop 0
	global_load_lds_dwordx4 v132, s[48:49]
	s_add_i32 m0, s50, 0x2000
	s_nop 0
	global_load_lds_dwordx4 v128, s[48:49]
	s_waitcnt vmcnt(6)
	s_barrier
	s_setprio 1
	v_mfma_f32_16x16x32_bf16 v[52:55], v[196:199], v[164:167], v[52:55]
	v_mfma_f32_16x16x32_bf16 v[48:51], v[204:207], v[164:167], v[48:51]
	v_mfma_f32_16x16x32_bf16 v[36:39], v[196:199], v[172:175], v[36:39]
	v_mfma_f32_16x16x32_bf16 v[32:35], v[204:207], v[172:175], v[32:35]
	v_mfma_f32_16x16x32_bf16 v[20:23], v[196:199], v[180:183], v[20:23]
	v_mfma_f32_16x16x32_bf16 v[16:19], v[204:207], v[180:183], v[16:19]
	v_mfma_f32_16x16x32_bf16 v[4:7], v[196:199], v[188:191], v[4:7]
	v_mfma_f32_16x16x32_bf16 v[0:3], v[204:207], v[188:191], v[0:3]
	v_mfma_f32_16x16x32_bf16 v[52:55], v[200:203], v[168:171], v[52:55]
	v_mfma_f32_16x16x32_bf16 v[48:51], v[208:211], v[168:171], v[48:51]
	v_mfma_f32_16x16x32_bf16 v[36:39], v[200:203], v[176:179], v[36:39]
	v_mfma_f32_16x16x32_bf16 v[32:35], v[208:211], v[176:179], v[32:35]
	v_mfma_f32_16x16x32_bf16 v[20:23], v[200:203], v[184:187], v[20:23]
	v_mfma_f32_16x16x32_bf16 v[16:19], v[208:211], v[184:187], v[16:19]
	v_mfma_f32_16x16x32_bf16 v[4:7], v[200:203], v[192:195], v[4:7]
	v_mfma_f32_16x16x32_bf16 v[0:3], v[208:211], v[192:195], v[0:3]
	s_setprio 0
	s_add_i32 s63, s63, 2
	s_add_u32 s46, s46, 0x100
	s_addc_u32 s47, s47, 0
	s_add_u32 s61, s61, 0x100
	s_addc_u32 s62, s62, 0
	s_cmp_gt_u32 s63, 29
	s_barrier
	s_cbranch_scc0 .LBB0_999
	v_lshl_add_u32 v144, s44, 8, v148
	v_ashrrev_i32_e32 v145, 31, v144
	v_lshl_add_u64 v[140:141], v[144:145], 2, s[14:15]
	global_load_dword v164, v[140:141], off
	v_lshl_or_b32 v146, s58, 8, v150
	v_ashrrev_i32_e32 v147, 31, v146
	v_lshlrev_b64 v[142:143], 11, v[144:145]
	v_lshl_add_u64 v[142:143], v[142:143], 0, v[146:147]
	v_lshlrev_b64 v[142:143], 1, v[142:143]
	v_lshl_add_u64 v[160:161], s[20:21], 0, v[142:143]
	global_load_dwordx4 v[154:157], v[160:161], off
	v_lshl_add_u64 v[162:163], s[24:25], 0, v[142:143]
	s_and_b64 vcc, exec, s[38:39]
	s_mov_b32 s58, s34
	s_mov_b32 s44, s36
	s_mov_b64 s[48:49], s[42:43]
	s_mov_b64 s[46:47], s[40:41]
	s_waitcnt vmcnt(0)
	v_mul_f32_e32 v145, 0xbfb8aa3b, v164
	v_mul_f32_e32 v124, v124, v145
	v_mul_f32_e32 v120, v120, v145
	v_mul_f32_e32 v125, v125, v145
	v_mul_f32_e32 v121, v121, v145
	v_mul_f32_e32 v126, v126, v145
	v_mul_f32_e32 v122, v122, v145
	v_mul_f32_e32 v127, v127, v145
	v_mul_f32_e32 v123, v123, v145
	v_exp_f32_e32 v124, v124
	v_exp_f32_e32 v120, v120
	v_exp_f32_e32 v125, v125
	v_exp_f32_e32 v121, v121
	v_exp_f32_e32 v126, v126
	v_exp_f32_e32 v122, v122
	v_exp_f32_e32 v127, v127
	v_exp_f32_e32 v123, v123
	v_add_f32_e32 v124, 1.0, v124
	v_add_f32_e32 v120, 1.0, v120
	v_add_f32_e32 v125, 1.0, v125
	v_add_f32_e32 v121, 1.0, v121
	v_add_f32_e32 v126, 1.0, v126
	v_add_f32_e32 v122, 1.0, v122
	v_add_f32_e32 v127, 1.0, v127
	v_add_f32_e32 v123, 1.0, v123
	v_rcp_f32_e32 v124, v124
	v_rcp_f32_e32 v120, v120
	v_rcp_f32_e32 v125, v125
	v_rcp_f32_e32 v121, v121
	v_rcp_f32_e32 v126, v126
	v_rcp_f32_e32 v122, v122
	v_rcp_f32_e32 v127, v127
	v_rcp_f32_e32 v123, v123
	v_lshlrev_b32_e32 v164, 16, v154
	v_and_b32_e32 v154, 0xffff0000, v154
	v_lshlrev_b32_e32 v165, 16, v155
	v_and_b32_e32 v155, 0xffff0000, v155
	v_lshlrev_b32_e32 v166, 16, v156
	v_and_b32_e32 v156, 0xffff0000, v156
	v_lshlrev_b32_e32 v167, 16, v157
	v_and_b32_e32 v157, 0xffff0000, v157
	v_mul_f32_e32 v124, v124, v164
	v_mul_f32_e32 v164, v120, v166
	v_mul_f32_e32 v120, v125, v154
	v_mul_f32_e32 v125, v121, v156
	v_mul_f32_e32 v121, v126, v165
	v_mul_f32_e32 v126, v122, v167
	v_mul_f32_e32 v122, v127, v155
	v_mul_f32_e32 v123, v123, v157
	v_cvt_pk_bf16_f32 v120, v124, v120
	v_cvt_pk_bf16_f32 v121, v121, v122
	v_cvt_pk_bf16_f32 v122, v164, v125
	v_cvt_pk_bf16_f32 v123, v126, v123
	global_store_dwordx4 v[162:163], v[120:123], off
	global_load_dwordx4 v[120:123], v[160:161], off offset:256
	v_mul_f32_e32 v116, v116, v145
	v_mul_f32_e32 v112, v112, v145
	v_mul_f32_e32 v117, v117, v145
	v_mul_f32_e32 v113, v113, v145
	v_mul_f32_e32 v118, v118, v145
	v_mul_f32_e32 v114, v114, v145
	v_mul_f32_e32 v119, v119, v145
	v_mul_f32_e32 v115, v115, v145
	v_exp_f32_e32 v116, v116
	v_exp_f32_e32 v112, v112
	v_exp_f32_e32 v117, v117
	v_exp_f32_e32 v113, v113
	v_exp_f32_e32 v118, v118
	v_exp_f32_e32 v114, v114
	v_exp_f32_e32 v119, v119
	v_exp_f32_e32 v115, v115
	v_add_f32_e32 v116, 1.0, v116
	v_add_f32_e32 v112, 1.0, v112
	v_add_f32_e32 v117, 1.0, v117
	v_add_f32_e32 v113, 1.0, v113
	v_add_f32_e32 v118, 1.0, v118
	v_add_f32_e32 v114, 1.0, v114
	v_add_f32_e32 v119, 1.0, v119
	v_add_f32_e32 v115, 1.0, v115
	v_rcp_f32_e32 v116, v116
	v_rcp_f32_e32 v112, v112
	v_rcp_f32_e32 v117, v117
	v_rcp_f32_e32 v113, v113
	v_rcp_f32_e32 v118, v118
	v_rcp_f32_e32 v114, v114
	v_rcp_f32_e32 v119, v119
	v_rcp_f32_e32 v115, v115
	v_or_b32_e32 v124, 16, v144
	v_ashrrev_i32_e32 v125, 31, v124
	v_lshlrev_b64 v[124:125], 11, v[124:125]
	v_lshl_add_u64 v[124:125], v[124:125], 0, v[146:147]
	v_lshlrev_b64 v[124:125], 1, v[124:125]
	v_lshl_add_u64 v[126:127], s[20:21], 0, v[124:125]
	s_waitcnt vmcnt(0)
; __device__ __forceinline__ float bf_lo(unsigned w) { return __uint_as_float(w << 16); }
; __device__ __forceinline__ float bf_hi(unsigned w) { return __uint_as_float(w & 0xffff0000u); }
; __device__ __forceinline__ float fast_rcp(float x) { return __builtin_amdgcn_rcpf(x); }
; __device__ __forceinline__ float fast_exp2(float x) { return __builtin_amdgcn_exp2f(x); }
; __device__ __forceinline__ u32x4 pack8(f32x4 v0, f32x4 v1) { u32x4 w; w.x = cvt_pk_bf16(v0[0], v0[1]); w.y = cvt_pk_bf16(v0[2], v0[3]); w.z = cvt_pk_bf16(v1[0], v1[1]); w.w = cvt_pk_bf16(v1[2], v1[3]); return w; }
;     __device__ __forceinline__ void operator()(const f32x4 (&acc)[2][2][4][2], const Unit& u, int wr, int wc, int fr, int fq) const {
;     ...
;             for (int m = 0; m < 4; ++m) { const size_t ro = (size_t)(row0 + ai * HALF + m * 16) * DM + col0; const float nr = -LOG2E * rs[row0 + ai * HALF + m * 16];
; #pragma unroll
;                 for (int bj = 0; bj < 2; ++bj) {
;                     const u32x4 pw = *(const u32x4*)(PP + ro + bj * HALF);
;                     const float pv[8] = {bf_lo(pw.x), bf_hi(pw.x), bf_lo(pw.y), bf_hi(pw.y), bf_lo(pw.z), bf_hi(pw.z), bf_lo(pw.w), bf_hi(pw.w)};
;                     f32x4 t0, t1;
; #pragma unroll
;                     for (int j = 0; j < 4; ++j) {
;                         t0[j] = fast_rcp(1.0f + fast_exp2(acc[ai][bj][m][0][j] * nr)) * pv[j];
;                         t1[j] = fast_rcp(1.0f + fast_exp2(acc[ai][bj][m][1][j] * nr)) * pv[4 + j]; }
;                     *(u32x4*)(O + ro + bj * HALF) = pack8(t0, t1); } }
	v_lshlrev_b32_e32 v145, 16, v120
	v_and_b32_e32 v120, 0xffff0000, v120
	v_lshlrev_b32_e32 v154, 16, v121
	v_and_b32_e32 v121, 0xffff0000, v121
	v_lshlrev_b32_e32 v155, 16, v122
	v_and_b32_e32 v122, 0xffff0000, v122
	v_lshlrev_b32_e32 v156, 16, v123
	v_and_b32_e32 v123, 0xffff0000, v123
	v_mul_f32_e32 v116, v116, v145
	v_mul_f32_e32 v145, v112, v155
	v_mul_f32_e32 v112, v117, v120
	v_mul_f32_e32 v117, v113, v122
	v_mul_f32_e32 v113, v118, v154
	v_mul_f32_e32 v118, v114, v156
	v_mul_f32_e32 v114, v119, v121
	v_mul_f32_e32 v115, v115, v123
	v_cvt_pk_bf16_f32 v112, v116, v112
	v_cvt_pk_bf16_f32 v113, v113, v114
	v_cvt_pk_bf16_f32 v114, v145, v117
	v_cvt_pk_bf16_f32 v115, v118, v115
	global_store_dwordx4 v[162:163], v[112:115], off offset:256
	global_load_dword v118, v[140:141], off offset:64
	s_nop 0
	global_load_dwordx4 v[112:115], v[126:127], off
	v_lshl_add_u64 v[116:117], s[24:25], 0, v[124:125]
	s_waitcnt vmcnt(0)
	v_mul_f32_e32 v118, 0xbfb8aa3b, v118
	v_mul_f32_e32 v108, v108, v118
	v_mul_f32_e32 v104, v104, v118
	v_mul_f32_e32 v109, v109, v118
	v_mul_f32_e32 v105, v105, v118
	v_mul_f32_e32 v110, v110, v118
	v_mul_f32_e32 v106, v106, v118
	v_mul_f32_e32 v111, v111, v118
	v_mul_f32_e32 v107, v107, v118
	v_exp_f32_e32 v108, v108
	v_exp_f32_e32 v104, v104
	v_exp_f32_e32 v109, v109
	v_exp_f32_e32 v105, v105
	v_exp_f32_e32 v110, v110
	v_exp_f32_e32 v106, v106
	v_exp_f32_e32 v111, v111
	v_exp_f32_e32 v107, v107
	v_add_f32_e32 v108, 1.0, v108
	v_add_f32_e32 v104, 1.0, v104
	v_add_f32_e32 v109, 1.0, v109
	v_add_f32_e32 v105, 1.0, v105
	v_add_f32_e32 v110, 1.0, v110
	v_add_f32_e32 v106, 1.0, v106
	v_add_f32_e32 v111, 1.0, v111
	v_add_f32_e32 v107, 1.0, v107
	v_rcp_f32_e32 v108, v108
	v_rcp_f32_e32 v104, v104
	v_rcp_f32_e32 v109, v109
	v_rcp_f32_e32 v105, v105
	v_rcp_f32_e32 v110, v110
	v_rcp_f32_e32 v106, v106
	v_rcp_f32_e32 v111, v111
	v_rcp_f32_e32 v107, v107
	v_lshlrev_b32_e32 v119, 16, v112
	v_and_b32_e32 v112, 0xffff0000, v112
	v_lshlrev_b32_e32 v120, 16, v113
	v_and_b32_e32 v113, 0xffff0000, v113
	v_lshlrev_b32_e32 v121, 16, v114
	v_and_b32_e32 v114, 0xffff0000, v114
	v_lshlrev_b32_e32 v122, 16, v115
	v_and_b32_e32 v115, 0xffff0000, v115
	v_mul_f32_e32 v108, v108, v119
	v_mul_f32_e32 v119, v104, v121
	v_mul_f32_e32 v104, v109, v112
	v_mul_f32_e32 v109, v105, v114
	v_mul_f32_e32 v105, v110, v120
	v_mul_f32_e32 v110, v106, v122
	v_mul_f32_e32 v106, v111, v113
	v_mul_f32_e32 v107, v107, v115
	v_cvt_pk_bf16_f32 v104, v108, v104
	v_cvt_pk_bf16_f32 v105, v105, v106
	v_cvt_pk_bf16_f32 v106, v119, v109
	v_cvt_pk_bf16_f32 v107, v110, v107
	global_store_dwordx4 v[116:117], v[104:107], off
	global_load_dwordx4 v[104:107], v[126:127], off offset:256
	v_mul_f32_e32 v100, v100, v118
	v_mul_f32_e32 v96, v96, v118
	v_mul_f32_e32 v101, v101, v118
	v_mul_f32_e32 v97, v97, v118
	v_mul_f32_e32 v102, v102, v118
	v_mul_f32_e32 v98, v98, v118
	v_mul_f32_e32 v103, v103, v118
	v_mul_f32_e32 v99, v99, v118
	v_exp_f32_e32 v100, v100
	v_exp_f32_e32 v96, v96
	v_exp_f32_e32 v101, v101
	v_exp_f32_e32 v97, v97
	v_exp_f32_e32 v102, v102
	v_exp_f32_e32 v98, v98
	v_exp_f32_e32 v103, v103
	v_exp_f32_e32 v99, v99
	v_add_f32_e32 v100, 1.0, v100
	v_add_f32_e32 v96, 1.0, v96
	v_add_f32_e32 v101, 1.0, v101
	v_add_f32_e32 v97, 1.0, v97
	v_add_f32_e32 v102, 1.0, v102
	v_add_f32_e32 v98, 1.0, v98
	v_add_f32_e32 v103, 1.0, v103
	v_add_f32_e32 v99, 1.0, v99
	v_rcp_f32_e32 v100, v100
	v_rcp_f32_e32 v96, v96
	v_rcp_f32_e32 v101, v101
	v_rcp_f32_e32 v97, v97
	v_rcp_f32_e32 v102, v102
	v_rcp_f32_e32 v98, v98
	v_rcp_f32_e32 v103, v103
	v_rcp_f32_e32 v99, v99
	v_or_b32_e32 v108, 32, v144
	v_ashrrev_i32_e32 v109, 31, v108
	v_lshlrev_b64 v[108:109], 11, v[108:109]
	v_lshl_add_u64 v[108:109], v[108:109], 0, v[146:147]
	v_lshlrev_b64 v[108:109], 1, v[108:109]
	v_lshl_add_u64 v[110:111], s[20:21], 0, v[108:109]
	s_waitcnt vmcnt(0)
	v_lshlrev_b32_e32 v112, 16, v104
	v_and_b32_e32 v104, 0xffff0000, v104
	v_lshlrev_b32_e32 v113, 16, v105
	v_and_b32_e32 v105, 0xffff0000, v105
	v_lshlrev_b32_e32 v114, 16, v106
	v_and_b32_e32 v106, 0xffff0000, v106
	v_lshlrev_b32_e32 v115, 16, v107
	v_and_b32_e32 v107, 0xffff0000, v107
	v_mul_f32_e32 v100, v100, v112
	v_mul_f32_e32 v112, v96, v114
	v_mul_f32_e32 v96, v101, v104
	v_mul_f32_e32 v101, v97, v106
	v_mul_f32_e32 v97, v102, v113
	v_mul_f32_e32 v102, v98, v115
	v_mul_f32_e32 v98, v103, v105
	v_mul_f32_e32 v99, v99, v107
	v_cvt_pk_bf16_f32 v96, v100, v96
	v_cvt_pk_bf16_f32 v97, v97, v98
	v_cvt_pk_bf16_f32 v98, v112, v101
	v_cvt_pk_bf16_f32 v99, v102, v99
	global_store_dwordx4 v[116:117], v[96:99], off offset:256
	global_load_dword v102, v[140:141], off offset:128
	s_nop 0
	global_load_dwordx4 v[96:99], v[110:111], off
	v_lshl_add_u64 v[100:101], s[24:25], 0, v[108:109]
	s_waitcnt vmcnt(0)
; __device__ __forceinline__ float bf_lo(unsigned w) { return __uint_as_float(w << 16); }
; __device__ __forceinline__ float bf_hi(unsigned w) { return __uint_as_float(w & 0xffff0000u); }
; __device__ __forceinline__ float fast_rcp(float x) { return __builtin_amdgcn_rcpf(x); }
; __device__ __forceinline__ float fast_exp2(float x) { return __builtin_amdgcn_exp2f(x); }
; __device__ __forceinline__ u32x4 pack8(f32x4 v0, f32x4 v1) { u32x4 w; w.x = cvt_pk_bf16(v0[0], v0[1]); w.y = cvt_pk_bf16(v0[2], v0[3]); w.z = cvt_pk_bf16(v1[0], v1[1]); w.w = cvt_pk_bf16(v1[2], v1[3]); return w; }
;     __device__ __forceinline__ void operator()(const f32x4 (&acc)[2][2][4][2], const Unit& u, int wr, int wc, int fr, int fq) const {
;     ...
;             for (int m = 0; m < 4; ++m) { const size_t ro = (size_t)(row0 + ai * HALF + m * 16) * DM + col0; const float nr = -LOG2E * rs[row0 + ai * HALF + m * 16];
; #pragma unroll
;                 for (int bj = 0; bj < 2; ++bj) {
;                     const u32x4 pw = *(const u32x4*)(PP + ro + bj * HALF);
;                     const float pv[8] = {bf_lo(pw.x), bf_hi(pw.x), bf_lo(pw.y), bf_hi(pw.y), bf_lo(pw.z), bf_hi(pw.z), bf_lo(pw.w), bf_hi(pw.w)};
;                     f32x4 t0, t1;
; #pragma unroll
;                     for (int j = 0; j < 4; ++j) {
;                         t0[j] = fast_rcp(1.0f + fast_exp2(acc[ai][bj][m][0][j] * nr)) * pv[j];
;                         t1[j] = fast_rcp(1.0f + fast_exp2(acc[ai][bj][m][1][j] * nr)) * pv[4 + j]; }
;                     *(u32x4*)(O + ro + bj * HALF) = pack8(t0, t1); } }
	v_mul_f32_e32 v102, 0xbfb8aa3b, v102
	v_mul_f32_e32 v92, v92, v102
	v_mul_f32_e32 v88, v88, v102
	v_mul_f32_e32 v93, v93, v102
	v_mul_f32_e32 v89, v89, v102
	v_mul_f32_e32 v94, v94, v102
	v_mul_f32_e32 v90, v90, v102
	v_mul_f32_e32 v95, v95, v102
	v_mul_f32_e32 v91, v91, v102
	v_exp_f32_e32 v92, v92
	v_exp_f32_e32 v88, v88
	v_exp_f32_e32 v93, v93
	v_exp_f32_e32 v89, v89
	v_exp_f32_e32 v94, v94
	v_exp_f32_e32 v90, v90
	v_exp_f32_e32 v95, v95
	v_exp_f32_e32 v91, v91
	v_add_f32_e32 v92, 1.0, v92
	v_add_f32_e32 v88, 1.0, v88
	v_add_f32_e32 v93, 1.0, v93
	v_add_f32_e32 v89, 1.0, v89
	v_add_f32_e32 v94, 1.0, v94
	v_add_f32_e32 v90, 1.0, v90
	v_add_f32_e32 v95, 1.0, v95
	v_add_f32_e32 v91, 1.0, v91
	v_rcp_f32_e32 v92, v92
	v_rcp_f32_e32 v88, v88
	v_rcp_f32_e32 v93, v93
	v_rcp_f32_e32 v89, v89
	v_rcp_f32_e32 v94, v94
	v_rcp_f32_e32 v90, v90
	v_rcp_f32_e32 v95, v95
	v_rcp_f32_e32 v91, v91
	v_lshlrev_b32_e32 v103, 16, v96
	v_and_b32_e32 v96, 0xffff0000, v96
	v_lshlrev_b32_e32 v104, 16, v97
	v_and_b32_e32 v97, 0xffff0000, v97
	v_lshlrev_b32_e32 v105, 16, v98
	v_and_b32_e32 v98, 0xffff0000, v98
	v_lshlrev_b32_e32 v106, 16, v99
	v_and_b32_e32 v99, 0xffff0000, v99
	v_mul_f32_e32 v92, v92, v103
	v_mul_f32_e32 v103, v88, v105
	v_mul_f32_e32 v88, v93, v96
	v_mul_f32_e32 v93, v89, v98
	v_mul_f32_e32 v89, v94, v104
	v_mul_f32_e32 v94, v90, v106
	v_mul_f32_e32 v90, v95, v97
	v_mul_f32_e32 v91, v91, v99
	v_cvt_pk_bf16_f32 v88, v92, v88
	v_cvt_pk_bf16_f32 v89, v89, v90
	v_cvt_pk_bf16_f32 v90, v103, v93
	v_cvt_pk_bf16_f32 v91, v94, v91
	global_store_dwordx4 v[100:101], v[88:91], off
	global_load_dwordx4 v[88:91], v[110:111], off offset:256
	v_mul_f32_e32 v84, v84, v102
	v_mul_f32_e32 v80, v80, v102
	v_mul_f32_e32 v85, v85, v102
	v_mul_f32_e32 v81, v81, v102
	v_mul_f32_e32 v86, v86, v102
	v_mul_f32_e32 v82, v82, v102
	v_mul_f32_e32 v87, v87, v102
	v_mul_f32_e32 v83, v83, v102
	v_exp_f32_e32 v84, v84
	v_exp_f32_e32 v80, v80
	v_exp_f32_e32 v85, v85
	v_exp_f32_e32 v81, v81
	v_exp_f32_e32 v86, v86
	v_exp_f32_e32 v82, v82
	v_exp_f32_e32 v87, v87
	v_exp_f32_e32 v83, v83
	v_add_f32_e32 v84, 1.0, v84
	v_add_f32_e32 v80, 1.0, v80
	v_add_f32_e32 v85, 1.0, v85
	v_add_f32_e32 v81, 1.0, v81
	v_add_f32_e32 v86, 1.0, v86
	v_add_f32_e32 v82, 1.0, v82
	v_add_f32_e32 v87, 1.0, v87
	v_add_f32_e32 v83, 1.0, v83
	v_rcp_f32_e32 v84, v84
	v_rcp_f32_e32 v80, v80
	v_rcp_f32_e32 v85, v85
	v_rcp_f32_e32 v81, v81
	v_rcp_f32_e32 v86, v86
	v_rcp_f32_e32 v82, v82
	v_rcp_f32_e32 v87, v87
	v_rcp_f32_e32 v83, v83
	v_or_b32_e32 v92, 48, v144
	v_ashrrev_i32_e32 v93, 31, v92
	v_lshlrev_b64 v[92:93], 11, v[92:93]
	v_lshl_add_u64 v[92:93], v[92:93], 0, v[146:147]
	v_lshlrev_b64 v[92:93], 1, v[92:93]
	v_lshl_add_u64 v[94:95], s[20:21], 0, v[92:93]
	s_waitcnt vmcnt(0)
	v_lshlrev_b32_e32 v96, 16, v88
	v_and_b32_e32 v88, 0xffff0000, v88
	v_lshlrev_b32_e32 v97, 16, v89
	v_and_b32_e32 v89, 0xffff0000, v89
	v_lshlrev_b32_e32 v98, 16, v90
	v_and_b32_e32 v90, 0xffff0000, v90
	v_lshlrev_b32_e32 v99, 16, v91
	v_and_b32_e32 v91, 0xffff0000, v91
	v_mul_f32_e32 v84, v84, v96
	v_mul_f32_e32 v96, v80, v98
	v_mul_f32_e32 v80, v85, v88
	v_mul_f32_e32 v85, v81, v90
	v_mul_f32_e32 v81, v86, v97
	v_mul_f32_e32 v86, v82, v99
	v_mul_f32_e32 v82, v87, v89
	v_mul_f32_e32 v83, v83, v91
	v_cvt_pk_bf16_f32 v80, v84, v80
	v_cvt_pk_bf16_f32 v81, v81, v82
	v_cvt_pk_bf16_f32 v82, v96, v85
	v_cvt_pk_bf16_f32 v83, v86, v83
	global_store_dwordx4 v[100:101], v[80:83], off offset:256
	global_load_dword v86, v[140:141], off offset:192
	s_nop 0
	global_load_dwordx4 v[80:83], v[94:95], off
	v_lshl_add_u64 v[84:85], s[24:25], 0, v[92:93]
	s_waitcnt vmcnt(0)
	v_mul_f32_e32 v86, 0xbfb8aa3b, v86
	v_mul_f32_e32 v76, v76, v86
	v_mul_f32_e32 v72, v72, v86
	v_mul_f32_e32 v77, v77, v86
	v_mul_f32_e32 v73, v73, v86
	v_mul_f32_e32 v78, v78, v86
	v_mul_f32_e32 v74, v74, v86
	v_mul_f32_e32 v79, v79, v86
	v_mul_f32_e32 v75, v75, v86
	v_exp_f32_e32 v76, v76
	v_exp_f32_e32 v72, v72
	v_exp_f32_e32 v77, v77
	v_exp_f32_e32 v73, v73
	v_exp_f32_e32 v78, v78
	v_exp_f32_e32 v74, v74
	v_exp_f32_e32 v79, v79
	v_exp_f32_e32 v75, v75
	v_add_f32_e32 v76, 1.0, v76
	v_add_f32_e32 v72, 1.0, v72
	v_add_f32_e32 v77, 1.0, v77
	v_add_f32_e32 v73, 1.0, v73
	v_add_f32_e32 v78, 1.0, v78
	v_add_f32_e32 v74, 1.0, v74
	v_add_f32_e32 v79, 1.0, v79
	v_add_f32_e32 v75, 1.0, v75
	v_rcp_f32_e32 v76, v76
	v_rcp_f32_e32 v72, v72
	v_rcp_f32_e32 v77, v77
	v_rcp_f32_e32 v73, v73
	v_rcp_f32_e32 v78, v78
	v_rcp_f32_e32 v74, v74
	v_rcp_f32_e32 v79, v79
	v_rcp_f32_e32 v75, v75
	v_lshlrev_b32_e32 v87, 16, v80
	v_and_b32_e32 v80, 0xffff0000, v80
	v_lshlrev_b32_e32 v88, 16, v81
	v_and_b32_e32 v81, 0xffff0000, v81
	v_lshlrev_b32_e32 v89, 16, v82
	v_and_b32_e32 v82, 0xffff0000, v82
	v_lshlrev_b32_e32 v90, 16, v83
	v_and_b32_e32 v83, 0xffff0000, v83
	v_mul_f32_e32 v76, v76, v87
	v_mul_f32_e32 v87, v72, v89
	v_mul_f32_e32 v72, v77, v80
	v_mul_f32_e32 v77, v73, v82
	v_mul_f32_e32 v73, v78, v88
	v_mul_f32_e32 v78, v74, v90
	v_mul_f32_e32 v74, v79, v81
	v_mul_f32_e32 v75, v75, v83
	v_cvt_pk_bf16_f32 v72, v76, v72
	v_cvt_pk_bf16_f32 v73, v73, v74
	v_cvt_pk_bf16_f32 v74, v87, v77
	v_cvt_pk_bf16_f32 v75, v78, v75
	global_store_dwordx4 v[84:85], v[72:75], off
	global_load_dwordx4 v[72:75], v[94:95], off offset:256
	v_mul_f32_e32 v68, v68, v86
	v_mul_f32_e32 v64, v64, v86
	v_mul_f32_e32 v69, v69, v86
	v_mul_f32_e32 v65, v65, v86
	v_mul_f32_e32 v70, v70, v86
	v_mul_f32_e32 v66, v66, v86
	v_mul_f32_e32 v71, v71, v86
	v_mul_f32_e32 v67, v67, v86
	v_exp_f32_e32 v68, v68
	v_exp_f32_e32 v64, v64
	v_exp_f32_e32 v69, v69
	v_exp_f32_e32 v65, v65
	v_exp_f32_e32 v70, v70
	v_exp_f32_e32 v66, v66
	v_exp_f32_e32 v71, v71
	v_exp_f32_e32 v67, v67
	v_add_f32_e32 v68, 1.0, v68
	v_add_f32_e32 v64, 1.0, v64
	v_add_f32_e32 v69, 1.0, v69
	v_add_f32_e32 v65, 1.0, v65
	v_add_f32_e32 v70, 1.0, v70
	v_add_f32_e32 v66, 1.0, v66
	v_add_f32_e32 v71, 1.0, v71
	v_add_f32_e32 v67, 1.0, v67
	v_rcp_f32_e32 v68, v68
	v_rcp_f32_e32 v64, v64
	v_rcp_f32_e32 v69, v69
	v_rcp_f32_e32 v65, v65
	v_rcp_f32_e32 v70, v70
	v_rcp_f32_e32 v66, v66
	v_rcp_f32_e32 v71, v71
	v_rcp_f32_e32 v67, v67
	v_lshl_add_u64 v[76:77], v[142:143], 0, s[2:3]
	v_lshl_add_u64 v[78:79], s[20:21], 0, v[76:77]
	s_waitcnt vmcnt(0)
; __device__ __forceinline__ float bf_lo(unsigned w) { return __uint_as_float(w << 16); }
; __device__ __forceinline__ float bf_hi(unsigned w) { return __uint_as_float(w & 0xffff0000u); }
; __device__ __forceinline__ float fast_rcp(float x) { return __builtin_amdgcn_rcpf(x); }
; __device__ __forceinline__ float fast_exp2(float x) { return __builtin_amdgcn_exp2f(x); }
; __device__ __forceinline__ u32x4 pack8(f32x4 v0, f32x4 v1) { u32x4 w; w.x = cvt_pk_bf16(v0[0], v0[1]); w.y = cvt_pk_bf16(v0[2], v0[3]); w.z = cvt_pk_bf16(v1[0], v1[1]); w.w = cvt_pk_bf16(v1[2], v1[3]); return w; }
;     __device__ __forceinline__ void operator()(const f32x4 (&acc)[2][2][4][2], const Unit& u, int wr, int wc, int fr, int fq) const {
;     ...
;             for (int m = 0; m < 4; ++m) { const size_t ro = (size_t)(row0 + ai * HALF + m * 16) * DM + col0; const float nr = -LOG2E * rs[row0 + ai * HALF + m * 16];
; #pragma unroll
;                 for (int bj = 0; bj < 2; ++bj) {
;                     const u32x4 pw = *(const u32x4*)(PP + ro + bj * HALF);
;                     const float pv[8] = {bf_lo(pw.x), bf_hi(pw.x), bf_lo(pw.y), bf_hi(pw.y), bf_lo(pw.z), bf_hi(pw.z), bf_lo(pw.w), bf_hi(pw.w)};
;                     f32x4 t0, t1;
; #pragma unroll
;                     for (int j = 0; j < 4; ++j) {
;                         t0[j] = fast_rcp(1.0f + fast_exp2(acc[ai][bj][m][0][j] * nr)) * pv[j];
;                         t1[j] = fast_rcp(1.0f + fast_exp2(acc[ai][bj][m][1][j] * nr)) * pv[4 + j]; }
;                     *(u32x4*)(O + ro + bj * HALF) = pack8(t0, t1); } }
	v_lshlrev_b32_e32 v80, 16, v72
	v_and_b32_e32 v72, 0xffff0000, v72
	v_lshlrev_b32_e32 v81, 16, v73
	v_and_b32_e32 v73, 0xffff0000, v73
	v_lshlrev_b32_e32 v82, 16, v74
	v_and_b32_e32 v74, 0xffff0000, v74
	v_lshlrev_b32_e32 v83, 16, v75
	v_and_b32_e32 v75, 0xffff0000, v75
	v_mul_f32_e32 v68, v68, v80
	v_mul_f32_e32 v80, v64, v82
	v_mul_f32_e32 v64, v69, v72
	v_mul_f32_e32 v69, v65, v74
	v_mul_f32_e32 v65, v70, v81
	v_mul_f32_e32 v70, v66, v83
	v_mul_f32_e32 v66, v71, v73
	v_mul_f32_e32 v67, v67, v75
	v_cvt_pk_bf16_f32 v64, v68, v64
	v_cvt_pk_bf16_f32 v65, v65, v66
	v_cvt_pk_bf16_f32 v66, v80, v69
	v_cvt_pk_bf16_f32 v67, v70, v67
	global_store_dwordx4 v[84:85], v[64:67], off offset:256
	global_load_dword v70, v[140:141], off offset:512
	s_nop 0
	global_load_dwordx4 v[64:67], v[78:79], off
	v_lshl_add_u64 v[68:69], s[24:25], 0, v[76:77]
	s_waitcnt vmcnt(0)
	v_mul_f32_e32 v70, 0xbfb8aa3b, v70
	v_mul_f32_e32 v60, v60, v70
	v_mul_f32_e32 v56, v56, v70
	v_mul_f32_e32 v61, v61, v70
	v_mul_f32_e32 v57, v57, v70
	v_mul_f32_e32 v62, v62, v70
	v_mul_f32_e32 v58, v58, v70
	v_mul_f32_e32 v63, v63, v70
	v_mul_f32_e32 v59, v59, v70
	v_exp_f32_e32 v60, v60
	v_exp_f32_e32 v56, v56
	v_exp_f32_e32 v61, v61
	v_exp_f32_e32 v57, v57
	v_exp_f32_e32 v62, v62
	v_exp_f32_e32 v58, v58
	v_exp_f32_e32 v63, v63
	v_exp_f32_e32 v59, v59
	v_add_f32_e32 v60, 1.0, v60
	v_add_f32_e32 v56, 1.0, v56
	v_add_f32_e32 v61, 1.0, v61
	v_add_f32_e32 v57, 1.0, v57
	v_add_f32_e32 v62, 1.0, v62
	v_add_f32_e32 v58, 1.0, v58
	v_add_f32_e32 v63, 1.0, v63
	v_add_f32_e32 v59, 1.0, v59
	v_rcp_f32_e32 v60, v60
	v_rcp_f32_e32 v56, v56
	v_rcp_f32_e32 v61, v61
	v_rcp_f32_e32 v57, v57
	v_rcp_f32_e32 v62, v62
	v_rcp_f32_e32 v58, v58
	v_rcp_f32_e32 v63, v63
	v_rcp_f32_e32 v59, v59
	v_lshlrev_b32_e32 v71, 16, v64
	v_and_b32_e32 v64, 0xffff0000, v64
	v_lshlrev_b32_e32 v72, 16, v65
	v_and_b32_e32 v65, 0xffff0000, v65
	v_lshlrev_b32_e32 v73, 16, v66
	v_and_b32_e32 v66, 0xffff0000, v66
	v_lshlrev_b32_e32 v74, 16, v67
	v_and_b32_e32 v67, 0xffff0000, v67
	v_mul_f32_e32 v60, v60, v71
	v_mul_f32_e32 v71, v56, v73
	v_mul_f32_e32 v56, v61, v64
	v_mul_f32_e32 v61, v57, v66
	v_mul_f32_e32 v57, v62, v72
	v_mul_f32_e32 v62, v58, v74
	v_mul_f32_e32 v58, v63, v65
	v_mul_f32_e32 v59, v59, v67
	v_cvt_pk_bf16_f32 v56, v60, v56
	v_cvt_pk_bf16_f32 v57, v57, v58
	v_cvt_pk_bf16_f32 v58, v71, v61
	v_cvt_pk_bf16_f32 v59, v62, v59
	global_store_dwordx4 v[68:69], v[56:59], off
	global_load_dwordx4 v[56:59], v[78:79], off offset:256
	v_mul_f32_e32 v52, v52, v70
	v_mul_f32_e32 v48, v48, v70
	v_mul_f32_e32 v53, v53, v70
	v_mul_f32_e32 v49, v49, v70
	v_mul_f32_e32 v54, v54, v70
	v_mul_f32_e32 v50, v50, v70
	v_mul_f32_e32 v55, v55, v70
	v_mul_f32_e32 v51, v51, v70
	v_exp_f32_e32 v52, v52
	v_exp_f32_e32 v48, v48
	v_exp_f32_e32 v53, v53
	v_exp_f32_e32 v49, v49
	v_exp_f32_e32 v54, v54
	v_exp_f32_e32 v50, v50
	v_exp_f32_e32 v55, v55
	v_exp_f32_e32 v51, v51
	v_add_f32_e32 v52, 1.0, v52
	v_add_f32_e32 v48, 1.0, v48
	v_add_f32_e32 v53, 1.0, v53
	v_add_f32_e32 v49, 1.0, v49
	v_add_f32_e32 v54, 1.0, v54
	v_add_f32_e32 v50, 1.0, v50
	v_add_f32_e32 v55, 1.0, v55
	v_add_f32_e32 v51, 1.0, v51
	v_rcp_f32_e32 v52, v52
	v_rcp_f32_e32 v48, v48
	v_rcp_f32_e32 v53, v53
	v_rcp_f32_e32 v49, v49
	v_rcp_f32_e32 v54, v54
	v_rcp_f32_e32 v50, v50
	v_rcp_f32_e32 v55, v55
	v_rcp_f32_e32 v51, v51
	v_lshl_add_u64 v[60:61], v[142:143], 0, s[6:7]
	v_lshl_add_u64 v[62:63], s[20:21], 0, v[60:61]
	s_waitcnt vmcnt(0)
	v_lshlrev_b32_e32 v64, 16, v56
	v_and_b32_e32 v56, 0xffff0000, v56
	v_lshlrev_b32_e32 v65, 16, v57
	v_and_b32_e32 v57, 0xffff0000, v57
	v_lshlrev_b32_e32 v66, 16, v58
	v_and_b32_e32 v58, 0xffff0000, v58
	v_lshlrev_b32_e32 v67, 16, v59
	v_and_b32_e32 v59, 0xffff0000, v59
	v_mul_f32_e32 v52, v52, v64
	v_mul_f32_e32 v64, v48, v66
	v_mul_f32_e32 v48, v53, v56
	v_mul_f32_e32 v53, v49, v58
	v_mul_f32_e32 v49, v54, v65
	v_mul_f32_e32 v54, v50, v67
	v_mul_f32_e32 v50, v55, v57
	v_mul_f32_e32 v51, v51, v59
	v_cvt_pk_bf16_f32 v48, v52, v48
	v_cvt_pk_bf16_f32 v49, v49, v50
	v_cvt_pk_bf16_f32 v50, v64, v53
	v_cvt_pk_bf16_f32 v51, v54, v51
	global_store_dwordx4 v[68:69], v[48:51], off offset:256
	global_load_dword v54, v[140:141], off offset:576
	s_nop 0
	global_load_dwordx4 v[48:51], v[62:63], off
	v_lshl_add_u64 v[52:53], s[24:25], 0, v[60:61]
	s_waitcnt vmcnt(0)
	v_mul_f32_e32 v54, 0xbfb8aa3b, v54
	v_mul_f32_e32 v44, v44, v54
	v_mul_f32_e32 v40, v40, v54
	v_mul_f32_e32 v45, v45, v54
	v_mul_f32_e32 v41, v41, v54
	v_mul_f32_e32 v46, v46, v54
	v_mul_f32_e32 v42, v42, v54
	v_mul_f32_e32 v47, v47, v54
	v_mul_f32_e32 v43, v43, v54
	v_exp_f32_e32 v44, v44
	v_exp_f32_e32 v40, v40
	v_exp_f32_e32 v45, v45
	v_exp_f32_e32 v41, v41
	v_exp_f32_e32 v46, v46
	v_exp_f32_e32 v42, v42
	v_exp_f32_e32 v47, v47
	v_exp_f32_e32 v43, v43
	v_add_f32_e32 v44, 1.0, v44
	v_add_f32_e32 v40, 1.0, v40
	v_add_f32_e32 v45, 1.0, v45
	v_add_f32_e32 v41, 1.0, v41
	v_add_f32_e32 v46, 1.0, v46
	v_add_f32_e32 v42, 1.0, v42
	v_add_f32_e32 v47, 1.0, v47
	v_add_f32_e32 v43, 1.0, v43
	v_rcp_f32_e32 v44, v44
	v_rcp_f32_e32 v40, v40
	v_rcp_f32_e32 v45, v45
	v_rcp_f32_e32 v41, v41
	v_rcp_f32_e32 v46, v46
	v_rcp_f32_e32 v42, v42
	v_rcp_f32_e32 v47, v47
	v_rcp_f32_e32 v43, v43
	v_lshlrev_b32_e32 v55, 16, v48
	v_and_b32_e32 v48, 0xffff0000, v48
	v_lshlrev_b32_e32 v56, 16, v49
	v_and_b32_e32 v49, 0xffff0000, v49
	v_lshlrev_b32_e32 v57, 16, v50
	v_and_b32_e32 v50, 0xffff0000, v50
	v_lshlrev_b32_e32 v58, 16, v51
	v_and_b32_e32 v51, 0xffff0000, v51
	v_mul_f32_e32 v44, v44, v55
	v_mul_f32_e32 v55, v40, v57
	v_mul_f32_e32 v40, v45, v48
	v_mul_f32_e32 v45, v41, v50
	v_mul_f32_e32 v41, v46, v56
	v_mul_f32_e32 v46, v42, v58
	v_mul_f32_e32 v42, v47, v49
	v_mul_f32_e32 v43, v43, v51
	v_cvt_pk_bf16_f32 v40, v44, v40
	v_cvt_pk_bf16_f32 v41, v41, v42
	v_cvt_pk_bf16_f32 v42, v55, v45
	v_cvt_pk_bf16_f32 v43, v46, v43
	global_store_dwordx4 v[52:53], v[40:43], off
	global_load_dwordx4 v[40:43], v[62:63], off offset:256
	v_mul_f32_e32 v36, v36, v54
	v_mul_f32_e32 v32, v32, v54
	v_mul_f32_e32 v37, v37, v54
	v_mul_f32_e32 v33, v33, v54
	v_mul_f32_e32 v38, v38, v54
	v_mul_f32_e32 v34, v34, v54
	v_mul_f32_e32 v39, v39, v54
	v_mul_f32_e32 v35, v35, v54
	v_exp_f32_e32 v36, v36
	v_exp_f32_e32 v32, v32
	v_exp_f32_e32 v37, v37
	v_exp_f32_e32 v33, v33
	v_exp_f32_e32 v38, v38
	v_exp_f32_e32 v34, v34
	v_exp_f32_e32 v39, v39
	v_exp_f32_e32 v35, v35
	v_add_f32_e32 v36, 1.0, v36
	v_add_f32_e32 v32, 1.0, v32
	v_add_f32_e32 v37, 1.0, v37
	v_add_f32_e32 v33, 1.0, v33
	v_add_f32_e32 v38, 1.0, v38
	v_add_f32_e32 v34, 1.0, v34
	v_add_f32_e32 v39, 1.0, v39
	v_add_f32_e32 v35, 1.0, v35
	v_rcp_f32_e32 v36, v36
	v_rcp_f32_e32 v32, v32
	v_rcp_f32_e32 v37, v37
	v_rcp_f32_e32 v33, v33
	v_rcp_f32_e32 v38, v38
	v_rcp_f32_e32 v34, v34
	v_rcp_f32_e32 v39, v39
	v_rcp_f32_e32 v35, v35
	v_lshl_add_u64 v[44:45], v[142:143], 0, s[8:9]
	v_lshl_add_u64 v[46:47], s[20:21], 0, v[44:45]
	s_waitcnt vmcnt(0)
; __device__ __forceinline__ float bf_lo(unsigned w) { return __uint_as_float(w << 16); }
; __device__ __forceinline__ float bf_hi(unsigned w) { return __uint_as_float(w & 0xffff0000u); }
; __device__ __forceinline__ float fast_rcp(float x) { return __builtin_amdgcn_rcpf(x); }
; __device__ __forceinline__ float fast_exp2(float x) { return __builtin_amdgcn_exp2f(x); }
; __device__ __forceinline__ u32x4 pack8(f32x4 v0, f32x4 v1) { u32x4 w; w.x = cvt_pk_bf16(v0[0], v0[1]); w.y = cvt_pk_bf16(v0[2], v0[3]); w.z = cvt_pk_bf16(v1[0], v1[1]); w.w = cvt_pk_bf16(v1[2], v1[3]); return w; }
;     __device__ __forceinline__ void operator()(const f32x4 (&acc)[2][2][4][2], const Unit& u, int wr, int wc, int fr, int fq) const {
;     ...
;             for (int m = 0; m < 4; ++m) { const size_t ro = (size_t)(row0 + ai * HALF + m * 16) * DM + col0; const float nr = -LOG2E * rs[row0 + ai * HALF + m * 16];
; #pragma unroll
;                 for (int bj = 0; bj < 2; ++bj) {
;                     const u32x4 pw = *(const u32x4*)(PP + ro + bj * HALF);
;                     const float pv[8] = {bf_lo(pw.x), bf_hi(pw.x), bf_lo(pw.y), bf_hi(pw.y), bf_lo(pw.z), bf_hi(pw.z), bf_lo(pw.w), bf_hi(pw.w)};
;                     f32x4 t0, t1;
; #pragma unroll
;                     for (int j = 0; j < 4; ++j) {
;                         t0[j] = fast_rcp(1.0f + fast_exp2(acc[ai][bj][m][0][j] * nr)) * pv[j];
;                         t1[j] = fast_rcp(1.0f + fast_exp2(acc[ai][bj][m][1][j] * nr)) * pv[4 + j]; }
;                     *(u32x4*)(O + ro + bj * HALF) = pack8(t0, t1); } }
	v_lshlrev_b32_e32 v48, 16, v40
	v_and_b32_e32 v40, 0xffff0000, v40
	v_lshlrev_b32_e32 v49, 16, v41
	v_and_b32_e32 v41, 0xffff0000, v41
	v_lshlrev_b32_e32 v50, 16, v42
	v_and_b32_e32 v42, 0xffff0000, v42
	v_lshlrev_b32_e32 v51, 16, v43
	v_and_b32_e32 v43, 0xffff0000, v43
	v_mul_f32_e32 v36, v36, v48
	v_mul_f32_e32 v48, v32, v50
	v_mul_f32_e32 v32, v37, v40
	v_mul_f32_e32 v37, v33, v42
	v_mul_f32_e32 v33, v38, v49
	v_mul_f32_e32 v38, v34, v51
	v_mul_f32_e32 v34, v39, v41
	v_mul_f32_e32 v35, v35, v43
	v_cvt_pk_bf16_f32 v32, v36, v32
	v_cvt_pk_bf16_f32 v33, v33, v34
	v_cvt_pk_bf16_f32 v34, v48, v37
	v_cvt_pk_bf16_f32 v35, v38, v35
	global_store_dwordx4 v[52:53], v[32:35], off offset:256
	global_load_dword v38, v[140:141], off offset:640
	s_nop 0
	global_load_dwordx4 v[32:35], v[46:47], off
	v_lshl_add_u64 v[36:37], s[24:25], 0, v[44:45]
	s_waitcnt vmcnt(0)
	v_mul_f32_e32 v38, 0xbfb8aa3b, v38
	v_mul_f32_e32 v28, v28, v38
	v_mul_f32_e32 v24, v24, v38
	v_mul_f32_e32 v29, v29, v38
	v_mul_f32_e32 v25, v25, v38
	v_mul_f32_e32 v30, v30, v38
	v_mul_f32_e32 v26, v26, v38
	v_mul_f32_e32 v31, v31, v38
	v_mul_f32_e32 v27, v27, v38
	v_exp_f32_e32 v28, v28
	v_exp_f32_e32 v24, v24
	v_exp_f32_e32 v29, v29
	v_exp_f32_e32 v25, v25
	v_exp_f32_e32 v30, v30
	v_exp_f32_e32 v26, v26
	v_exp_f32_e32 v31, v31
	v_exp_f32_e32 v27, v27
	v_add_f32_e32 v28, 1.0, v28
	v_add_f32_e32 v24, 1.0, v24
	v_add_f32_e32 v29, 1.0, v29
	v_add_f32_e32 v25, 1.0, v25
	v_add_f32_e32 v30, 1.0, v30
	v_add_f32_e32 v26, 1.0, v26
	v_add_f32_e32 v31, 1.0, v31
	v_add_f32_e32 v27, 1.0, v27
	v_rcp_f32_e32 v28, v28
	v_rcp_f32_e32 v24, v24
	v_rcp_f32_e32 v29, v29
	v_rcp_f32_e32 v25, v25
	v_rcp_f32_e32 v30, v30
	v_rcp_f32_e32 v26, v26
	v_rcp_f32_e32 v31, v31
	v_rcp_f32_e32 v27, v27
	v_lshlrev_b32_e32 v39, 16, v32
	v_and_b32_e32 v32, 0xffff0000, v32
	v_lshlrev_b32_e32 v40, 16, v33
	v_and_b32_e32 v33, 0xffff0000, v33
	v_lshlrev_b32_e32 v41, 16, v34
	v_and_b32_e32 v34, 0xffff0000, v34
	v_lshlrev_b32_e32 v42, 16, v35
	v_and_b32_e32 v35, 0xffff0000, v35
	v_mul_f32_e32 v28, v28, v39
	v_mul_f32_e32 v39, v24, v41
	v_mul_f32_e32 v24, v29, v32
	v_mul_f32_e32 v29, v25, v34
	v_mul_f32_e32 v25, v30, v40
	v_mul_f32_e32 v30, v26, v42
	v_mul_f32_e32 v26, v31, v33
	v_mul_f32_e32 v27, v27, v35
	v_cvt_pk_bf16_f32 v24, v28, v24
	v_cvt_pk_bf16_f32 v25, v25, v26
	v_cvt_pk_bf16_f32 v26, v39, v29
	v_cvt_pk_bf16_f32 v27, v30, v27
	global_store_dwordx4 v[36:37], v[24:27], off
	global_load_dwordx4 v[24:27], v[46:47], off offset:256
	v_mul_f32_e32 v20, v20, v38
	v_mul_f32_e32 v16, v16, v38
	v_mul_f32_e32 v21, v21, v38
	v_mul_f32_e32 v17, v17, v38
	v_mul_f32_e32 v22, v22, v38
	v_mul_f32_e32 v18, v18, v38
	v_mul_f32_e32 v23, v23, v38
	v_mul_f32_e32 v19, v19, v38
	v_exp_f32_e32 v20, v20
	v_exp_f32_e32 v16, v16
	v_exp_f32_e32 v21, v21
	v_exp_f32_e32 v17, v17
	v_exp_f32_e32 v22, v22
	v_exp_f32_e32 v18, v18
	v_exp_f32_e32 v23, v23
	v_exp_f32_e32 v19, v19
	v_add_f32_e32 v20, 1.0, v20
	v_add_f32_e32 v16, 1.0, v16
	v_add_f32_e32 v21, 1.0, v21
	v_add_f32_e32 v17, 1.0, v17
	v_add_f32_e32 v22, 1.0, v22
	v_add_f32_e32 v18, 1.0, v18
	v_add_f32_e32 v23, 1.0, v23
	v_add_f32_e32 v19, 1.0, v19
	v_rcp_f32_e32 v20, v20
	v_rcp_f32_e32 v16, v16
	v_rcp_f32_e32 v21, v21
	v_rcp_f32_e32 v17, v17
	v_rcp_f32_e32 v22, v22
	v_rcp_f32_e32 v18, v18
	v_rcp_f32_e32 v23, v23
	v_rcp_f32_e32 v19, v19
	v_lshl_add_u64 v[28:29], v[142:143], 0, s[30:31]
	v_lshl_add_u64 v[30:31], s[20:21], 0, v[28:29]
	s_waitcnt vmcnt(0)
; __device__ __forceinline__ float bf_lo(unsigned w) { return __uint_as_float(w << 16); }
; __device__ __forceinline__ float bf_hi(unsigned w) { return __uint_as_float(w & 0xffff0000u); }
; __device__ __forceinline__ float fast_rcp(float x) { return __builtin_amdgcn_rcpf(x); }
; __device__ __forceinline__ float fast_exp2(float x) { return __builtin_amdgcn_exp2f(x); }
; __device__ __forceinline__ u32x4 pack8(f32x4 v0, f32x4 v1) { u32x4 w; w.x = cvt_pk_bf16(v0[0], v0[1]); w.y = cvt_pk_bf16(v0[2], v0[3]); w.z = cvt_pk_bf16(v1[0], v1[1]); w.w = cvt_pk_bf16(v1[2], v1[3]); return w; }
;     __device__ __forceinline__ void operator()(const f32x4 (&acc)[2][2][4][2], const Unit& u, int wr, int wc, int fr, int fq) const {
;     ...
;             for (int m = 0; m < 4; ++m) { const size_t ro = (size_t)(row0 + ai * HALF + m * 16) * DM + col0; const float nr = -LOG2E * rs[row0 + ai * HALF + m * 16];
; #pragma unroll
;                 for (int bj = 0; bj < 2; ++bj) {
;                     const u32x4 pw = *(const u32x4*)(PP + ro + bj * HALF);
;                     const float pv[8] = {bf_lo(pw.x), bf_hi(pw.x), bf_lo(pw.y), bf_hi(pw.y), bf_lo(pw.z), bf_hi(pw.z), bf_lo(pw.w), bf_hi(pw.w)};
;                     f32x4 t0, t1;
; #pragma unroll
;                     for (int j = 0; j < 4; ++j) {
;                         t0[j] = fast_rcp(1.0f + fast_exp2(acc[ai][bj][m][0][j] * nr)) * pv[j];
;                         t1[j] = fast_rcp(1.0f + fast_exp2(acc[ai][bj][m][1][j] * nr)) * pv[4 + j]; }
;                     *(u32x4*)(O + ro + bj * HALF) = pack8(t0, t1); } }
	v_lshlrev_b32_e32 v32, 16, v24
	v_and_b32_e32 v24, 0xffff0000, v24
	v_lshlrev_b32_e32 v33, 16, v25
	v_and_b32_e32 v25, 0xffff0000, v25
	v_lshlrev_b32_e32 v34, 16, v26
	v_and_b32_e32 v26, 0xffff0000, v26
	v_lshlrev_b32_e32 v35, 16, v27
	v_and_b32_e32 v27, 0xffff0000, v27
	v_mul_f32_e32 v20, v20, v32
	v_mul_f32_e32 v32, v16, v34
	v_mul_f32_e32 v16, v21, v24
	v_mul_f32_e32 v21, v17, v26
	v_mul_f32_e32 v17, v22, v33
	v_mul_f32_e32 v22, v18, v35
	v_mul_f32_e32 v18, v23, v25
	v_mul_f32_e32 v19, v19, v27
	v_cvt_pk_bf16_f32 v16, v20, v16
	v_cvt_pk_bf16_f32 v17, v17, v18
	v_cvt_pk_bf16_f32 v18, v32, v21
	v_cvt_pk_bf16_f32 v19, v22, v19
	global_store_dwordx4 v[36:37], v[16:19], off offset:256
	global_load_dword v22, v[140:141], off offset:704
	s_nop 0
	global_load_dwordx4 v[16:19], v[30:31], off
	v_lshl_add_u64 v[20:21], s[24:25], 0, v[28:29]
	s_waitcnt vmcnt(0)
	v_mul_f32_e32 v22, 0xbfb8aa3b, v22
	v_mul_f32_e32 v12, v12, v22
	v_mul_f32_e32 v8, v8, v22
	v_mul_f32_e32 v13, v13, v22
	v_mul_f32_e32 v9, v9, v22
	v_mul_f32_e32 v14, v14, v22
	v_mul_f32_e32 v10, v10, v22
	v_mul_f32_e32 v15, v15, v22
	v_mul_f32_e32 v11, v11, v22
	v_exp_f32_e32 v12, v12
	v_exp_f32_e32 v8, v8
	v_exp_f32_e32 v13, v13
	v_exp_f32_e32 v9, v9
	v_exp_f32_e32 v14, v14
	v_exp_f32_e32 v10, v10
	v_exp_f32_e32 v15, v15
	v_exp_f32_e32 v11, v11
	v_add_f32_e32 v12, 1.0, v12
	v_add_f32_e32 v8, 1.0, v8
	v_add_f32_e32 v13, 1.0, v13
	v_add_f32_e32 v9, 1.0, v9
	v_add_f32_e32 v14, 1.0, v14
	v_add_f32_e32 v10, 1.0, v10
	v_add_f32_e32 v15, 1.0, v15
	v_add_f32_e32 v11, 1.0, v11
	v_rcp_f32_e32 v12, v12
	v_rcp_f32_e32 v8, v8
	v_rcp_f32_e32 v13, v13
	v_rcp_f32_e32 v9, v9
	v_rcp_f32_e32 v14, v14
	v_rcp_f32_e32 v10, v10
	v_rcp_f32_e32 v15, v15
	v_rcp_f32_e32 v11, v11
	v_lshlrev_b32_e32 v23, 16, v16
	v_and_b32_e32 v16, 0xffff0000, v16
	v_lshlrev_b32_e32 v24, 16, v17
	v_and_b32_e32 v17, 0xffff0000, v17
	v_lshlrev_b32_e32 v25, 16, v18
	v_and_b32_e32 v18, 0xffff0000, v18
	v_lshlrev_b32_e32 v26, 16, v19
	v_and_b32_e32 v19, 0xffff0000, v19
	v_mul_f32_e32 v12, v12, v23
	v_mul_f32_e32 v23, v8, v25
	v_mul_f32_e32 v8, v13, v16
	v_mul_f32_e32 v13, v9, v18
	v_mul_f32_e32 v9, v14, v24
	v_mul_f32_e32 v14, v10, v26
	v_mul_f32_e32 v10, v15, v17
	v_mul_f32_e32 v11, v11, v19
	v_cvt_pk_bf16_f32 v8, v12, v8
	v_cvt_pk_bf16_f32 v9, v9, v10
	v_cvt_pk_bf16_f32 v10, v23, v13
	v_cvt_pk_bf16_f32 v11, v14, v11
	global_store_dwordx4 v[20:21], v[8:11], off
	global_load_dwordx4 v[8:11], v[30:31], off offset:256
	v_mul_f32_e32 v4, v4, v22
	v_mul_f32_e32 v0, v0, v22
	v_mul_f32_e32 v5, v5, v22
	v_mul_f32_e32 v1, v1, v22
	v_mul_f32_e32 v6, v6, v22
	v_mul_f32_e32 v2, v2, v22
	v_mul_f32_e32 v7, v7, v22
	v_mul_f32_e32 v3, v3, v22
	v_exp_f32_e32 v4, v4
	v_exp_f32_e32 v0, v0
	v_exp_f32_e32 v5, v5
	v_exp_f32_e32 v1, v1
	v_exp_f32_e32 v6, v6
	v_exp_f32_e32 v2, v2
	v_exp_f32_e32 v7, v7
	v_exp_f32_e32 v3, v3
	v_add_f32_e32 v4, 1.0, v4
	v_add_f32_e32 v0, 1.0, v0
	v_add_f32_e32 v5, 1.0, v5
	v_add_f32_e32 v1, 1.0, v1
	v_add_f32_e32 v6, 1.0, v6
	v_add_f32_e32 v2, 1.0, v2
	v_add_f32_e32 v7, 1.0, v7
	v_add_f32_e32 v3, 1.0, v3
	v_rcp_f32_e32 v4, v4
	v_rcp_f32_e32 v0, v0
	v_rcp_f32_e32 v5, v5
	v_rcp_f32_e32 v1, v1
	v_rcp_f32_e32 v6, v6
	v_rcp_f32_e32 v2, v2
	v_rcp_f32_e32 v7, v7
	v_rcp_f32_e32 v3, v3
	s_waitcnt vmcnt(0)
	v_lshlrev_b32_e32 v12, 16, v8
	v_and_b32_e32 v8, 0xffff0000, v8
	v_lshlrev_b32_e32 v13, 16, v9
	v_and_b32_e32 v9, 0xffff0000, v9
	v_lshlrev_b32_e32 v14, 16, v10
	v_and_b32_e32 v10, 0xffff0000, v10
	v_lshlrev_b32_e32 v15, 16, v11
	v_and_b32_e32 v11, 0xffff0000, v11
	v_mul_f32_e32 v4, v4, v12
	v_mul_f32_e32 v12, v0, v14
	v_mul_f32_e32 v0, v5, v8
	v_mul_f32_e32 v5, v1, v10
	v_mul_f32_e32 v1, v6, v13
	v_mul_f32_e32 v6, v2, v15
	v_mul_f32_e32 v2, v7, v9
	v_mul_f32_e32 v3, v3, v11
	v_cvt_pk_bf16_f32 v0, v4, v0
	v_cvt_pk_bf16_f32 v1, v1, v2
	v_cvt_pk_bf16_f32 v2, v12, v5
	v_cvt_pk_bf16_f32 v3, v6, v3
	global_store_dwordx4 v[20:21], v[0:3], off offset:256
	s_cbranch_vccz .LBB0_996
	s_waitcnt vmcnt(0)
	s_cmpk_gt_u32 s10, 0xff
	s_cbranch_scc1 .LBB0_1003
	s_barrier

; __global__ __launch_bounds__(512, 2) void fwd_megakernel(Params P) {
	.amdhsa_kernel _Z14fwd_megakernel6Params
		.amdhsa_group_segment_fixed_size 0
		.amdhsa_private_segment_fixed_size 0
		.amdhsa_kernarg_size 448
		.amdhsa_user_sgpr_count 2
		.amdhsa_user_sgpr_dispatch_ptr 0
		.amdhsa_user_sgpr_queue_ptr 0
		.amdhsa_user_sgpr_kernarg_segment_ptr 1
		.amdhsa_user_sgpr_dispatch_id 0
		.amdhsa_user_sgpr_kernarg_preload_length 0
		.amdhsa_user_sgpr_kernarg_preload_offset 0
		.amdhsa_user_sgpr_private_segment_size 0
		.amdhsa_uses_dynamic_stack 0
		.amdhsa_enable_private_segment 0
		.amdhsa_system_sgpr_workgroup_id_x 1
		.amdhsa_system_sgpr_workgroup_id_y 0
		.amdhsa_system_sgpr_workgroup_id_z 0
		.amdhsa_system_sgpr_workgroup_info 0
		.amdhsa_system_vgpr_workitem_id 2
		.amdhsa_next_free_vgpr 233
		.amdhsa_next_free_sgpr 102
		.amdhsa_accum_offset 236
		.amdhsa_reserve_vcc 1
		.amdhsa_float_round_mode_32 0
		.amdhsa_float_round_mode_16_64 0
		.amdhsa_float_denorm_mode_32 3
		.amdhsa_float_denorm_mode_16_64 3
		.amdhsa_dx10_clamp 1
		.amdhsa_ieee_mode 1
		.amdhsa_fp16_overflow 0
		.amdhsa_tg_split 0
		.amdhsa_exception_fp_ieee_invalid_op 0
		.amdhsa_exception_fp_denorm_src 0
		.amdhsa_exception_fp_ieee_div_zero 0
		.amdhsa_exception_fp_ieee_overflow 0
		.amdhsa_exception_fp_ieee_underflow 0
		.amdhsa_exception_fp_ieee_inexact 0
		.amdhsa_exception_int_div_zero 0
	.end_amdhsa_kernel

; __global__ __launch_bounds__(512, 2) void fwd_megakernel(Params P) {
amdhsa.kernels:
  - .agpr_count:     0
    .args:
      - .offset:         0
        .size:           192
        .value_kind:     by_value
      - .offset:         192
        .size:           4
        .value_kind:     hidden_block_count_x
      - .offset:         196
        .size:           4
        .value_kind:     hidden_block_count_y
      - .offset:         200
        .size:           4
        .value_kind:     hidden_block_count_z
      - .offset:         204
        .size:           2
        .value_kind:     hidden_group_size_x
      - .offset:         206
        .size:           2
        .value_kind:     hidden_group_size_y
      - .offset:         208
        .size:           2
        .value_kind:     hidden_group_size_z
      - .offset:         210
        .size:           2
        .value_kind:     hidden_remainder_x
      - .offset:         212
        .size:           2
        .value_kind:     hidden_remainder_y
      - .offset:         214
        .size:           2
        .value_kind:     hidden_remainder_z
      - .offset:         232
        .size:           8
        .value_kind:     hidden_global_offset_x
      - .offset:         240
        .size:           8
        .value_kind:     hidden_global_offset_y
      - .offset:         248
        .size:           8
        .value_kind:     hidden_global_offset_z
      - .offset:         256
        .size:           2
        .value_kind:     hidden_grid_dims
      - .offset:         280
        .size:           8
        .value_kind:     hidden_multigrid_sync_arg
      - .offset:         312
        .size:           4
        .value_kind:     hidden_dynamic_lds_size
    .group_segment_fixed_size: 0
    .kernarg_segment_align: 8
    .kernarg_segment_size: 448
    .language:       OpenCL C
    .language_version:
      - 2
      - 0
    .max_flat_workgroup_size: 512
    .name:           _Z14fwd_megakernel6Params
    .private_segment_fixed_size: 0
    .sgpr_count:     108
    .sgpr_spill_count: 29
    .symbol:         _Z14fwd_megakernel6Params.kd
    .uniform_work_group_size: 1
    .uses_dynamic_stack: false
    .vgpr_count:     233
    .vgpr_spill_count: 0
    .wavefront_size: 64
